# non-temporal hint also on the read-once f32 weight / adaLN loads of the GEMM-phase tail jobs and the prologue
# speedup vs baseline: 1.0098x; 1.0001x over previous
.LBB0_11:
	v_add_co_u32_e32 v32, vcc, s30, v30
	v_mov_b32_e32 v148, s5
	s_nop 0
	v_addc_co_u32_e32 v33, vcc, -1, v31, vcc
	v_add_co_u32_e32 v34, vcc, s31, v30
	global_load_dwordx4 v[22:25], v[30:31], off nt
	s_nop 0
	v_addc_co_u32_e32 v35, vcc, -1, v31, vcc
	v_add_co_u32_e32 v38, vcc, s34, v30
	s_add_i32 s4, s4, 16
	s_nop 0
	v_addc_co_u32_e32 v39, vcc, -1, v31, vcc
	v_add_co_u32_e32 v36, vcc, s35, v30
	global_load_dwordx4 v[52:55], v[32:33], off nt
	s_nop 0
	global_load_dwordx4 v[32:35], v[34:35], off nt
	s_nop 0
	global_load_dwordx4 v[56:59], v[38:39], off nt
	v_addc_co_u32_e32 v37, vcc, -1, v31, vcc
	v_add_co_u32_e32 v40, vcc, s52, v30
	ds_read_b128 v[60:63], v148
	ds_read_b128 v[64:67], v148 offset:16
	v_addc_co_u32_e32 v41, vcc, -1, v31, vcc
	v_add_co_u32_e32 v42, vcc, s53, v30
	global_load_dwordx4 v[36:39], v[36:37], off nt
	s_nop 0
	v_addc_co_u32_e32 v43, vcc, -1, v31, vcc
	v_add_co_u32_e32 v44, vcc, s54, v30
	ds_read_b128 v[68:71], v148 offset:256
	ds_read_b128 v[72:75], v148 offset:272
	ds_read_b128 v[76:79], v148 offset:512
	ds_read_b128 v[80:83], v148 offset:528
	ds_read_b128 v[84:87], v148 offset:768
	ds_read_b128 v[88:91], v148 offset:784
	ds_read_b128 v[92:95], v148 offset:1024
	ds_read_b128 v[96:99], v148 offset:1040
	v_addc_co_u32_e32 v45, vcc, -1, v31, vcc
	v_add_co_u32_e32 v46, vcc, s55, v30
	s_waitcnt lgkmcnt(9)
	v_mov_b32_e32 v172, v63
	v_addc_co_u32_e32 v47, vcc, -1, v31, vcc
	v_add_co_u32_e32 v48, vcc, s56, v30
	s_waitcnt lgkmcnt(7)
	v_mov_b32_e32 v174, v71
	v_addc_co_u32_e32 v49, vcc, -1, v31, vcc
	v_add_co_u32_e32 v50, vcc, s57, v30
	s_waitcnt lgkmcnt(5)
	v_mov_b32_e32 v176, v79
	v_addc_co_u32_e32 v51, vcc, -1, v31, vcc
	v_add_co_u32_e32 v152, vcc, s58, v30
	global_load_dwordx4 v[100:103], v[40:41], off nt
	s_nop 0
	global_load_dwordx4 v[40:43], v[42:43], off nt
	s_nop 0
	global_load_dwordx4 v[104:107], v[44:45], off nt
	s_nop 0
	global_load_dwordx4 v[44:47], v[46:47], off nt
	s_nop 0
	global_load_dwordx4 v[108:111], v[48:49], off nt
	s_nop 0
	global_load_dwordx4 v[48:51], v[50:51], off nt
	v_addc_co_u32_e32 v153, vcc, -1, v31, vcc
	v_add_co_u32_e32 v156, vcc, s59, v30
	ds_read_b128 v[112:115], v148 offset:32
	ds_read_b128 v[116:119], v148 offset:48
	ds_read_b128 v[120:123], v148 offset:288
	ds_read_b128 v[124:127], v148 offset:304
	ds_read_b128 v[128:131], v148 offset:544
	ds_read_b128 v[132:135], v148 offset:560
	ds_read_b128 v[136:139], v148 offset:800
	ds_read_b128 v[140:143], v148 offset:816
	ds_read_b128 v[144:147], v148 offset:1056
	ds_read_b128 v[148:151], v148 offset:1072
	v_addc_co_u32_e32 v157, vcc, -1, v31, vcc
	v_add_co_u32_e32 v160, vcc, s60, v30
	s_waitcnt lgkmcnt(13)
	v_mov_b32_e32 v180, v87
	v_addc_co_u32_e32 v161, vcc, -1, v31, vcc
	v_add_co_u32_e32 v164, vcc, s62, v30
	s_waitcnt lgkmcnt(11)
	v_mov_b32_e32 v182, v95
	v_addc_co_u32_e32 v165, vcc, -1, v31, vcc
	v_add_co_u32_e32 v168, vcc, s63, v30
	v_mov_b32_e32 v184, v67
	s_nop 0
	v_addc_co_u32_e32 v169, vcc, -1, v31, vcc
	global_load_dwordx4 v[152:155], v[152:153], off nt
	s_nop 0
	global_load_dwordx4 v[156:159], v[156:157], off nt
	s_nop 0
	global_load_dwordx4 v[160:163], v[160:161], off nt
	s_nop 0
	global_load_dwordx4 v[164:167], v[164:165], off nt
	s_nop 0
	global_load_dwordx4 v[168:171], v[168:169], off nt
	v_mov_b32_e32 v186, v75
	v_mov_b32_e32 v188, v83
	v_mov_b32_e32 v190, v91
	s_waitcnt lgkmcnt(10)
	v_mov_b32_e32 v192, v99
	s_waitcnt lgkmcnt(9)
	v_mov_b32_e32 v194, v115
	s_waitcnt lgkmcnt(7)
	v_mov_b32_e32 v196, v123
	s_waitcnt lgkmcnt(5)
	v_mov_b32_e32 v198, v131
	s_waitcnt lgkmcnt(3)
	v_mov_b32_e32 v200, v139
	s_waitcnt lgkmcnt(1)
	v_mov_b32_e32 v202, v147
	s_add_i32 s5, s5, 64
	v_mov_b32_e32 v204, v119
	v_mov_b32_e32 v206, v127
	v_mov_b32_e32 v208, v135
	v_mov_b32_e32 v210, v143
	s_waitcnt lgkmcnt(0)
	v_mov_b32_e32 v212, v151
	v_lshl_add_u64 v[30:31], v[30:31], 0, s[6:7]
	s_cmp_gt_u32 s4, 47
	s_waitcnt vmcnt(14)
	v_pk_fma_f32 v[20:21], v[54:55], v[60:61], v[20:21] op_sel_hi:[1,0,1]
	v_pk_fma_f32 v[18:19], v[52:53], v[60:61], v[18:19] op_sel_hi:[1,0,1]
	v_pk_fma_f32 v[16:17], v[54:55], v[68:69], v[16:17] op_sel_hi:[1,0,1]
	v_pk_fma_f32 v[14:15], v[52:53], v[68:69], v[14:15] op_sel_hi:[1,0,1]
	v_pk_fma_f32 v[12:13], v[54:55], v[76:77], v[12:13] op_sel_hi:[1,0,1]
	v_pk_fma_f32 v[10:11], v[52:53], v[76:77], v[10:11] op_sel_hi:[1,0,1]
	v_pk_fma_f32 v[8:9], v[54:55], v[84:85], v[8:9] op_sel_hi:[1,0,1]
	v_pk_fma_f32 v[6:7], v[52:53], v[84:85], v[6:7] op_sel_hi:[1,0,1]
	v_pk_fma_f32 v[4:5], v[54:55], v[92:93], v[4:5] op_sel_hi:[1,0,1]
	v_pk_fma_f32 v[2:3], v[52:53], v[92:93], v[2:3] op_sel_hi:[1,0,1]
	s_waitcnt vmcnt(13)
	v_pk_fma_f32 v[20:21], v[34:35], v[60:61], v[20:21] op_sel:[0,1,0]
	v_pk_fma_f32 v[18:19], v[32:33], v[60:61], v[18:19] op_sel:[0,1,0]
	v_pk_fma_f32 v[16:17], v[34:35], v[68:69], v[16:17] op_sel:[0,1,0]
	v_pk_fma_f32 v[14:15], v[32:33], v[68:69], v[14:15] op_sel:[0,1,0]
	v_pk_fma_f32 v[12:13], v[34:35], v[76:77], v[12:13] op_sel:[0,1,0]
	v_pk_fma_f32 v[10:11], v[32:33], v[76:77], v[10:11] op_sel:[0,1,0]
	v_pk_fma_f32 v[8:9], v[34:35], v[84:85], v[8:9] op_sel:[0,1,0]
	v_pk_fma_f32 v[6:7], v[32:33], v[84:85], v[6:7] op_sel:[0,1,0]
	v_pk_fma_f32 v[4:5], v[34:35], v[92:93], v[4:5] op_sel:[0,1,0]
	v_pk_fma_f32 v[2:3], v[32:33], v[92:93], v[2:3] op_sel:[0,1,0]
	s_waitcnt vmcnt(12)
	v_pk_fma_f32 v[20:21], v[58:59], v[62:63], v[20:21] op_sel_hi:[1,0,1]
	v_pk_fma_f32 v[18:19], v[56:57], v[62:63], v[18:19] op_sel_hi:[1,0,1]
	v_pk_fma_f32 v[16:17], v[58:59], v[70:71], v[16:17] op_sel_hi:[1,0,1]
	v_pk_fma_f32 v[14:15], v[56:57], v[70:71], v[14:15] op_sel_hi:[1,0,1]
	v_pk_fma_f32 v[12:13], v[58:59], v[78:79], v[12:13] op_sel_hi:[1,0,1]
	v_pk_fma_f32 v[10:11], v[56:57], v[78:79], v[10:11] op_sel_hi:[1,0,1]
	v_pk_fma_f32 v[8:9], v[58:59], v[86:87], v[8:9] op_sel_hi:[1,0,1]
	v_pk_fma_f32 v[6:7], v[56:57], v[86:87], v[6:7] op_sel_hi:[1,0,1]
	v_pk_fma_f32 v[4:5], v[58:59], v[94:95], v[4:5] op_sel_hi:[1,0,1]
	v_pk_fma_f32 v[2:3], v[56:57], v[94:95], v[2:3] op_sel_hi:[1,0,1]
	s_waitcnt vmcnt(11)
	v_pk_fma_f32 v[20:21], v[38:39], v[172:173], v[20:21] op_sel_hi:[1,0,1]
	v_pk_fma_f32 v[18:19], v[36:37], v[172:173], v[18:19] op_sel_hi:[1,0,1]
	v_pk_fma_f32 v[16:17], v[38:39], v[174:175], v[16:17] op_sel_hi:[1,0,1]
	v_pk_fma_f32 v[14:15], v[36:37], v[174:175], v[14:15] op_sel_hi:[1,0,1]
	v_pk_fma_f32 v[12:13], v[38:39], v[176:177], v[12:13] op_sel_hi:[1,0,1]
	v_pk_fma_f32 v[10:11], v[36:37], v[176:177], v[10:11] op_sel_hi:[1,0,1]
	v_pk_fma_f32 v[8:9], v[38:39], v[180:181], v[8:9] op_sel_hi:[1,0,1]
	v_pk_fma_f32 v[6:7], v[36:37], v[180:181], v[6:7] op_sel_hi:[1,0,1]
	v_pk_fma_f32 v[4:5], v[38:39], v[182:183], v[4:5] op_sel_hi:[1,0,1]
	v_pk_fma_f32 v[2:3], v[36:37], v[182:183], v[2:3] op_sel_hi:[1,0,1]
	s_waitcnt vmcnt(10)
	v_pk_fma_f32 v[20:21], v[102:103], v[64:65], v[20:21] op_sel_hi:[1,0,1]
	v_pk_fma_f32 v[18:19], v[100:101], v[64:65], v[18:19] op_sel_hi:[1,0,1]
	v_pk_fma_f32 v[16:17], v[102:103], v[72:73], v[16:17] op_sel_hi:[1,0,1]
	v_pk_fma_f32 v[14:15], v[100:101], v[72:73], v[14:15] op_sel_hi:[1,0,1]
	v_pk_fma_f32 v[12:13], v[102:103], v[80:81], v[12:13] op_sel_hi:[1,0,1]
	v_pk_fma_f32 v[10:11], v[100:101], v[80:81], v[10:11] op_sel_hi:[1,0,1]
	v_pk_fma_f32 v[8:9], v[102:103], v[88:89], v[8:9] op_sel_hi:[1,0,1]
	v_pk_fma_f32 v[6:7], v[100:101], v[88:89], v[6:7] op_sel_hi:[1,0,1]
	v_pk_fma_f32 v[4:5], v[102:103], v[96:97], v[4:5] op_sel_hi:[1,0,1]
	v_pk_fma_f32 v[2:3], v[100:101], v[96:97], v[2:3] op_sel_hi:[1,0,1]
	s_waitcnt vmcnt(9)
	v_pk_fma_f32 v[20:21], v[42:43], v[64:65], v[20:21] op_sel:[0,1,0]
	v_pk_fma_f32 v[18:19], v[40:41], v[64:65], v[18:19] op_sel:[0,1,0]
	v_pk_fma_f32 v[16:17], v[42:43], v[72:73], v[16:17] op_sel:[0,1,0]
	v_pk_fma_f32 v[14:15], v[40:41], v[72:73], v[14:15] op_sel:[0,1,0]
	v_pk_fma_f32 v[12:13], v[42:43], v[80:81], v[12:13] op_sel:[0,1,0]
	v_pk_fma_f32 v[10:11], v[40:41], v[80:81], v[10:11] op_sel:[0,1,0]
	v_pk_fma_f32 v[8:9], v[42:43], v[88:89], v[8:9] op_sel:[0,1,0]
	v_pk_fma_f32 v[6:7], v[40:41], v[88:89], v[6:7] op_sel:[0,1,0]
	v_pk_fma_f32 v[4:5], v[42:43], v[96:97], v[4:5] op_sel:[0,1,0]
	v_pk_fma_f32 v[2:3], v[40:41], v[96:97], v[2:3] op_sel:[0,1,0]
	s_waitcnt vmcnt(8)
	v_pk_fma_f32 v[20:21], v[106:107], v[66:67], v[20:21] op_sel_hi:[1,0,1]
	v_pk_fma_f32 v[18:19], v[104:105], v[66:67], v[18:19] op_sel_hi:[1,0,1]
	v_pk_fma_f32 v[16:17], v[106:107], v[74:75], v[16:17] op_sel_hi:[1,0,1]
	v_pk_fma_f32 v[14:15], v[104:105], v[74:75], v[14:15] op_sel_hi:[1,0,1]
	v_pk_fma_f32 v[12:13], v[106:107], v[82:83], v[12:13] op_sel_hi:[1,0,1]
	v_pk_fma_f32 v[10:11], v[104:105], v[82:83], v[10:11] op_sel_hi:[1,0,1]
	v_pk_fma_f32 v[8:9], v[106:107], v[90:91], v[8:9] op_sel_hi:[1,0,1]
	v_pk_fma_f32 v[6:7], v[104:105], v[90:91], v[6:7] op_sel_hi:[1,0,1]
	v_pk_fma_f32 v[4:5], v[106:107], v[98:99], v[4:5] op_sel_hi:[1,0,1]
	v_pk_fma_f32 v[2:3], v[104:105], v[98:99], v[2:3] op_sel_hi:[1,0,1]
	s_waitcnt vmcnt(7)
	v_pk_fma_f32 v[20:21], v[46:47], v[184:185], v[20:21] op_sel_hi:[1,0,1]
	v_pk_fma_f32 v[18:19], v[44:45], v[184:185], v[18:19] op_sel_hi:[1,0,1]
	v_pk_fma_f32 v[16:17], v[46:47], v[186:187], v[16:17] op_sel_hi:[1,0,1]
	v_pk_fma_f32 v[14:15], v[44:45], v[186:187], v[14:15] op_sel_hi:[1,0,1]
	v_pk_fma_f32 v[12:13], v[46:47], v[188:189], v[12:13] op_sel_hi:[1,0,1]
	v_pk_fma_f32 v[10:11], v[44:45], v[188:189], v[10:11] op_sel_hi:[1,0,1]
	v_pk_fma_f32 v[8:9], v[46:47], v[190:191], v[8:9] op_sel_hi:[1,0,1]
	v_pk_fma_f32 v[6:7], v[44:45], v[190:191], v[6:7] op_sel_hi:[1,0,1]
	v_pk_fma_f32 v[4:5], v[46:47], v[192:193], v[4:5] op_sel_hi:[1,0,1]
	v_pk_fma_f32 v[2:3], v[44:45], v[192:193], v[2:3] op_sel_hi:[1,0,1]
	s_waitcnt vmcnt(6)
	v_pk_fma_f32 v[20:21], v[110:111], v[112:113], v[20:21] op_sel_hi:[1,0,1]
	v_pk_fma_f32 v[18:19], v[108:109], v[112:113], v[18:19] op_sel_hi:[1,0,1]
	v_pk_fma_f32 v[16:17], v[110:111], v[120:121], v[16:17] op_sel_hi:[1,0,1]
	v_pk_fma_f32 v[14:15], v[108:109], v[120:121], v[14:15] op_sel_hi:[1,0,1]
	v_pk_fma_f32 v[12:13], v[110:111], v[128:129], v[12:13] op_sel_hi:[1,0,1]
	v_pk_fma_f32 v[10:11], v[108:109], v[128:129], v[10:11] op_sel_hi:[1,0,1]
	v_pk_fma_f32 v[8:9], v[110:111], v[136:137], v[8:9] op_sel_hi:[1,0,1]
	v_pk_fma_f32 v[6:7], v[108:109], v[136:137], v[6:7] op_sel_hi:[1,0,1]
	v_pk_fma_f32 v[4:5], v[110:111], v[144:145], v[4:5] op_sel_hi:[1,0,1]
	v_pk_fma_f32 v[2:3], v[108:109], v[144:145], v[2:3] op_sel_hi:[1,0,1]
	s_waitcnt vmcnt(5)
	v_pk_fma_f32 v[20:21], v[50:51], v[112:113], v[20:21] op_sel:[0,1,0]
	v_pk_fma_f32 v[18:19], v[48:49], v[112:113], v[18:19] op_sel:[0,1,0]
	v_pk_fma_f32 v[16:17], v[50:51], v[120:121], v[16:17] op_sel:[0,1,0]
	v_pk_fma_f32 v[14:15], v[48:49], v[120:121], v[14:15] op_sel:[0,1,0]
	v_pk_fma_f32 v[12:13], v[50:51], v[128:129], v[12:13] op_sel:[0,1,0]
	v_pk_fma_f32 v[10:11], v[48:49], v[128:129], v[10:11] op_sel:[0,1,0]
	v_pk_fma_f32 v[8:9], v[50:51], v[136:137], v[8:9] op_sel:[0,1,0]
	v_pk_fma_f32 v[6:7], v[48:49], v[136:137], v[6:7] op_sel:[0,1,0]
	v_pk_fma_f32 v[4:5], v[50:51], v[144:145], v[4:5] op_sel:[0,1,0]
	v_pk_fma_f32 v[2:3], v[48:49], v[144:145], v[2:3] op_sel:[0,1,0]
	s_waitcnt vmcnt(4)
	v_pk_fma_f32 v[20:21], v[154:155], v[114:115], v[20:21] op_sel_hi:[1,0,1]
	v_pk_fma_f32 v[18:19], v[152:153], v[114:115], v[18:19] op_sel_hi:[1,0,1]
	v_pk_fma_f32 v[16:17], v[154:155], v[122:123], v[16:17] op_sel_hi:[1,0,1]
	v_pk_fma_f32 v[14:15], v[152:153], v[122:123], v[14:15] op_sel_hi:[1,0,1]
	v_pk_fma_f32 v[12:13], v[154:155], v[130:131], v[12:13] op_sel_hi:[1,0,1]
	v_pk_fma_f32 v[10:11], v[152:153], v[130:131], v[10:11] op_sel_hi:[1,0,1]
	v_pk_fma_f32 v[8:9], v[154:155], v[138:139], v[8:9] op_sel_hi:[1,0,1]
	v_pk_fma_f32 v[6:7], v[152:153], v[138:139], v[6:7] op_sel_hi:[1,0,1]
	v_pk_fma_f32 v[4:5], v[154:155], v[146:147], v[4:5] op_sel_hi:[1,0,1]
	v_pk_fma_f32 v[2:3], v[152:153], v[146:147], v[2:3] op_sel_hi:[1,0,1]
	s_waitcnt vmcnt(3)
	v_pk_fma_f32 v[20:21], v[158:159], v[194:195], v[20:21] op_sel_hi:[1,0,1]
	v_pk_fma_f32 v[18:19], v[156:157], v[194:195], v[18:19] op_sel_hi:[1,0,1]
	v_pk_fma_f32 v[16:17], v[158:159], v[196:197], v[16:17] op_sel_hi:[1,0,1]
	v_pk_fma_f32 v[14:15], v[156:157], v[196:197], v[14:15] op_sel_hi:[1,0,1]
	v_pk_fma_f32 v[12:13], v[158:159], v[198:199], v[12:13] op_sel_hi:[1,0,1]
	v_pk_fma_f32 v[10:11], v[156:157], v[198:199], v[10:11] op_sel_hi:[1,0,1]
	v_pk_fma_f32 v[8:9], v[158:159], v[200:201], v[8:9] op_sel_hi:[1,0,1]
	v_pk_fma_f32 v[6:7], v[156:157], v[200:201], v[6:7] op_sel_hi:[1,0,1]
	v_pk_fma_f32 v[4:5], v[158:159], v[202:203], v[4:5] op_sel_hi:[1,0,1]
	v_pk_fma_f32 v[2:3], v[156:157], v[202:203], v[2:3] op_sel_hi:[1,0,1]
	s_waitcnt vmcnt(2)
	v_pk_fma_f32 v[20:21], v[162:163], v[116:117], v[20:21] op_sel_hi:[1,0,1]
	v_pk_fma_f32 v[18:19], v[160:161], v[116:117], v[18:19] op_sel_hi:[1,0,1]
	v_pk_fma_f32 v[16:17], v[162:163], v[124:125], v[16:17] op_sel_hi:[1,0,1]
	v_pk_fma_f32 v[14:15], v[160:161], v[124:125], v[14:15] op_sel_hi:[1,0,1]
	v_pk_fma_f32 v[12:13], v[162:163], v[132:133], v[12:13] op_sel_hi:[1,0,1]
	v_pk_fma_f32 v[10:11], v[160:161], v[132:133], v[10:11] op_sel_hi:[1,0,1]
	v_pk_fma_f32 v[8:9], v[162:163], v[140:141], v[8:9] op_sel_hi:[1,0,1]
	v_pk_fma_f32 v[6:7], v[160:161], v[140:141], v[6:7] op_sel_hi:[1,0,1]
	v_pk_fma_f32 v[4:5], v[162:163], v[148:149], v[4:5] op_sel_hi:[1,0,1]
	v_pk_fma_f32 v[2:3], v[160:161], v[148:149], v[2:3] op_sel_hi:[1,0,1]
	s_waitcnt vmcnt(1)
	v_pk_fma_f32 v[20:21], v[166:167], v[116:117], v[20:21] op_sel:[0,1,0]
	v_pk_fma_f32 v[18:19], v[164:165], v[116:117], v[18:19] op_sel:[0,1,0]
	v_pk_fma_f32 v[16:17], v[166:167], v[124:125], v[16:17] op_sel:[0,1,0]
	v_pk_fma_f32 v[14:15], v[164:165], v[124:125], v[14:15] op_sel:[0,1,0]
	v_pk_fma_f32 v[12:13], v[166:167], v[132:133], v[12:13] op_sel:[0,1,0]
	v_pk_fma_f32 v[10:11], v[164:165], v[132:133], v[10:11] op_sel:[0,1,0]
	v_pk_fma_f32 v[8:9], v[166:167], v[140:141], v[8:9] op_sel:[0,1,0]
	v_pk_fma_f32 v[6:7], v[164:165], v[140:141], v[6:7] op_sel:[0,1,0]
	v_pk_fma_f32 v[4:5], v[166:167], v[148:149], v[4:5] op_sel:[0,1,0]
	v_pk_fma_f32 v[2:3], v[164:165], v[148:149], v[2:3] op_sel:[0,1,0]
	s_waitcnt vmcnt(0)
	v_pk_fma_f32 v[20:21], v[170:171], v[118:119], v[20:21] op_sel_hi:[1,0,1]
	v_pk_fma_f32 v[18:19], v[168:169], v[118:119], v[18:19] op_sel_hi:[1,0,1]
	v_pk_fma_f32 v[16:17], v[170:171], v[126:127], v[16:17] op_sel_hi:[1,0,1]
	v_pk_fma_f32 v[14:15], v[168:169], v[126:127], v[14:15] op_sel_hi:[1,0,1]
	v_pk_fma_f32 v[12:13], v[170:171], v[134:135], v[12:13] op_sel_hi:[1,0,1]
	v_pk_fma_f32 v[10:11], v[168:169], v[134:135], v[10:11] op_sel_hi:[1,0,1]
	v_pk_fma_f32 v[8:9], v[170:171], v[142:143], v[8:9] op_sel_hi:[1,0,1]
	v_pk_fma_f32 v[6:7], v[168:169], v[142:143], v[6:7] op_sel_hi:[1,0,1]
	v_pk_fma_f32 v[4:5], v[170:171], v[150:151], v[4:5] op_sel_hi:[1,0,1]
	v_pk_fma_f32 v[2:3], v[168:169], v[150:151], v[2:3] op_sel_hi:[1,0,1]
	v_pk_fma_f32 v[20:21], v[24:25], v[204:205], v[20:21] op_sel_hi:[1,0,1]
	v_pk_fma_f32 v[18:19], v[22:23], v[204:205], v[18:19] op_sel_hi:[1,0,1]
	v_pk_fma_f32 v[16:17], v[24:25], v[206:207], v[16:17] op_sel_hi:[1,0,1]
	v_pk_fma_f32 v[14:15], v[22:23], v[206:207], v[14:15] op_sel_hi:[1,0,1]
	v_pk_fma_f32 v[12:13], v[24:25], v[208:209], v[12:13] op_sel_hi:[1,0,1]
	v_pk_fma_f32 v[10:11], v[22:23], v[208:209], v[10:11] op_sel_hi:[1,0,1]
	v_pk_fma_f32 v[8:9], v[24:25], v[210:211], v[8:9] op_sel_hi:[1,0,1]
	v_pk_fma_f32 v[6:7], v[22:23], v[210:211], v[6:7] op_sel_hi:[1,0,1]
	v_pk_fma_f32 v[4:5], v[24:25], v[212:213], v[4:5] op_sel_hi:[1,0,1]
	v_pk_fma_f32 v[2:3], v[22:23], v[212:213], v[2:3] op_sel_hi:[1,0,1]
	s_cbranch_scc0 .LBB0_11
	s_lshl_b32 s4, s64, 4
	s_and_b32 s4, s4, 16
	s_add_i32 s4, s65, s4
	s_mul_i32 s9, s4, 0x3c000
	s_mul_hi_i32 s8, s4, 0x3c000
	s_add_u32 s4, s14, s9
	s_addc_u32 s5, s15, s8
	s_add_u32 s4, s4, s2
	s_addc_u32 s5, s5, s3
	global_store_dwordx4 v26, v[18:21], s[4:5]
	s_add_u32 s4, s16, s9
	s_addc_u32 s5, s17, s8
	s_add_u32 s4, s4, s2
	s_addc_u32 s5, s5, s3
	global_store_dwordx4 v26, v[14:17], s[4:5]
	s_add_u32 s4, s18, s9
	s_addc_u32 s5, s19, s8
	s_add_u32 s4, s4, s2
	s_addc_u32 s5, s5, s3
	global_store_dwordx4 v26, v[10:13], s[4:5]
	s_add_u32 s4, s23, s9
	s_addc_u32 s5, s24, s8
	s_add_u32 s4, s4, s2
	s_addc_u32 s5, s5, s3
	global_store_dwordx4 v26, v[6:9], s[4:5]
	s_add_u32 s4, s25, s9
	s_addc_u32 s5, s26, s8
	s_add_u32 s2, s4, s2
	s_addc_u32 s3, s5, s3
	global_store_dwordx4 v26, v[2:5], s[2:3]
	s_waitcnt lgkmcnt(0)
	s_add_i32 s13, s13, s22
	s_cmpk_gt_i32 s13, 0x5ff
	s_cbranch_scc0 .LBB0_10

.LBB0_21:
	v_cvt_f32_ubyte0_e32 v2, s13
	v_rcp_iflag_f32_e32 v2, v2
	s_add_i32 s17, s12, 0xfffffc00
	s_and_b64 s[10:11], s[10:11], exec
	s_cselect_b32 s10, s12, s17
	v_mul_f32_e32 v2, 0x4f7ffffe, v2
	v_cvt_u32_f32_e32 v2, v2
	s_and_b64 s[8:9], s[8:9], exec
	s_cselect_b32 s8, s10, s21
	s_sub_i32 s11, 0, s13
	v_readfirstlane_b32 s12, v2
	s_mul_i32 s11, s11, s12
	s_mul_hi_u32 s11, s12, s11
	s_abs_i32 s10, s8
	s_add_i32 s12, s12, s11
	s_mul_hi_u32 s11, s10, s12
	s_mul_i32 s12, s11, s13
	s_sub_i32 s10, s10, s12
	s_ashr_i32 s9, s8, 31
	s_add_i32 s12, s11, 1
	s_sub_i32 s17, s10, s13
	s_cmp_ge_u32 s10, s13
	s_cselect_b32 s11, s12, s11
	s_cselect_b32 s10, s17, s10
	s_add_i32 s12, s11, 1
	s_cmp_ge_u32 s10, s13
	s_cselect_b32 s10, s12, s11
	s_xor_b32 s10, s10, s9
	s_sub_i32 s9, s10, s9
	s_mul_i32 s10, s9, s13
	s_sub_i32 s10, s8, s10
	s_lshl_b32 s8, s9, 6
	s_lshl_b32 s10, s10, 6
	s_cmp_ge_i32 s10, s6
	s_cselect_b64 s[12:13], -1, 0
	s_and_b64 vcc, exec, s[12:13]
	s_cbranch_vccnz .LBB0_23
	v_or_b32_e32 v2, s8, v1
	v_mad_i64_i32 v[2:3], s[18:19], v2, s6, 0
	v_lshl_add_u64 v[2:3], v[2:3], 2, s[14:15]
	s_ashr_i32 s11, s10, 31
	v_lshl_add_u64 v[2:3], s[10:11], 2, v[2:3]
	v_mov_b32_e32 v9, v7
	v_lshl_add_u64 v[10:11], v[2:3], 0, v[8:9]
	global_load_dwordx4 v[2:5], v[10:11], off nt
	s_lshl_b32 s6, s6, 4
	v_lshl_add_u64 v[10:11], v[10:11], 0, s[6:7]
	global_load_dwordx4 v[68:71], v[10:11], off nt
	v_lshl_add_u64 v[10:11], v[10:11], 0, s[6:7]
	global_load_dwordx4 v[72:75], v[10:11], off nt
	v_lshl_add_u64 v[10:11], v[10:11], 0, s[6:7]
	global_load_dwordx4 v[76:79], v[10:11], off nt
	v_lshl_add_u64 v[10:11], v[10:11], 0, s[6:7]
	global_load_dwordx4 v[80:83], v[10:11], off nt
	v_lshl_add_u64 v[10:11], v[10:11], 0, s[6:7]
	global_load_dwordx4 v[84:87], v[10:11], off nt
	v_lshl_add_u64 v[10:11], v[10:11], 0, s[6:7]
	global_load_dwordx4 v[88:91], v[10:11], off nt
	v_lshl_add_u64 v[10:11], v[10:11], 0, s[6:7]
	global_load_dwordx4 v[92:95], v[10:11], off nt
	v_lshl_add_u64 v[10:11], v[10:11], 0, s[6:7]
	global_load_dwordx4 v[96:99], v[10:11], off nt
	v_lshl_add_u64 v[10:11], v[10:11], 0, s[6:7]
	global_load_dwordx4 v[100:103], v[10:11], off nt
	v_lshl_add_u64 v[10:11], v[10:11], 0, s[6:7]
	global_load_dwordx4 v[104:107], v[10:11], off nt
	v_lshl_add_u64 v[10:11], v[10:11], 0, s[6:7]
	global_load_dwordx4 v[108:111], v[10:11], off nt
	v_lshl_add_u64 v[10:11], v[10:11], 0, s[6:7]
	global_load_dwordx4 v[112:115], v[10:11], off nt
	v_lshl_add_u64 v[10:11], v[10:11], 0, s[6:7]
	global_load_dwordx4 v[116:119], v[10:11], off nt
	v_lshl_add_u64 v[10:11], v[10:11], 0, s[6:7]
	global_load_dwordx4 v[120:123], v[10:11], off nt
	v_lshl_add_u64 v[10:11], v[10:11], 0, s[6:7]
	global_load_dwordx4 v[124:127], v[10:11], off nt
	v_add_u32_e32 v9, 0x38e8, v36
	v_add_u32_e32 v10, 0x3cf0, v36
	v_add_u32_e32 v11, 0x3cf8, v36
	s_waitcnt vmcnt(15)
	ds_write2_b32 v36, v2, v3 offset1:1
	ds_write2_b32 v36, v4, v5 offset0:2 offset1:3
	s_waitcnt vmcnt(14)
	ds_write2_b32 v37, v68, v69 offset1:1
	ds_write2_b32 v38, v70, v71 offset1:1
	s_waitcnt vmcnt(13)
	ds_write2_b32 v39, v72, v73 offset1:1
	ds_write2_b32 v40, v74, v75 offset1:1
	s_waitcnt vmcnt(12)
	ds_write2_b32 v41, v76, v77 offset1:1
	ds_write2_b32 v42, v78, v79 offset1:1
	s_waitcnt vmcnt(11)
	ds_write2_b32 v43, v80, v81 offset1:1
	ds_write2_b32 v44, v82, v83 offset1:1
	s_waitcnt vmcnt(10)
	ds_write2_b32 v45, v84, v85 offset1:1
	ds_write2_b32 v46, v86, v87 offset1:1
	s_waitcnt vmcnt(9)
	ds_write2_b32 v47, v88, v89 offset1:1
	ds_write2_b32 v48, v90, v91 offset1:1
	s_waitcnt vmcnt(8)
	ds_write2_b32 v49, v92, v93 offset1:1
	ds_write2_b32 v50, v94, v95 offset1:1
	s_waitcnt vmcnt(7)
	ds_write2_b32 v51, v96, v97 offset1:1
	ds_write2_b32 v52, v98, v99 offset1:1
	s_waitcnt vmcnt(6)
	ds_write2_b32 v53, v100, v101 offset1:1
	ds_write2_b32 v54, v102, v103 offset1:1
	s_waitcnt vmcnt(5)
	ds_write2_b32 v55, v104, v105 offset1:1
	ds_write2_b32 v56, v106, v107 offset1:1
	s_waitcnt vmcnt(4)
	ds_write2_b32 v57, v108, v109 offset1:1
	ds_write2_b32 v58, v110, v111 offset1:1
	s_waitcnt vmcnt(3)
	ds_write2_b32 v59, v112, v113 offset1:1
	ds_write2_b32 v60, v114, v115 offset1:1
	s_waitcnt vmcnt(2)
	ds_write2_b32 v61, v116, v117 offset1:1
	ds_write2_b32 v62, v118, v119 offset1:1
	s_waitcnt vmcnt(1)
	ds_write2_b32 v63, v120, v121 offset1:1
	ds_write2_b32 v9, v122, v123 offset1:1
	s_waitcnt vmcnt(0)
	ds_write2_b32 v10, v124, v125 offset1:1
	ds_write2_b32 v11, v126, v127 offset1:1

.LBB0_307:
	s_lshl_b32 s24, s25, 6
	s_cmp_ge_i32 s30, s4
	s_cselect_b64 s[26:27], -1, 0
	s_and_b64 vcc, exec, s[26:27]
	s_cbranch_vccnz .LBB0_309
	v_or_b32_e32 v2, s24, v9
	s_ashr_i32 s25, s24, 31
	s_mul_i32 s25, s25, s4
	v_mad_u64_u32 v[2:3], s[62:63], v2, s4, 0
	v_add_u32_e32 v3, s25, v3
	v_lshl_add_u64 v[2:3], v[2:3], 2, s[0:1]
	s_ashr_i32 s31, s30, 31
	v_lshl_add_u64 v[2:3], s[30:31], 2, v[2:3]
	v_mov_b32_e32 v11, v7
	v_lshl_add_u64 v[64:65], v[2:3], 0, v[10:11]
	s_lshl_b64 s[0:1], s[4:5], 4
	v_lshl_add_u64 v[68:69], v[64:65], 0, s[0:1]
	v_lshl_add_u64 v[72:73], v[68:69], 0, s[0:1]
	global_load_dwordx4 v[2:5], v[64:65], off nt
	s_nop 0
	global_load_dwordx4 v[64:67], v[68:69], off nt
	s_nop 0
	global_load_dwordx4 v[68:71], v[72:73], off nt
	v_lshl_add_u64 v[72:73], v[72:73], 0, s[0:1]
	global_load_dwordx4 v[78:81], v[72:73], off nt
	v_lshl_add_u64 v[72:73], v[72:73], 0, s[0:1]
	global_load_dwordx4 v[82:85], v[72:73], off nt
	v_lshl_add_u64 v[72:73], v[72:73], 0, s[0:1]
	global_load_dwordx4 v[86:89], v[72:73], off nt
	v_lshl_add_u64 v[72:73], v[72:73], 0, s[0:1]
	global_load_dwordx4 v[90:93], v[72:73], off nt
	v_lshl_add_u64 v[72:73], v[72:73], 0, s[0:1]
	global_load_dwordx4 v[94:97], v[72:73], off nt
	v_lshl_add_u64 v[72:73], v[72:73], 0, s[0:1]
	global_load_dwordx4 v[98:101], v[72:73], off nt
	v_lshl_add_u64 v[72:73], v[72:73], 0, s[0:1]
	global_load_dwordx4 v[102:105], v[72:73], off nt
	v_lshl_add_u64 v[72:73], v[72:73], 0, s[0:1]
	global_load_dwordx4 v[106:109], v[72:73], off nt
	v_lshl_add_u64 v[72:73], v[72:73], 0, s[0:1]
	global_load_dwordx4 v[110:113], v[72:73], off nt
	v_lshl_add_u64 v[72:73], v[72:73], 0, s[0:1]
	global_load_dwordx4 v[114:117], v[72:73], off nt
	v_lshl_add_u64 v[72:73], v[72:73], 0, s[0:1]
	global_load_dwordx4 v[118:121], v[72:73], off nt
	v_lshl_add_u64 v[72:73], v[72:73], 0, s[0:1]
	global_load_dwordx4 v[122:125], v[72:73], off nt
	v_lshl_add_u64 v[72:73], v[72:73], 0, s[0:1]
	global_load_dwordx4 v[126:129], v[72:73], off nt
	s_waitcnt vmcnt(0)
	ds_write2_b32 v36, v2, v3 offset1:1
	ds_write2_b32 v36, v4, v5 offset0:2 offset1:3
	ds_write2_b32 v37, v64, v65 offset1:1
	ds_write2_b32 v38, v66, v67 offset1:1
	ds_write2_b32 v39, v68, v69 offset1:1
	ds_write2_b32 v40, v70, v71 offset1:1
	ds_write2_b32 v41, v78, v79 offset1:1
	ds_write2_b32 v42, v80, v81 offset1:1
	ds_write2_b32 v43, v82, v83 offset1:1
	ds_write2_b32 v44, v84, v85 offset1:1
	ds_write2_b32 v45, v86, v87 offset1:1
	ds_write2_b32 v46, v88, v89 offset1:1
	ds_write2_b32 v47, v90, v91 offset1:1
	ds_write2_b32 v48, v92, v93 offset1:1
	ds_write2_b32 v49, v94, v95 offset1:1
	ds_write2_b32 v50, v96, v97 offset1:1
	ds_write2_b32 v51, v98, v99 offset1:1
	ds_write2_b32 v52, v100, v101 offset1:1
	ds_write2_b32 v53, v102, v103 offset1:1
	ds_write2_b32 v54, v104, v105 offset1:1
	ds_write2_b32 v55, v106, v107 offset1:1
	ds_write2_b32 v56, v108, v109 offset1:1
	ds_write2_b32 v57, v110, v111 offset1:1
	ds_write2_b32 v58, v112, v113 offset1:1
	ds_write2_b32 v59, v114, v115 offset1:1
	ds_write2_b32 v60, v116, v117 offset1:1
	ds_write2_b32 v61, v118, v119 offset1:1
	ds_write2_b32 v62, v120, v121 offset1:1
	v_add_u32_e32 v2, 0x38e0, v36
	ds_write2_b32 v2, v122, v123 offset1:1
	v_add_u32_e32 v2, 0x38e8, v36
	ds_write2_b32 v2, v124, v125 offset1:1
	v_add_u32_e32 v2, 0x3cf0, v36
	ds_write2_b32 v2, v126, v127 offset1:1
	v_add_u32_e32 v2, 0x3cf8, v36
	ds_write2_b32 v2, v128, v129 offset1:1

.LBB0_347:
	s_mov_b32 s25, 0xfff4c000
	v_add_co_u32_e32 v30, vcc, s25, v26
	s_mov_b32 s25, 0xfff58000
	s_nop 0
	v_addc_co_u32_e32 v31, vcc, -1, v27, vcc
	global_load_dwordx4 v[30:33], v[30:31], off nt
	v_add_co_u32_e32 v34, vcc, s25, v26
	s_mov_b32 s25, 0xfff64000
	s_nop 0
	v_addc_co_u32_e32 v35, vcc, -1, v27, vcc
	v_add_co_u32_e32 v38, vcc, s25, v26
	s_mov_b32 s25, 0xfff70000
	s_nop 0
	v_addc_co_u32_e32 v39, vcc, -1, v27, vcc
	global_load_dwordx4 v[34:37], v[34:35], off nt
	v_add_co_u32_e32 v42, vcc, s25, v26
	global_load_dwordx4 v[38:41], v[38:39], off nt
	s_nop 0
	v_addc_co_u32_e32 v43, vcc, -1, v27, vcc
	global_load_dwordx4 v[42:45], v[42:43], off nt
	s_mov_b32 s25, 0xfff7c000
	v_add_co_u32_e32 v46, vcc, s25, v26
	s_mov_b32 s25, 0xfff88000
	s_nop 0
	v_addc_co_u32_e32 v47, vcc, -1, v27, vcc
	global_load_dwordx4 v[46:49], v[46:47], off nt
	v_add_co_u32_e32 v50, vcc, s25, v26
	s_mov_b32 s25, 0xfff94000
	s_nop 0
	v_addc_co_u32_e32 v51, vcc, -1, v27, vcc
	v_add_co_u32_e32 v54, vcc, s25, v26
	s_mov_b32 s25, 0xfffa0000
	s_nop 0
	v_addc_co_u32_e32 v55, vcc, -1, v27, vcc
	global_load_dwordx4 v[50:53], v[50:51], off nt
	v_add_co_u32_e32 v58, vcc, s25, v26
	global_load_dwordx4 v[54:57], v[54:55], off nt
	s_nop 0
	v_addc_co_u32_e32 v59, vcc, -1, v27, vcc
	global_load_dwordx4 v[58:61], v[58:59], off nt
	s_mov_b32 s25, 0xfffac000
	v_add_co_u32_e32 v62, vcc, s25, v26
	s_mov_b32 s25, 0xfffb8000
	s_nop 0
	v_addc_co_u32_e32 v63, vcc, -1, v27, vcc
	v_add_co_u32_e32 v66, vcc, s25, v26
	s_mov_b32 s25, 0xfffc4000
	s_nop 0
	v_addc_co_u32_e32 v67, vcc, -1, v27, vcc
	v_add_co_u32_e32 v70, vcc, s25, v26
	global_load_dwordx4 v[62:65], v[62:63], off nt
	s_nop 0
	v_addc_co_u32_e32 v71, vcc, -1, v27, vcc
	global_load_dwordx4 v[66:69], v[66:67], off nt
	v_add_co_u32_e32 v74, vcc, s17, v26
	global_load_dwordx4 v[70:73], v[70:71], off nt
	s_nop 0
	v_addc_co_u32_e32 v75, vcc, -1, v27, vcc
	global_load_dwordx4 v[74:77], v[74:75], off nt
	v_add_co_u32_e32 v78, vcc, s18, v26
	v_mov_b32_e32 v29, s24
	s_nop 0
	v_addc_co_u32_e32 v79, vcc, -1, v27, vcc
	global_load_dwordx4 v[78:81], v[78:79], off nt
	v_add_co_u32_e32 v82, vcc, s19, v26
	s_add_i32 s23, s23, 16
	s_nop 0
	v_addc_co_u32_e32 v83, vcc, -1, v27, vcc
	global_load_dwordx4 v[82:85], v[82:83], off nt
	v_add_co_u32_e32 v86, vcc, s20, v26
	s_add_i32 s24, s24, 64
	s_nop 0
	v_addc_co_u32_e32 v87, vcc, -1, v27, vcc
	global_load_dwordx4 v[86:89], v[86:87], off nt
	s_nop 0
	global_load_dwordx4 v[90:93], v[26:27], off nt
	ds_read_b128 v[94:97], v29
	ds_read_b128 v[98:101], v29 offset:16
	ds_read_b128 v[102:105], v29 offset:32
	ds_read_b128 v[106:109], v29 offset:48
	v_lshl_add_u64 v[26:27], v[26:27], 0, s[0:1]
	s_waitcnt vmcnt(15) lgkmcnt(3)
	v_pk_fma_f32 v[110:111], v[32:33], v[94:95], v[20:21] op_sel_hi:[1,0,1]
	v_pk_fma_f32 v[112:113], v[30:31], v[94:95], v[18:19] op_sel_hi:[1,0,1]
	ds_read_b128 v[18:21], v29 offset:512
	s_cmpk_gt_u32 s23, 0x6f
	s_waitcnt lgkmcnt(0)
	v_pk_fma_f32 v[114:115], v[32:33], v[18:19], v[16:17] op_sel_hi:[1,0,1]
	v_pk_fma_f32 v[116:117], v[30:31], v[18:19], v[14:15] op_sel_hi:[1,0,1]
	ds_read_b128 v[14:17], v29 offset:1024
	s_waitcnt lgkmcnt(0)
	v_pk_fma_f32 v[118:119], v[32:33], v[14:15], v[12:13] op_sel_hi:[1,0,1]
	v_pk_fma_f32 v[120:121], v[30:31], v[14:15], v[10:11] op_sel_hi:[1,0,1]
	ds_read_b128 v[10:13], v29 offset:1536
	s_waitcnt lgkmcnt(0)
	v_pk_fma_f32 v[122:123], v[32:33], v[10:11], v[8:9] op_sel_hi:[1,0,1]
	v_pk_fma_f32 v[124:125], v[30:31], v[10:11], v[6:7] op_sel_hi:[1,0,1]
	ds_read_b128 v[6:9], v29 offset:2048
	s_waitcnt lgkmcnt(0)
	v_pk_fma_f32 v[4:5], v[32:33], v[6:7], v[4:5] op_sel_hi:[1,0,1]
	v_pk_fma_f32 v[2:3], v[30:31], v[6:7], v[2:3] op_sel_hi:[1,0,1]
	s_waitcnt vmcnt(14)
	v_pk_fma_f32 v[30:31], v[36:37], v[94:95], v[110:111] op_sel:[0,1,0]
	v_pk_fma_f32 v[32:33], v[34:35], v[94:95], v[112:113] op_sel:[0,1,0]
	v_pk_fma_f32 v[4:5], v[36:37], v[6:7], v[4:5] op_sel:[0,1,0]
	v_pk_fma_f32 v[2:3], v[34:35], v[6:7], v[2:3] op_sel:[0,1,0]
	v_pk_fma_f32 v[94:95], v[36:37], v[18:19], v[114:115] op_sel:[0,1,0]
	v_pk_fma_f32 v[18:19], v[34:35], v[18:19], v[116:117] op_sel:[0,1,0]
	s_waitcnt vmcnt(13)
	v_pk_fma_f32 v[6:7], v[40:41], v[96:97], v[30:31] op_sel_hi:[1,0,1]
	v_pk_fma_f32 v[30:31], v[38:39], v[96:97], v[32:33] op_sel_hi:[1,0,1]
	v_pk_fma_f32 v[4:5], v[40:41], v[8:9], v[4:5] op_sel_hi:[1,0,1]
	v_pk_fma_f32 v[2:3], v[38:39], v[8:9], v[2:3] op_sel_hi:[1,0,1]
	v_mov_b32_e32 v8, v97
	v_pk_fma_f32 v[110:111], v[36:37], v[14:15], v[118:119] op_sel:[0,1,0]
	v_pk_fma_f32 v[14:15], v[34:35], v[14:15], v[120:121] op_sel:[0,1,0]
	v_pk_fma_f32 v[32:33], v[40:41], v[20:21], v[94:95] op_sel_hi:[1,0,1]
	v_pk_fma_f32 v[18:19], v[38:39], v[20:21], v[18:19] op_sel_hi:[1,0,1]
	s_waitcnt vmcnt(12)
	v_pk_fma_f32 v[6:7], v[44:45], v[8:9], v[6:7] op_sel_hi:[1,0,1]
	v_pk_fma_f32 v[30:31], v[42:43], v[8:9], v[30:31] op_sel_hi:[1,0,1]
	v_mov_b32_e32 v8, v21
	v_pk_fma_f32 v[112:113], v[36:37], v[10:11], v[122:123] op_sel:[0,1,0]
	v_pk_fma_f32 v[10:11], v[34:35], v[10:11], v[124:125] op_sel:[0,1,0]
	v_pk_fma_f32 v[34:35], v[40:41], v[16:17], v[110:111] op_sel_hi:[1,0,1]
	v_pk_fma_f32 v[14:15], v[38:39], v[16:17], v[14:15] op_sel_hi:[1,0,1]
	v_pk_fma_f32 v[20:21], v[44:45], v[8:9], v[32:33] op_sel_hi:[1,0,1]
	v_pk_fma_f32 v[18:19], v[42:43], v[8:9], v[18:19] op_sel_hi:[1,0,1]
	v_mov_b32_e32 v8, v17
	v_pk_fma_f32 v[36:37], v[40:41], v[12:13], v[112:113] op_sel_hi:[1,0,1]
	v_pk_fma_f32 v[10:11], v[38:39], v[12:13], v[10:11] op_sel_hi:[1,0,1]
	v_pk_fma_f32 v[16:17], v[44:45], v[8:9], v[34:35] op_sel_hi:[1,0,1]
	v_pk_fma_f32 v[14:15], v[42:43], v[8:9], v[14:15] op_sel_hi:[1,0,1]
	v_mov_b32_e32 v8, v13
	v_pk_fma_f32 v[32:33], v[44:45], v[8:9], v[36:37] op_sel_hi:[1,0,1]
	v_pk_fma_f32 v[34:35], v[42:43], v[8:9], v[10:11] op_sel_hi:[1,0,1]
	v_mov_b32_e32 v8, v9
	v_pk_fma_f32 v[36:37], v[44:45], v[8:9], v[4:5] op_sel_hi:[1,0,1]
	v_pk_fma_f32 v[38:39], v[42:43], v[8:9], v[2:3] op_sel_hi:[1,0,1]
	s_waitcnt vmcnt(11)
	v_pk_fma_f32 v[40:41], v[48:49], v[98:99], v[6:7] op_sel_hi:[1,0,1]
	ds_read_b128 v[2:5], v29 offset:528
	ds_read_b128 v[6:9], v29 offset:1040
	ds_read_b128 v[10:13], v29 offset:1552
	v_pk_fma_f32 v[30:31], v[46:47], v[98:99], v[30:31] op_sel_hi:[1,0,1]
	s_waitcnt vmcnt(10)
	v_pk_fma_f32 v[40:41], v[52:53], v[98:99], v[40:41] op_sel:[0,1,0]
	s_waitcnt lgkmcnt(2)
	v_pk_fma_f32 v[20:21], v[48:49], v[2:3], v[20:21] op_sel_hi:[1,0,1]
	s_waitcnt lgkmcnt(1)
	v_pk_fma_f32 v[42:43], v[48:49], v[6:7], v[16:17] op_sel_hi:[1,0,1]
	v_pk_fma_f32 v[44:45], v[46:47], v[6:7], v[14:15] op_sel_hi:[1,0,1]
	ds_read_b128 v[14:17], v29 offset:2064
	v_pk_fma_f32 v[18:19], v[46:47], v[2:3], v[18:19] op_sel_hi:[1,0,1]
	s_waitcnt lgkmcnt(1)
	v_pk_fma_f32 v[32:33], v[48:49], v[10:11], v[32:33] op_sel_hi:[1,0,1]
	v_pk_fma_f32 v[34:35], v[46:47], v[10:11], v[34:35] op_sel_hi:[1,0,1]
	v_pk_fma_f32 v[30:31], v[50:51], v[98:99], v[30:31] op_sel:[0,1,0]
	s_waitcnt lgkmcnt(0)
	v_pk_fma_f32 v[36:37], v[48:49], v[14:15], v[36:37] op_sel_hi:[1,0,1]
	v_pk_fma_f32 v[20:21], v[52:53], v[2:3], v[20:21] op_sel:[0,1,0]
	v_pk_fma_f32 v[2:3], v[50:51], v[2:3], v[18:19] op_sel:[0,1,0]
	v_pk_fma_f32 v[32:33], v[52:53], v[10:11], v[32:33] op_sel:[0,1,0]
	v_pk_fma_f32 v[10:11], v[50:51], v[10:11], v[34:35] op_sel:[0,1,0]
	v_pk_fma_f32 v[34:35], v[52:53], v[14:15], v[36:37] op_sel:[0,1,0]
	s_waitcnt vmcnt(9)
	v_pk_fma_f32 v[36:37], v[56:57], v[100:101], v[40:41] op_sel_hi:[1,0,1]
	v_pk_fma_f32 v[30:31], v[54:55], v[100:101], v[30:31] op_sel_hi:[1,0,1]
	v_pk_fma_f32 v[20:21], v[56:57], v[4:5], v[20:21] op_sel_hi:[1,0,1]
	v_pk_fma_f32 v[2:3], v[54:55], v[4:5], v[2:3] op_sel_hi:[1,0,1]
	v_mov_b32_e32 v4, v101
	v_pk_fma_f32 v[38:39], v[46:47], v[14:15], v[38:39] op_sel_hi:[1,0,1]
	v_pk_fma_f32 v[18:19], v[52:53], v[6:7], v[42:43] op_sel:[0,1,0]
	v_pk_fma_f32 v[6:7], v[50:51], v[6:7], v[44:45] op_sel:[0,1,0]
	s_waitcnt vmcnt(8)
	v_pk_fma_f32 v[36:37], v[60:61], v[4:5], v[36:37] op_sel_hi:[1,0,1]
	v_pk_fma_f32 v[30:31], v[58:59], v[4:5], v[30:31] op_sel_hi:[1,0,1]
	v_mov_b32_e32 v4, v5
	v_pk_fma_f32 v[14:15], v[50:51], v[14:15], v[38:39] op_sel:[0,1,0]
	v_pk_fma_f32 v[18:19], v[56:57], v[8:9], v[18:19] op_sel_hi:[1,0,1]
	v_pk_fma_f32 v[6:7], v[54:55], v[8:9], v[6:7] op_sel_hi:[1,0,1]
	v_pk_fma_f32 v[38:39], v[58:59], v[4:5], v[2:3] op_sel_hi:[1,0,1]
	v_mov_b32_e32 v2, v9
	v_pk_fma_f32 v[32:33], v[56:57], v[12:13], v[32:33] op_sel_hi:[1,0,1]
	v_pk_fma_f32 v[10:11], v[54:55], v[12:13], v[10:11] op_sel_hi:[1,0,1]
	v_pk_fma_f32 v[18:19], v[60:61], v[2:3], v[18:19] op_sel_hi:[1,0,1]
	v_pk_fma_f32 v[40:41], v[58:59], v[2:3], v[6:7] op_sel_hi:[1,0,1]
	v_mov_b32_e32 v2, v13
	v_pk_fma_f32 v[34:35], v[56:57], v[16:17], v[34:35] op_sel_hi:[1,0,1]
	v_pk_fma_f32 v[14:15], v[54:55], v[16:17], v[14:15] op_sel_hi:[1,0,1]
	v_pk_fma_f32 v[32:33], v[60:61], v[2:3], v[32:33] op_sel_hi:[1,0,1]
	v_pk_fma_f32 v[42:43], v[58:59], v[2:3], v[10:11] op_sel_hi:[1,0,1]
	v_mov_b32_e32 v2, v17
	v_pk_fma_f32 v[20:21], v[60:61], v[4:5], v[20:21] op_sel_hi:[1,0,1]
	v_pk_fma_f32 v[34:35], v[60:61], v[2:3], v[34:35] op_sel_hi:[1,0,1]
	v_pk_fma_f32 v[44:45], v[58:59], v[2:3], v[14:15] op_sel_hi:[1,0,1]
	ds_read_b128 v[2:5], v29 offset:544
	ds_read_b128 v[6:9], v29 offset:1056
	ds_read_b128 v[10:13], v29 offset:1568
	ds_read_b128 v[14:17], v29 offset:2080
	s_waitcnt vmcnt(7)
	v_pk_fma_f32 v[36:37], v[64:65], v[102:103], v[36:37] op_sel_hi:[1,0,1]
	v_pk_fma_f32 v[30:31], v[62:63], v[102:103], v[30:31] op_sel_hi:[1,0,1]
	s_waitcnt lgkmcnt(3)
	v_pk_fma_f32 v[20:21], v[64:65], v[2:3], v[20:21] op_sel_hi:[1,0,1]
	v_pk_fma_f32 v[38:39], v[62:63], v[2:3], v[38:39] op_sel_hi:[1,0,1]
	s_waitcnt vmcnt(6)
	v_pk_fma_f32 v[36:37], v[68:69], v[102:103], v[36:37] op_sel:[0,1,0]
	v_pk_fma_f32 v[30:31], v[66:67], v[102:103], v[30:31] op_sel:[0,1,0]
	v_pk_fma_f32 v[20:21], v[68:69], v[2:3], v[20:21] op_sel:[0,1,0]
	v_pk_fma_f32 v[2:3], v[66:67], v[2:3], v[38:39] op_sel:[0,1,0]
	s_waitcnt lgkmcnt(2)
	v_pk_fma_f32 v[18:19], v[64:65], v[6:7], v[18:19] op_sel_hi:[1,0,1]
	v_pk_fma_f32 v[40:41], v[62:63], v[6:7], v[40:41] op_sel_hi:[1,0,1]
	s_waitcnt vmcnt(5)
	v_pk_fma_f32 v[36:37], v[72:73], v[104:105], v[36:37] op_sel_hi:[1,0,1]
	v_pk_fma_f32 v[30:31], v[70:71], v[104:105], v[30:31] op_sel_hi:[1,0,1]
	v_pk_fma_f32 v[20:21], v[72:73], v[4:5], v[20:21] op_sel_hi:[1,0,1]
	v_pk_fma_f32 v[2:3], v[70:71], v[4:5], v[2:3] op_sel_hi:[1,0,1]
	v_mov_b32_e32 v4, v105
	s_waitcnt lgkmcnt(1)
	v_pk_fma_f32 v[32:33], v[64:65], v[10:11], v[32:33] op_sel_hi:[1,0,1]
	v_pk_fma_f32 v[42:43], v[62:63], v[10:11], v[42:43] op_sel_hi:[1,0,1]
	v_pk_fma_f32 v[18:19], v[68:69], v[6:7], v[18:19] op_sel:[0,1,0]
	v_pk_fma_f32 v[6:7], v[66:67], v[6:7], v[40:41] op_sel:[0,1,0]
	s_waitcnt vmcnt(4)
	v_pk_fma_f32 v[36:37], v[76:77], v[4:5], v[36:37] op_sel_hi:[1,0,1]
	v_pk_fma_f32 v[30:31], v[74:75], v[4:5], v[30:31] op_sel_hi:[1,0,1]
	v_mov_b32_e32 v4, v5
	s_waitcnt lgkmcnt(0)
	v_pk_fma_f32 v[34:35], v[64:65], v[14:15], v[34:35] op_sel_hi:[1,0,1]
	v_pk_fma_f32 v[44:45], v[62:63], v[14:15], v[44:45] op_sel_hi:[1,0,1]
	v_pk_fma_f32 v[32:33], v[68:69], v[10:11], v[32:33] op_sel:[0,1,0]
	v_pk_fma_f32 v[10:11], v[66:67], v[10:11], v[42:43] op_sel:[0,1,0]
	v_pk_fma_f32 v[18:19], v[72:73], v[8:9], v[18:19] op_sel_hi:[1,0,1]
	v_pk_fma_f32 v[6:7], v[70:71], v[8:9], v[6:7] op_sel_hi:[1,0,1]
	v_pk_fma_f32 v[38:39], v[74:75], v[4:5], v[2:3] op_sel_hi:[1,0,1]
	v_mov_b32_e32 v2, v9
	v_pk_fma_f32 v[34:35], v[68:69], v[14:15], v[34:35] op_sel:[0,1,0]
	v_pk_fma_f32 v[14:15], v[66:67], v[14:15], v[44:45] op_sel:[0,1,0]
	v_pk_fma_f32 v[32:33], v[72:73], v[12:13], v[32:33] op_sel_hi:[1,0,1]
	v_pk_fma_f32 v[10:11], v[70:71], v[12:13], v[10:11] op_sel_hi:[1,0,1]
	v_pk_fma_f32 v[18:19], v[76:77], v[2:3], v[18:19] op_sel_hi:[1,0,1]
	v_pk_fma_f32 v[40:41], v[74:75], v[2:3], v[6:7] op_sel_hi:[1,0,1]
	v_mov_b32_e32 v2, v13
	v_pk_fma_f32 v[34:35], v[72:73], v[16:17], v[34:35] op_sel_hi:[1,0,1]
	v_pk_fma_f32 v[14:15], v[70:71], v[16:17], v[14:15] op_sel_hi:[1,0,1]
	v_pk_fma_f32 v[12:13], v[76:77], v[2:3], v[32:33] op_sel_hi:[1,0,1]
	v_pk_fma_f32 v[10:11], v[74:75], v[2:3], v[10:11] op_sel_hi:[1,0,1]
	v_mov_b32_e32 v2, v17
	v_pk_fma_f32 v[20:21], v[76:77], v[4:5], v[20:21] op_sel_hi:[1,0,1]
	v_pk_fma_f32 v[16:17], v[76:77], v[2:3], v[34:35] op_sel_hi:[1,0,1]
	v_pk_fma_f32 v[14:15], v[74:75], v[2:3], v[14:15] op_sel_hi:[1,0,1]
	ds_read_b128 v[2:5], v29 offset:560
	ds_read_b128 v[6:9], v29 offset:1072
	s_waitcnt vmcnt(3)
	v_pk_fma_f32 v[42:43], v[80:81], v[106:107], v[36:37] op_sel_hi:[1,0,1]
	v_pk_fma_f32 v[44:45], v[78:79], v[106:107], v[30:31] op_sel_hi:[1,0,1]
	ds_read_b128 v[30:33], v29 offset:1584
	ds_read_b128 v[34:37], v29 offset:2096
	s_waitcnt lgkmcnt(3)
	v_pk_fma_f32 v[20:21], v[80:81], v[2:3], v[20:21] op_sel_hi:[1,0,1]
	v_pk_fma_f32 v[38:39], v[78:79], v[2:3], v[38:39] op_sel_hi:[1,0,1]
	s_waitcnt lgkmcnt(2)
	v_pk_fma_f32 v[18:19], v[80:81], v[6:7], v[18:19] op_sel_hi:[1,0,1]
	s_waitcnt lgkmcnt(1)
	v_pk_fma_f32 v[12:13], v[80:81], v[30:31], v[12:13] op_sel_hi:[1,0,1]
	v_pk_fma_f32 v[10:11], v[78:79], v[30:31], v[10:11] op_sel_hi:[1,0,1]
	s_waitcnt lgkmcnt(0)
	v_pk_fma_f32 v[16:17], v[80:81], v[34:35], v[16:17] op_sel_hi:[1,0,1]
	v_pk_fma_f32 v[14:15], v[78:79], v[34:35], v[14:15] op_sel_hi:[1,0,1]
	s_waitcnt vmcnt(2)
	v_pk_fma_f32 v[42:43], v[84:85], v[106:107], v[42:43] op_sel:[0,1,0]
	v_pk_fma_f32 v[44:45], v[82:83], v[106:107], v[44:45] op_sel:[0,1,0]
	v_pk_fma_f32 v[20:21], v[84:85], v[2:3], v[20:21] op_sel:[0,1,0]
	v_pk_fma_f32 v[2:3], v[82:83], v[2:3], v[38:39] op_sel:[0,1,0]
	v_pk_fma_f32 v[40:41], v[78:79], v[6:7], v[40:41] op_sel_hi:[1,0,1]
	v_pk_fma_f32 v[18:19], v[84:85], v[6:7], v[18:19] op_sel:[0,1,0]
	v_pk_fma_f32 v[12:13], v[84:85], v[30:31], v[12:13] op_sel:[0,1,0]
	v_pk_fma_f32 v[10:11], v[82:83], v[30:31], v[10:11] op_sel:[0,1,0]
	v_pk_fma_f32 v[16:17], v[84:85], v[34:35], v[16:17] op_sel:[0,1,0]
	v_pk_fma_f32 v[14:15], v[82:83], v[34:35], v[14:15] op_sel:[0,1,0]
	s_waitcnt vmcnt(1)
	v_pk_fma_f32 v[30:31], v[88:89], v[108:109], v[42:43] op_sel_hi:[1,0,1]
	v_pk_fma_f32 v[34:35], v[86:87], v[108:109], v[44:45] op_sel_hi:[1,0,1]
	v_pk_fma_f32 v[38:39], v[88:89], v[4:5], v[20:21] op_sel_hi:[1,0,1]
	v_pk_fma_f32 v[2:3], v[86:87], v[4:5], v[2:3] op_sel_hi:[1,0,1]
	v_mov_b32_e32 v4, v109
	v_pk_fma_f32 v[6:7], v[82:83], v[6:7], v[40:41] op_sel:[0,1,0]
	v_pk_fma_f32 v[40:41], v[88:89], v[8:9], v[18:19] op_sel_hi:[1,0,1]
	s_waitcnt vmcnt(0)
	v_pk_fma_f32 v[20:21], v[92:93], v[4:5], v[30:31] op_sel_hi:[1,0,1]
	v_pk_fma_f32 v[18:19], v[90:91], v[4:5], v[34:35] op_sel_hi:[1,0,1]
	v_mov_b32_e32 v4, v5
	v_pk_fma_f32 v[6:7], v[86:87], v[8:9], v[6:7] op_sel_hi:[1,0,1]
	v_pk_fma_f32 v[48:49], v[86:87], v[36:37], v[14:15] op_sel_hi:[1,0,1]
	v_pk_fma_f32 v[14:15], v[90:91], v[4:5], v[2:3] op_sel_hi:[1,0,1]
	v_mov_b32_e32 v2, v9
	v_pk_fma_f32 v[42:43], v[88:89], v[32:33], v[12:13] op_sel_hi:[1,0,1]
	v_pk_fma_f32 v[44:45], v[86:87], v[32:33], v[10:11] op_sel_hi:[1,0,1]
	v_pk_fma_f32 v[12:13], v[92:93], v[2:3], v[40:41] op_sel_hi:[1,0,1]
	v_pk_fma_f32 v[10:11], v[90:91], v[2:3], v[6:7] op_sel_hi:[1,0,1]
	v_mov_b32_e32 v2, v33
	v_pk_fma_f32 v[46:47], v[88:89], v[36:37], v[16:17] op_sel_hi:[1,0,1]
	v_pk_fma_f32 v[8:9], v[92:93], v[2:3], v[42:43] op_sel_hi:[1,0,1]
	v_pk_fma_f32 v[6:7], v[90:91], v[2:3], v[44:45] op_sel_hi:[1,0,1]
	v_mov_b32_e32 v2, v37
	v_pk_fma_f32 v[16:17], v[92:93], v[4:5], v[38:39] op_sel_hi:[1,0,1]
	v_pk_fma_f32 v[4:5], v[92:93], v[2:3], v[46:47] op_sel_hi:[1,0,1]
	v_pk_fma_f32 v[2:3], v[90:91], v[2:3], v[48:49] op_sel_hi:[1,0,1]
	s_cbranch_scc0 .LBB0_347
	s_lshl_b32 s21, s21, 4
	s_add_i32 s21, s21, 16
	s_and_b32 s21, s21, 16
	s_add_i32 s21, s22, s21
	s_mul_hi_i32 s24, s21, 0x3c000
	s_mul_i32 s21, s21, 0x3c000
	s_add_u32 s22, s7, s21
	s_addc_u32 s23, s8, s24
	s_add_u32 s22, s22, s4
	s_addc_u32 s23, s23, s5
	global_store_dwordx4 v22, v[18:21], s[22:23]
	s_add_u32 s22, s9, s21
	s_addc_u32 s23, s10, s24
	s_add_u32 s22, s22, s4
	s_addc_u32 s23, s23, s5
	global_store_dwordx4 v22, v[14:17], s[22:23]
	s_add_u32 s22, s11, s21
	s_addc_u32 s23, s12, s24
	s_add_u32 s22, s22, s4
	s_addc_u32 s23, s23, s5
	global_store_dwordx4 v22, v[10:13], s[22:23]
	s_add_u32 s22, s13, s21
	s_addc_u32 s23, s14, s24
	s_add_u32 s22, s22, s4
	s_addc_u32 s23, s23, s5
	s_add_u32 s21, s15, s21
	global_store_dwordx4 v22, v[6:9], s[22:23]
	s_addc_u32 s22, s16, s24
	s_add_u32 s4, s21, s4
	s_addc_u32 s5, s22, s5
	global_store_dwordx4 v22, v[2:5], s[4:5]
	s_waitcnt lgkmcnt(0)
	s_add_i32 s52, s52, s53
	s_cmpk_gt_i32 s52, 0x2ff
	s_cbranch_scc0 .LBB0_346

.LBB0_355:
	s_and_b32 s6, s12, 0xffff
	s_mul_hi_u32 s2, s6, 0x1745d18
	s_mul_i32 s7, s2, 0x1600
	s_sub_i32 s7, s14, s7
	s_mulk_i32 s2, 0x2c00
	s_mul_i32 s6, s6, 0xba2f
	s_bfe_i32 s10, s12, 0x10001
	s_sub_i32 s2, s16, s2
	s_lshr_b32 s6, s6, 17
	s_and_b32 s10, s10, 0x1600
	s_and_b32 s7, s7, 0xffffff80
	s_and_b32 s18, s6, 0x7fc0
	s_and_b32 s6, s2, 64
	s_add_i32 s7, s7, s10
	s_or_b32 s10, s7, s6
	s_cmpk_gt_i32 s10, 0x2bff
	s_cselect_b64 s[6:7], -1, 0
	s_mov_b64 s[8:9], s[50:51]
	s_and_b64 vcc, exec, s[6:7]
	s_cbranch_vccnz .LBB0_357
	v_or_b32_e32 v2, s18, v14
	v_mul_u32_u24_e32 v2, 0xb000, v2
	v_mov_b32_e32 v3, v7
	v_lshl_add_u64 v[2:3], s[8:9], 0, v[2:3]
	s_ashr_i32 s11, s10, 31
	v_lshl_add_u64 v[2:3], s[10:11], 2, v[2:3]
	v_mov_b32_e32 v9, v7
	v_lshl_add_u64 v[104:105], v[2:3], 0, v[8:9]
	v_add_co_u32_e32 v10, vcc, 0x2c000, v104
	s_nop 1
	v_addc_co_u32_e32 v11, vcc, 0, v105, vcc
	v_add_co_u32_e32 v52, vcc, 0x58000, v104
	global_load_dwordx4 v[2:5], v[104:105], off nt
	s_nop 0
	global_load_dwordx4 v[10:13], v[10:11], off nt
	v_addc_co_u32_e32 v53, vcc, 0, v105, vcc
	v_add_co_u32_e32 v56, vcc, 0x84000, v104
	s_nop 1
	v_addc_co_u32_e32 v57, vcc, 0, v105, vcc
	v_add_co_u32_e32 v60, vcc, 0xb0000, v104
	global_load_dwordx4 v[52:55], v[52:53], off nt
	s_nop 0
	global_load_dwordx4 v[56:59], v[56:57], off nt
	v_addc_co_u32_e32 v61, vcc, 0, v105, vcc
	v_add_co_u32_e32 v64, vcc, 0xdc000, v104
	s_nop 1
	v_addc_co_u32_e32 v65, vcc, 0, v105, vcc
	v_add_co_u32_e32 v68, vcc, 0x108000, v104
	global_load_dwordx4 v[60:63], v[60:61], off nt
	s_nop 0
	global_load_dwordx4 v[64:67], v[64:65], off nt
	v_addc_co_u32_e32 v69, vcc, 0, v105, vcc
	v_add_co_u32_e32 v72, vcc, 0x134000, v104
	s_nop 1
	v_addc_co_u32_e32 v73, vcc, 0, v105, vcc
	v_add_co_u32_e32 v76, vcc, 0x160000, v104
	global_load_dwordx4 v[68:71], v[68:69], off nt
	s_nop 0
	global_load_dwordx4 v[72:75], v[72:73], off nt
	v_addc_co_u32_e32 v77, vcc, 0, v105, vcc
	v_add_co_u32_e32 v80, vcc, 0x18c000, v104
	s_nop 1
	v_addc_co_u32_e32 v81, vcc, 0, v105, vcc
	v_add_co_u32_e32 v84, vcc, 0x1b8000, v104
	global_load_dwordx4 v[76:79], v[76:77], off nt
	s_nop 0
	global_load_dwordx4 v[80:83], v[80:81], off nt
	v_addc_co_u32_e32 v85, vcc, 0, v105, vcc
	v_add_co_u32_e32 v88, vcc, 0x1e4000, v104
	s_nop 1
	v_addc_co_u32_e32 v89, vcc, 0, v105, vcc
	v_add_co_u32_e32 v92, vcc, 0x210000, v104
	global_load_dwordx4 v[84:87], v[84:85], off nt
	s_nop 0
	global_load_dwordx4 v[88:91], v[88:89], off nt
	v_addc_co_u32_e32 v93, vcc, 0, v105, vcc
	v_add_co_u32_e32 v96, vcc, 0x23c000, v104
	s_nop 1
	v_addc_co_u32_e32 v97, vcc, 0, v105, vcc
	global_load_dwordx4 v[92:95], v[92:93], off nt
	s_nop 0
	global_load_dwordx4 v[96:99], v[96:97], off nt
	v_add_co_u32_e32 v100, vcc, 0x268000, v104
	s_nop 1
	v_addc_co_u32_e32 v101, vcc, 0, v105, vcc
	global_load_dwordx4 v[100:103], v[100:101], off nt
	v_add_co_u32_e32 v104, vcc, 0x294000, v104
	s_nop 1
	v_addc_co_u32_e32 v105, vcc, 0, v105, vcc
	global_load_dwordx4 v[104:107], v[104:105], off nt
	s_waitcnt vmcnt(0)
	ds_write2_b32 v17, v2, v3 offset1:1
	ds_write2_b32 v17, v4, v5 offset0:2 offset1:3
	ds_write2_b32 v18, v10, v11 offset1:1
	ds_write2_b32 v19, v12, v13 offset1:1
	ds_write2_b32 v20, v52, v53 offset1:1
	ds_write2_b32 v21, v54, v55 offset1:1
	ds_write2_b32 v22, v56, v57 offset1:1
	ds_write2_b32 v23, v58, v59 offset1:1
	ds_write2_b32 v24, v60, v61 offset1:1
	ds_write2_b32 v25, v62, v63 offset1:1
	ds_write2_b32 v26, v64, v65 offset1:1
	ds_write2_b32 v27, v66, v67 offset1:1
	ds_write2_b32 v28, v68, v69 offset1:1
	ds_write2_b32 v29, v70, v71 offset1:1
	ds_write2_b32 v30, v72, v73 offset1:1
	ds_write2_b32 v31, v74, v75 offset1:1
	ds_write2_b32 v32, v76, v77 offset1:1
	ds_write2_b32 v33, v78, v79 offset1:1
	ds_write2_b32 v34, v80, v81 offset1:1
	ds_write2_b32 v35, v82, v83 offset1:1
	ds_write2_b32 v36, v84, v85 offset1:1
	ds_write2_b32 v37, v86, v87 offset1:1
	ds_write2_b32 v38, v88, v89 offset1:1
	ds_write2_b32 v39, v90, v91 offset1:1
	ds_write2_b32 v40, v92, v93 offset1:1
	ds_write2_b32 v41, v94, v95 offset1:1
	ds_write2_b32 v42, v96, v97 offset1:1
	ds_write2_b32 v43, v98, v99 offset1:1
	ds_write2_b32 v44, v100, v101 offset1:1
	ds_write2_b32 v45, v102, v103 offset1:1
	ds_write2_b32 v46, v104, v105 offset1:1
	ds_write2_b32 v47, v106, v107 offset1:1

.LBB0_380:
	s_add_i32 s0, s15, s19
	s_ashr_i32 s1, s0, 31
	s_lshr_b32 s1, s1, 27
	s_add_i32 s0, s0, s1
	s_ashr_i32 s0, s0, 5
	s_lshl_b32 s5, s0, 11
	s_lshl_b32 s4, s0, 6
	s_sub_i32 s0, s16, s5
	v_readlane_b32 s64, v250, 2
	s_cmpk_gt_i32 s0, 0x7ff
	v_readlane_b32 s65, v250, 3
	s_cselect_b64 s[6:7], -1, 0
	s_mov_b64 s[8:9], s[64:65]
	s_and_b64 vcc, exec, s[6:7]
	v_readlane_b32 s66, v250, 4
	v_readlane_b32 s67, v250, 5
	v_readlane_b32 s68, v250, 6
	v_readlane_b32 s69, v250, 7
	v_readlane_b32 s70, v250, 8
	v_readlane_b32 s71, v250, 9
	v_readlane_b32 s72, v250, 10
	v_readlane_b32 s73, v250, 11
	v_readlane_b32 s74, v250, 12
	v_readlane_b32 s75, v250, 13
	v_readlane_b32 s76, v250, 14
	v_readlane_b32 s77, v250, 15
	v_readlane_b32 s78, v250, 16
	v_readlane_b32 s79, v250, 17
	s_cbranch_vccnz .LBB0_382
	v_or_b32_e32 v2, s4, v10
	v_ashrrev_i32_e32 v3, 31, v2
	v_lshlrev_b64 v[2:3], 13, v[2:3]
	v_lshl_add_u64 v[2:3], s[8:9], 0, v[2:3]
	s_ashr_i32 s1, s0, 31
	v_lshl_add_u64 v[2:3], s[0:1], 2, v[2:3]
	v_mov_b32_e32 v9, v7
	v_lshl_add_u64 v[58:59], v[2:3], 0, v[8:9]
	v_add_co_u32_e32 v64, vcc, 0x8000, v58
	s_nop 1
	v_addc_co_u32_e32 v65, vcc, 0, v59, vcc
	v_add_co_u32_e32 v68, vcc, 0x10000, v58
	global_load_dwordx4 v[2:5], v[58:59], off nt
	s_nop 0
	global_load_dwordx4 v[64:67], v[64:65], off nt
	v_addc_co_u32_e32 v69, vcc, 0, v59, vcc
	v_add_co_u32_e32 v72, vcc, 0x18000, v58
	s_nop 1
	v_addc_co_u32_e32 v73, vcc, 0, v59, vcc
	v_add_co_u32_e32 v76, vcc, 0x20000, v58
	global_load_dwordx4 v[68:71], v[68:69], off nt
	s_nop 0
	global_load_dwordx4 v[72:75], v[72:73], off nt
	v_addc_co_u32_e32 v77, vcc, 0, v59, vcc
	v_add_co_u32_e32 v80, vcc, 0x28000, v58
	s_nop 1
	v_addc_co_u32_e32 v81, vcc, 0, v59, vcc
	v_add_co_u32_e32 v84, vcc, 0x30000, v58
	global_load_dwordx4 v[76:79], v[76:77], off nt
	s_nop 0
	global_load_dwordx4 v[80:83], v[80:81], off nt
	v_addc_co_u32_e32 v85, vcc, 0, v59, vcc
	v_add_co_u32_e32 v88, vcc, 0x38000, v58
	s_nop 1
	v_addc_co_u32_e32 v89, vcc, 0, v59, vcc
	v_add_co_u32_e32 v92, vcc, 0x40000, v58
	global_load_dwordx4 v[84:87], v[84:85], off nt
	s_nop 0
	global_load_dwordx4 v[88:91], v[88:89], off nt
	v_addc_co_u32_e32 v93, vcc, 0, v59, vcc
	v_add_co_u32_e32 v96, vcc, 0x48000, v58
	s_nop 1
	v_addc_co_u32_e32 v97, vcc, 0, v59, vcc
	v_add_co_u32_e32 v100, vcc, 0x50000, v58
	global_load_dwordx4 v[92:95], v[92:93], off nt
	s_nop 0
	global_load_dwordx4 v[96:99], v[96:97], off nt
	v_addc_co_u32_e32 v101, vcc, 0, v59, vcc
	v_add_co_u32_e32 v104, vcc, 0x58000, v58
	s_nop 1
	v_addc_co_u32_e32 v105, vcc, 0, v59, vcc
	v_add_co_u32_e32 v108, vcc, 0x60000, v58
	global_load_dwordx4 v[100:103], v[100:101], off nt
	s_nop 0
	global_load_dwordx4 v[104:107], v[104:105], off nt
	v_addc_co_u32_e32 v109, vcc, 0, v59, vcc
	v_add_co_u32_e32 v112, vcc, 0x68000, v58
	s_nop 1
	v_addc_co_u32_e32 v113, vcc, 0, v59, vcc
	global_load_dwordx4 v[108:111], v[108:109], off nt
	s_nop 0
	global_load_dwordx4 v[112:115], v[112:113], off nt
	v_add_co_u32_e32 v116, vcc, 0x70000, v58
	s_nop 1
	v_addc_co_u32_e32 v117, vcc, 0, v59, vcc
	global_load_dwordx4 v[116:119], v[116:117], off nt
	v_add_co_u32_e32 v58, vcc, 0x78000, v58
	s_nop 1
	v_addc_co_u32_e32 v59, vcc, 0, v59, vcc
	global_load_dwordx4 v[120:123], v[58:59], off nt
	s_waitcnt vmcnt(0)
	ds_write2_b32 v27, v2, v3 offset1:1
	ds_write2_b32 v27, v4, v5 offset0:2 offset1:3
	ds_write2_b32 v28, v64, v65 offset1:1
	ds_write2_b32 v29, v66, v67 offset1:1
	ds_write2_b32 v30, v68, v69 offset1:1
	ds_write2_b32 v31, v70, v71 offset1:1
	ds_write2_b32 v32, v72, v73 offset1:1
	ds_write2_b32 v33, v74, v75 offset1:1
	ds_write2_b32 v34, v76, v77 offset1:1
	ds_write2_b32 v35, v78, v79 offset1:1
	ds_write2_b32 v36, v80, v81 offset1:1
	ds_write2_b32 v37, v82, v83 offset1:1
	ds_write2_b32 v38, v84, v85 offset1:1
	ds_write2_b32 v39, v86, v87 offset1:1
	ds_write2_b32 v40, v88, v89 offset1:1
	ds_write2_b32 v41, v90, v91 offset1:1
	ds_write2_b32 v42, v92, v93 offset1:1
	ds_write2_b32 v43, v94, v95 offset1:1
	ds_write2_b32 v44, v96, v97 offset1:1
	ds_write2_b32 v45, v98, v99 offset1:1
	ds_write2_b32 v46, v100, v101 offset1:1
	ds_write2_b32 v47, v102, v103 offset1:1
	ds_write2_b32 v48, v104, v105 offset1:1
	ds_write2_b32 v49, v106, v107 offset1:1
	ds_write2_b32 v50, v108, v109 offset1:1
	ds_write2_b32 v51, v110, v111 offset1:1
	ds_write2_b32 v52, v112, v113 offset1:1
	ds_write2_b32 v53, v114, v115 offset1:1
	ds_write2_b32 v54, v116, v117 offset1:1
	ds_write2_b32 v55, v118, v119 offset1:1
	ds_write2_b32 v56, v120, v121 offset1:1
	ds_write2_b32 v57, v122, v123 offset1:1

.LBB0_401:
	s_mov_b32 s31, 0xfff4c000
	v_add_co_u32_e32 v28, vcc, s31, v26
	s_mov_b32 s31, 0xfff58000
	s_nop 0
	v_addc_co_u32_e32 v29, vcc, -1, v27, vcc
	global_load_dwordx4 v[28:31], v[28:29], off nt
	v_add_co_u32_e32 v32, vcc, s31, v26
	s_mov_b32 s31, 0xfff64000
	s_nop 0
	v_addc_co_u32_e32 v33, vcc, -1, v27, vcc
	v_add_co_u32_e32 v36, vcc, s31, v26
	s_mov_b32 s31, 0xfff70000
	s_nop 0
	v_addc_co_u32_e32 v37, vcc, -1, v27, vcc
	global_load_dwordx4 v[32:35], v[32:33], off nt
	v_add_co_u32_e32 v40, vcc, s31, v26
	global_load_dwordx4 v[36:39], v[36:37], off nt
	s_nop 0
	v_addc_co_u32_e32 v41, vcc, -1, v27, vcc
	global_load_dwordx4 v[40:43], v[40:41], off nt
	s_mov_b32 s31, 0xfff7c000
	v_add_co_u32_e32 v44, vcc, s31, v26
	v_mov_b32_e32 v124, s30
	s_nop 0
	v_addc_co_u32_e32 v45, vcc, -1, v27, vcc
	global_load_dwordx4 v[44:47], v[44:45], off nt
	v_add_co_u32_e32 v48, vcc, s17, v26
	s_add_i32 s29, s29, 16
	s_nop 0
	v_addc_co_u32_e32 v49, vcc, -1, v27, vcc
	v_add_co_u32_e32 v52, vcc, s18, v26
	global_load_dwordx4 v[48:51], v[48:49], off nt
	s_nop 0
	v_addc_co_u32_e32 v53, vcc, -1, v27, vcc
	v_add_co_u32_e32 v56, vcc, s19, v26
	global_load_dwordx4 v[52:55], v[52:53], off nt
	s_nop 0
	v_addc_co_u32_e32 v57, vcc, -1, v27, vcc
	global_load_dwordx4 v[56:59], v[56:57], off nt
	v_add_co_u32_e32 v60, vcc, s20, v26
	s_add_i32 s30, s30, 64
	s_nop 0
	v_addc_co_u32_e32 v61, vcc, -1, v27, vcc
	v_add_co_u32_e32 v64, vcc, s21, v26
	global_load_dwordx4 v[60:63], v[60:61], off nt
	s_nop 0
	v_addc_co_u32_e32 v65, vcc, -1, v27, vcc
	v_add_co_u32_e32 v68, vcc, s22, v26
	global_load_dwordx4 v[64:67], v[64:65], off nt
	s_nop 0
	v_addc_co_u32_e32 v69, vcc, -1, v27, vcc
	v_add_co_u32_e32 v72, vcc, s23, v26
	global_load_dwordx4 v[68:71], v[68:69], off nt
	s_nop 0
	v_addc_co_u32_e32 v73, vcc, -1, v27, vcc
	global_load_dwordx4 v[72:75], v[72:73], off nt
	v_add_co_u32_e32 v76, vcc, s24, v26
	s_cmpk_gt_u32 s29, 0x6f
	s_nop 0
	v_addc_co_u32_e32 v77, vcc, -1, v27, vcc
	global_load_dwordx4 v[76:79], v[76:77], off nt
	v_add_co_u32_e32 v80, vcc, s25, v26
	s_nop 1
	v_addc_co_u32_e32 v81, vcc, -1, v27, vcc
	global_load_dwordx4 v[80:83], v[80:81], off nt
	v_add_co_u32_e32 v84, vcc, s26, v26
	s_nop 1
	v_addc_co_u32_e32 v85, vcc, -1, v27, vcc
	global_load_dwordx4 v[84:87], v[84:85], off nt
	s_nop 0
	global_load_dwordx4 v[88:91], v[26:27], off nt
	ds_read_b128 v[92:95], v124
	ds_read_b128 v[96:99], v124 offset:16
	ds_read_b128 v[100:103], v124 offset:32
	ds_read_b128 v[104:107], v124 offset:48
	v_lshl_add_u64 v[26:27], v[26:27], 0, s[0:1]
	s_waitcnt vmcnt(15) lgkmcnt(3)
	v_pk_fma_f32 v[108:109], v[30:31], v[92:93], v[20:21] op_sel_hi:[1,0,1]
	v_pk_fma_f32 v[110:111], v[28:29], v[92:93], v[18:19] op_sel_hi:[1,0,1]
	ds_read_b128 v[18:21], v124 offset:512
	s_waitcnt lgkmcnt(0)
	v_pk_fma_f32 v[112:113], v[30:31], v[18:19], v[16:17] op_sel_hi:[1,0,1]
	v_pk_fma_f32 v[114:115], v[28:29], v[18:19], v[14:15] op_sel_hi:[1,0,1]
	ds_read_b128 v[14:17], v124 offset:1024
	s_waitcnt lgkmcnt(0)
	v_pk_fma_f32 v[116:117], v[30:31], v[14:15], v[12:13] op_sel_hi:[1,0,1]
	v_pk_fma_f32 v[118:119], v[28:29], v[14:15], v[10:11] op_sel_hi:[1,0,1]
	ds_read_b128 v[10:13], v124 offset:1536
	s_waitcnt lgkmcnt(0)
	v_pk_fma_f32 v[120:121], v[30:31], v[10:11], v[8:9] op_sel_hi:[1,0,1]
	v_pk_fma_f32 v[122:123], v[28:29], v[10:11], v[6:7] op_sel_hi:[1,0,1]
	ds_read_b128 v[6:9], v124 offset:2048
	s_waitcnt lgkmcnt(0)
	v_pk_fma_f32 v[4:5], v[30:31], v[6:7], v[4:5] op_sel_hi:[1,0,1]
	v_pk_fma_f32 v[2:3], v[28:29], v[6:7], v[2:3] op_sel_hi:[1,0,1]
	s_waitcnt vmcnt(14)
	v_pk_fma_f32 v[28:29], v[34:35], v[92:93], v[108:109] op_sel:[0,1,0]
	v_pk_fma_f32 v[30:31], v[32:33], v[92:93], v[110:111] op_sel:[0,1,0]
	v_pk_fma_f32 v[4:5], v[34:35], v[6:7], v[4:5] op_sel:[0,1,0]
	v_pk_fma_f32 v[2:3], v[32:33], v[6:7], v[2:3] op_sel:[0,1,0]
	v_pk_fma_f32 v[92:93], v[34:35], v[18:19], v[112:113] op_sel:[0,1,0]
	v_pk_fma_f32 v[18:19], v[32:33], v[18:19], v[114:115] op_sel:[0,1,0]
	s_waitcnt vmcnt(13)
	v_pk_fma_f32 v[6:7], v[38:39], v[94:95], v[28:29] op_sel_hi:[1,0,1]
	v_pk_fma_f32 v[28:29], v[36:37], v[94:95], v[30:31] op_sel_hi:[1,0,1]
	v_pk_fma_f32 v[4:5], v[38:39], v[8:9], v[4:5] op_sel_hi:[1,0,1]
	v_pk_fma_f32 v[2:3], v[36:37], v[8:9], v[2:3] op_sel_hi:[1,0,1]
	v_mov_b32_e32 v8, v95
	v_pk_fma_f32 v[108:109], v[34:35], v[14:15], v[116:117] op_sel:[0,1,0]
	v_pk_fma_f32 v[14:15], v[32:33], v[14:15], v[118:119] op_sel:[0,1,0]
	v_pk_fma_f32 v[30:31], v[38:39], v[20:21], v[92:93] op_sel_hi:[1,0,1]
	v_pk_fma_f32 v[18:19], v[36:37], v[20:21], v[18:19] op_sel_hi:[1,0,1]
	s_waitcnt vmcnt(12)
	v_pk_fma_f32 v[6:7], v[42:43], v[8:9], v[6:7] op_sel_hi:[1,0,1]
	v_pk_fma_f32 v[28:29], v[40:41], v[8:9], v[28:29] op_sel_hi:[1,0,1]
	v_mov_b32_e32 v8, v21
	v_pk_fma_f32 v[110:111], v[34:35], v[10:11], v[120:121] op_sel:[0,1,0]
	v_pk_fma_f32 v[10:11], v[32:33], v[10:11], v[122:123] op_sel:[0,1,0]
	v_pk_fma_f32 v[32:33], v[38:39], v[16:17], v[108:109] op_sel_hi:[1,0,1]
	v_pk_fma_f32 v[14:15], v[36:37], v[16:17], v[14:15] op_sel_hi:[1,0,1]
	v_pk_fma_f32 v[20:21], v[42:43], v[8:9], v[30:31] op_sel_hi:[1,0,1]
	v_pk_fma_f32 v[18:19], v[40:41], v[8:9], v[18:19] op_sel_hi:[1,0,1]
	v_mov_b32_e32 v8, v17
	v_pk_fma_f32 v[34:35], v[38:39], v[12:13], v[110:111] op_sel_hi:[1,0,1]
	v_pk_fma_f32 v[10:11], v[36:37], v[12:13], v[10:11] op_sel_hi:[1,0,1]
	v_pk_fma_f32 v[16:17], v[42:43], v[8:9], v[32:33] op_sel_hi:[1,0,1]
	v_pk_fma_f32 v[14:15], v[40:41], v[8:9], v[14:15] op_sel_hi:[1,0,1]
	v_mov_b32_e32 v8, v13
	v_pk_fma_f32 v[30:31], v[42:43], v[8:9], v[34:35] op_sel_hi:[1,0,1]
	v_pk_fma_f32 v[32:33], v[40:41], v[8:9], v[10:11] op_sel_hi:[1,0,1]
	v_mov_b32_e32 v8, v9
	v_pk_fma_f32 v[34:35], v[42:43], v[8:9], v[4:5] op_sel_hi:[1,0,1]
	v_pk_fma_f32 v[36:37], v[40:41], v[8:9], v[2:3] op_sel_hi:[1,0,1]
	s_waitcnt vmcnt(11)
	v_pk_fma_f32 v[38:39], v[46:47], v[96:97], v[6:7] op_sel_hi:[1,0,1]
	ds_read_b128 v[2:5], v124 offset:528
	ds_read_b128 v[6:9], v124 offset:1040
	ds_read_b128 v[10:13], v124 offset:1552
	v_pk_fma_f32 v[28:29], v[44:45], v[96:97], v[28:29] op_sel_hi:[1,0,1]
	s_waitcnt vmcnt(10)
	v_pk_fma_f32 v[38:39], v[50:51], v[96:97], v[38:39] op_sel:[0,1,0]
	s_waitcnt lgkmcnt(2)
	v_pk_fma_f32 v[20:21], v[46:47], v[2:3], v[20:21] op_sel_hi:[1,0,1]
	s_waitcnt lgkmcnt(1)
	v_pk_fma_f32 v[40:41], v[46:47], v[6:7], v[16:17] op_sel_hi:[1,0,1]
	v_pk_fma_f32 v[42:43], v[44:45], v[6:7], v[14:15] op_sel_hi:[1,0,1]
	ds_read_b128 v[14:17], v124 offset:2064
	v_pk_fma_f32 v[18:19], v[44:45], v[2:3], v[18:19] op_sel_hi:[1,0,1]
	s_waitcnt lgkmcnt(1)
	v_pk_fma_f32 v[30:31], v[46:47], v[10:11], v[30:31] op_sel_hi:[1,0,1]
	v_pk_fma_f32 v[32:33], v[44:45], v[10:11], v[32:33] op_sel_hi:[1,0,1]
	v_pk_fma_f32 v[28:29], v[48:49], v[96:97], v[28:29] op_sel:[0,1,0]
	s_waitcnt lgkmcnt(0)
	v_pk_fma_f32 v[34:35], v[46:47], v[14:15], v[34:35] op_sel_hi:[1,0,1]
	v_pk_fma_f32 v[20:21], v[50:51], v[2:3], v[20:21] op_sel:[0,1,0]
	v_pk_fma_f32 v[2:3], v[48:49], v[2:3], v[18:19] op_sel:[0,1,0]
	v_pk_fma_f32 v[30:31], v[50:51], v[10:11], v[30:31] op_sel:[0,1,0]
	v_pk_fma_f32 v[10:11], v[48:49], v[10:11], v[32:33] op_sel:[0,1,0]
	v_pk_fma_f32 v[32:33], v[50:51], v[14:15], v[34:35] op_sel:[0,1,0]
	s_waitcnt vmcnt(9)
	v_pk_fma_f32 v[34:35], v[54:55], v[98:99], v[38:39] op_sel_hi:[1,0,1]
	v_pk_fma_f32 v[28:29], v[52:53], v[98:99], v[28:29] op_sel_hi:[1,0,1]
	v_pk_fma_f32 v[20:21], v[54:55], v[4:5], v[20:21] op_sel_hi:[1,0,1]
	v_pk_fma_f32 v[2:3], v[52:53], v[4:5], v[2:3] op_sel_hi:[1,0,1]
	v_mov_b32_e32 v4, v99
	v_pk_fma_f32 v[36:37], v[44:45], v[14:15], v[36:37] op_sel_hi:[1,0,1]
	v_pk_fma_f32 v[18:19], v[50:51], v[6:7], v[40:41] op_sel:[0,1,0]
	v_pk_fma_f32 v[6:7], v[48:49], v[6:7], v[42:43] op_sel:[0,1,0]
	s_waitcnt vmcnt(8)
	v_pk_fma_f32 v[34:35], v[58:59], v[4:5], v[34:35] op_sel_hi:[1,0,1]
	v_pk_fma_f32 v[28:29], v[56:57], v[4:5], v[28:29] op_sel_hi:[1,0,1]
	v_mov_b32_e32 v4, v5
	v_pk_fma_f32 v[14:15], v[48:49], v[14:15], v[36:37] op_sel:[0,1,0]
	v_pk_fma_f32 v[18:19], v[54:55], v[8:9], v[18:19] op_sel_hi:[1,0,1]
	v_pk_fma_f32 v[6:7], v[52:53], v[8:9], v[6:7] op_sel_hi:[1,0,1]
	v_pk_fma_f32 v[36:37], v[56:57], v[4:5], v[2:3] op_sel_hi:[1,0,1]
	v_mov_b32_e32 v2, v9
	v_pk_fma_f32 v[30:31], v[54:55], v[12:13], v[30:31] op_sel_hi:[1,0,1]
	v_pk_fma_f32 v[10:11], v[52:53], v[12:13], v[10:11] op_sel_hi:[1,0,1]
	v_pk_fma_f32 v[18:19], v[58:59], v[2:3], v[18:19] op_sel_hi:[1,0,1]
	v_pk_fma_f32 v[38:39], v[56:57], v[2:3], v[6:7] op_sel_hi:[1,0,1]
	v_mov_b32_e32 v2, v13
	v_pk_fma_f32 v[32:33], v[54:55], v[16:17], v[32:33] op_sel_hi:[1,0,1]
	v_pk_fma_f32 v[14:15], v[52:53], v[16:17], v[14:15] op_sel_hi:[1,0,1]
	v_pk_fma_f32 v[30:31], v[58:59], v[2:3], v[30:31] op_sel_hi:[1,0,1]
	v_pk_fma_f32 v[40:41], v[56:57], v[2:3], v[10:11] op_sel_hi:[1,0,1]
	v_mov_b32_e32 v2, v17
	v_pk_fma_f32 v[20:21], v[58:59], v[4:5], v[20:21] op_sel_hi:[1,0,1]
	v_pk_fma_f32 v[32:33], v[58:59], v[2:3], v[32:33] op_sel_hi:[1,0,1]
	v_pk_fma_f32 v[42:43], v[56:57], v[2:3], v[14:15] op_sel_hi:[1,0,1]
	ds_read_b128 v[2:5], v124 offset:544
	ds_read_b128 v[6:9], v124 offset:1056
	ds_read_b128 v[10:13], v124 offset:1568
	ds_read_b128 v[14:17], v124 offset:2080
	s_waitcnt vmcnt(7)
	v_pk_fma_f32 v[34:35], v[62:63], v[100:101], v[34:35] op_sel_hi:[1,0,1]
	v_pk_fma_f32 v[28:29], v[60:61], v[100:101], v[28:29] op_sel_hi:[1,0,1]
	s_waitcnt lgkmcnt(3)
	v_pk_fma_f32 v[20:21], v[62:63], v[2:3], v[20:21] op_sel_hi:[1,0,1]
	v_pk_fma_f32 v[36:37], v[60:61], v[2:3], v[36:37] op_sel_hi:[1,0,1]
	s_waitcnt vmcnt(6)
	v_pk_fma_f32 v[34:35], v[66:67], v[100:101], v[34:35] op_sel:[0,1,0]
	v_pk_fma_f32 v[28:29], v[64:65], v[100:101], v[28:29] op_sel:[0,1,0]
	v_pk_fma_f32 v[20:21], v[66:67], v[2:3], v[20:21] op_sel:[0,1,0]
	v_pk_fma_f32 v[2:3], v[64:65], v[2:3], v[36:37] op_sel:[0,1,0]
	s_waitcnt lgkmcnt(2)
	v_pk_fma_f32 v[18:19], v[62:63], v[6:7], v[18:19] op_sel_hi:[1,0,1]
	v_pk_fma_f32 v[38:39], v[60:61], v[6:7], v[38:39] op_sel_hi:[1,0,1]
	s_waitcnt vmcnt(5)
	v_pk_fma_f32 v[34:35], v[70:71], v[102:103], v[34:35] op_sel_hi:[1,0,1]
	v_pk_fma_f32 v[28:29], v[68:69], v[102:103], v[28:29] op_sel_hi:[1,0,1]
	v_pk_fma_f32 v[20:21], v[70:71], v[4:5], v[20:21] op_sel_hi:[1,0,1]
	v_pk_fma_f32 v[2:3], v[68:69], v[4:5], v[2:3] op_sel_hi:[1,0,1]
	v_mov_b32_e32 v4, v103
	s_waitcnt lgkmcnt(1)
	v_pk_fma_f32 v[30:31], v[62:63], v[10:11], v[30:31] op_sel_hi:[1,0,1]
	v_pk_fma_f32 v[40:41], v[60:61], v[10:11], v[40:41] op_sel_hi:[1,0,1]
	v_pk_fma_f32 v[18:19], v[66:67], v[6:7], v[18:19] op_sel:[0,1,0]
	v_pk_fma_f32 v[6:7], v[64:65], v[6:7], v[38:39] op_sel:[0,1,0]
	s_waitcnt vmcnt(4)
	v_pk_fma_f32 v[34:35], v[74:75], v[4:5], v[34:35] op_sel_hi:[1,0,1]
	v_pk_fma_f32 v[28:29], v[72:73], v[4:5], v[28:29] op_sel_hi:[1,0,1]
	v_mov_b32_e32 v4, v5
	s_waitcnt lgkmcnt(0)
	v_pk_fma_f32 v[32:33], v[62:63], v[14:15], v[32:33] op_sel_hi:[1,0,1]
	v_pk_fma_f32 v[42:43], v[60:61], v[14:15], v[42:43] op_sel_hi:[1,0,1]
	v_pk_fma_f32 v[30:31], v[66:67], v[10:11], v[30:31] op_sel:[0,1,0]
	v_pk_fma_f32 v[10:11], v[64:65], v[10:11], v[40:41] op_sel:[0,1,0]
	v_pk_fma_f32 v[18:19], v[70:71], v[8:9], v[18:19] op_sel_hi:[1,0,1]
	v_pk_fma_f32 v[6:7], v[68:69], v[8:9], v[6:7] op_sel_hi:[1,0,1]
	v_pk_fma_f32 v[36:37], v[72:73], v[4:5], v[2:3] op_sel_hi:[1,0,1]
	v_mov_b32_e32 v2, v9
	v_pk_fma_f32 v[32:33], v[66:67], v[14:15], v[32:33] op_sel:[0,1,0]
	v_pk_fma_f32 v[14:15], v[64:65], v[14:15], v[42:43] op_sel:[0,1,0]
	v_pk_fma_f32 v[30:31], v[70:71], v[12:13], v[30:31] op_sel_hi:[1,0,1]
	v_pk_fma_f32 v[10:11], v[68:69], v[12:13], v[10:11] op_sel_hi:[1,0,1]
	v_pk_fma_f32 v[18:19], v[74:75], v[2:3], v[18:19] op_sel_hi:[1,0,1]
	v_pk_fma_f32 v[38:39], v[72:73], v[2:3], v[6:7] op_sel_hi:[1,0,1]
	v_mov_b32_e32 v2, v13
	v_pk_fma_f32 v[32:33], v[70:71], v[16:17], v[32:33] op_sel_hi:[1,0,1]
	v_pk_fma_f32 v[14:15], v[68:69], v[16:17], v[14:15] op_sel_hi:[1,0,1]
	v_pk_fma_f32 v[12:13], v[74:75], v[2:3], v[30:31] op_sel_hi:[1,0,1]
	v_pk_fma_f32 v[10:11], v[72:73], v[2:3], v[10:11] op_sel_hi:[1,0,1]
	v_mov_b32_e32 v2, v17
	v_pk_fma_f32 v[20:21], v[74:75], v[4:5], v[20:21] op_sel_hi:[1,0,1]
	v_pk_fma_f32 v[16:17], v[74:75], v[2:3], v[32:33] op_sel_hi:[1,0,1]
	v_pk_fma_f32 v[14:15], v[72:73], v[2:3], v[14:15] op_sel_hi:[1,0,1]
	ds_read_b128 v[2:5], v124 offset:560
	ds_read_b128 v[6:9], v124 offset:1072
	s_waitcnt vmcnt(3)
	v_pk_fma_f32 v[40:41], v[78:79], v[104:105], v[34:35] op_sel_hi:[1,0,1]
	v_pk_fma_f32 v[42:43], v[76:77], v[104:105], v[28:29] op_sel_hi:[1,0,1]
	ds_read_b128 v[28:31], v124 offset:1584
	ds_read_b128 v[32:35], v124 offset:2096
	s_waitcnt lgkmcnt(3)
	v_pk_fma_f32 v[20:21], v[78:79], v[2:3], v[20:21] op_sel_hi:[1,0,1]
	v_pk_fma_f32 v[36:37], v[76:77], v[2:3], v[36:37] op_sel_hi:[1,0,1]
	s_waitcnt lgkmcnt(2)
	v_pk_fma_f32 v[18:19], v[78:79], v[6:7], v[18:19] op_sel_hi:[1,0,1]
	s_waitcnt lgkmcnt(1)
	v_pk_fma_f32 v[12:13], v[78:79], v[28:29], v[12:13] op_sel_hi:[1,0,1]
	v_pk_fma_f32 v[10:11], v[76:77], v[28:29], v[10:11] op_sel_hi:[1,0,1]
	s_waitcnt lgkmcnt(0)
	v_pk_fma_f32 v[16:17], v[78:79], v[32:33], v[16:17] op_sel_hi:[1,0,1]
	v_pk_fma_f32 v[14:15], v[76:77], v[32:33], v[14:15] op_sel_hi:[1,0,1]
	s_waitcnt vmcnt(2)
	v_pk_fma_f32 v[40:41], v[82:83], v[104:105], v[40:41] op_sel:[0,1,0]
	v_pk_fma_f32 v[42:43], v[80:81], v[104:105], v[42:43] op_sel:[0,1,0]
	v_pk_fma_f32 v[20:21], v[82:83], v[2:3], v[20:21] op_sel:[0,1,0]
	v_pk_fma_f32 v[2:3], v[80:81], v[2:3], v[36:37] op_sel:[0,1,0]
	v_pk_fma_f32 v[38:39], v[76:77], v[6:7], v[38:39] op_sel_hi:[1,0,1]
	v_pk_fma_f32 v[18:19], v[82:83], v[6:7], v[18:19] op_sel:[0,1,0]
	v_pk_fma_f32 v[12:13], v[82:83], v[28:29], v[12:13] op_sel:[0,1,0]
	v_pk_fma_f32 v[10:11], v[80:81], v[28:29], v[10:11] op_sel:[0,1,0]
	v_pk_fma_f32 v[16:17], v[82:83], v[32:33], v[16:17] op_sel:[0,1,0]
	v_pk_fma_f32 v[14:15], v[80:81], v[32:33], v[14:15] op_sel:[0,1,0]
	s_waitcnt vmcnt(1)
	v_pk_fma_f32 v[28:29], v[86:87], v[106:107], v[40:41] op_sel_hi:[1,0,1]
	v_pk_fma_f32 v[32:33], v[84:85], v[106:107], v[42:43] op_sel_hi:[1,0,1]
	v_pk_fma_f32 v[36:37], v[86:87], v[4:5], v[20:21] op_sel_hi:[1,0,1]
	v_pk_fma_f32 v[2:3], v[84:85], v[4:5], v[2:3] op_sel_hi:[1,0,1]
	v_mov_b32_e32 v4, v107
	v_pk_fma_f32 v[6:7], v[80:81], v[6:7], v[38:39] op_sel:[0,1,0]
	v_pk_fma_f32 v[38:39], v[86:87], v[8:9], v[18:19] op_sel_hi:[1,0,1]
	s_waitcnt vmcnt(0)
	v_pk_fma_f32 v[20:21], v[90:91], v[4:5], v[28:29] op_sel_hi:[1,0,1]
	v_pk_fma_f32 v[18:19], v[88:89], v[4:5], v[32:33] op_sel_hi:[1,0,1]
	v_mov_b32_e32 v4, v5
	v_pk_fma_f32 v[6:7], v[84:85], v[8:9], v[6:7] op_sel_hi:[1,0,1]
	v_pk_fma_f32 v[46:47], v[84:85], v[34:35], v[14:15] op_sel_hi:[1,0,1]
	v_pk_fma_f32 v[14:15], v[88:89], v[4:5], v[2:3] op_sel_hi:[1,0,1]
	v_mov_b32_e32 v2, v9
	v_pk_fma_f32 v[40:41], v[86:87], v[30:31], v[12:13] op_sel_hi:[1,0,1]
	v_pk_fma_f32 v[42:43], v[84:85], v[30:31], v[10:11] op_sel_hi:[1,0,1]
	v_pk_fma_f32 v[12:13], v[90:91], v[2:3], v[38:39] op_sel_hi:[1,0,1]
	v_pk_fma_f32 v[10:11], v[88:89], v[2:3], v[6:7] op_sel_hi:[1,0,1]
	v_mov_b32_e32 v2, v31
	v_pk_fma_f32 v[44:45], v[86:87], v[34:35], v[16:17] op_sel_hi:[1,0,1]
	v_pk_fma_f32 v[8:9], v[90:91], v[2:3], v[40:41] op_sel_hi:[1,0,1]
	v_pk_fma_f32 v[6:7], v[88:89], v[2:3], v[42:43] op_sel_hi:[1,0,1]
	v_mov_b32_e32 v2, v35
	v_pk_fma_f32 v[16:17], v[90:91], v[4:5], v[36:37] op_sel_hi:[1,0,1]
	v_pk_fma_f32 v[4:5], v[90:91], v[2:3], v[44:45] op_sel_hi:[1,0,1]
	v_pk_fma_f32 v[2:3], v[88:89], v[2:3], v[46:47] op_sel_hi:[1,0,1]
	s_cbranch_scc0 .LBB0_401
	s_lshl_b32 s27, s27, 4
	s_add_i32 s27, s27, 16
	s_and_b32 s27, s27, 16
	s_add_i32 s27, s28, s27
	s_mul_hi_i32 s30, s27, 0x3c000
	s_mul_i32 s27, s27, 0x3c000
	s_add_u32 s28, s5, s27
	s_addc_u32 s29, s6, s30
	s_add_u32 s28, s28, s2
	s_addc_u32 s29, s29, s3
	global_store_dwordx4 v22, v[18:21], s[28:29]
	s_add_u32 s28, s7, s27
	s_addc_u32 s29, s8, s30
	s_add_u32 s28, s28, s2
	s_addc_u32 s29, s29, s3
	global_store_dwordx4 v22, v[14:17], s[28:29]
	s_add_u32 s28, s9, s27
	s_addc_u32 s29, s10, s30
	s_add_u32 s28, s28, s2
	s_addc_u32 s29, s29, s3
	global_store_dwordx4 v22, v[10:13], s[28:29]
	s_add_u32 s28, s11, s27
	s_addc_u32 s29, s14, s30
	s_add_u32 s28, s28, s2
	s_addc_u32 s29, s29, s3
	s_add_u32 s27, s15, s27
	global_store_dwordx4 v22, v[6:9], s[28:29]
	s_addc_u32 s28, s16, s30
	s_add_u32 s2, s27, s2
	s_addc_u32 s3, s28, s3
	global_store_dwordx4 v22, v[2:5], s[2:3]
	s_waitcnt lgkmcnt(0)
	s_add_i32 s12, s12, s13
	s_cmpk_gt_i32 s12, 0x2ff
	s_cbranch_scc0 .LBB0_400

.LBB0_747:
	s_mul_hi_i32 s0, s16, 0x2aaaaaab
	s_lshr_b32 s1, s0, 31
	s_ashr_i32 s0, s0, 4
	s_add_i32 s0, s0, s1
	s_mul_i32 s1, s0, 0xffffffa0
	s_lshl_b32 s4, s0, 6
	s_mulk_i32 s0, 0xe800
	s_add_i32 s5, s16, s1
	s_add_i32 s0, s18, s0
	v_readlane_b32 s68, v250, 2
	s_cmpk_gt_i32 s5, 0x5f
	v_readlane_b32 s76, v250, 10
	v_readlane_b32 s77, v250, 11
	s_cselect_b64 s[6:7], -1, 0
	s_mov_b64 s[8:9], s[76:77]
	s_and_b64 vcc, exec, s[6:7]
	v_readlane_b32 s69, v250, 3
	v_readlane_b32 s70, v250, 4
	v_readlane_b32 s71, v250, 5
	v_readlane_b32 s72, v250, 6
	v_readlane_b32 s73, v250, 7
	v_readlane_b32 s74, v250, 8
	v_readlane_b32 s75, v250, 9
	v_readlane_b32 s78, v250, 12
	v_readlane_b32 s79, v250, 13
	v_readlane_b32 s80, v250, 14
	v_readlane_b32 s81, v250, 15
	v_readlane_b32 s82, v250, 16
	v_readlane_b32 s83, v250, 17
	s_cbranch_vccnz .LBB0_749
	v_or_b32_e32 v4, s4, v14
	v_mov_b64_e32 v[2:3], s[8:9]
	v_mad_i64_i32 v[2:3], s[8:9], v4, s20, v[2:3]
	s_ashr_i32 s1, s0, 31
	v_lshl_add_u64 v[2:3], s[0:1], 2, v[2:3]
	v_mov_b32_e32 v9, v7
	v_lshl_add_u64 v[118:119], v[2:3], 0, v[8:9]
	v_add_co_u32_e32 v10, vcc, 0x18000, v118
	s_nop 1
	v_addc_co_u32_e32 v11, vcc, 0, v119, vcc
	v_add_co_u32_e32 v66, vcc, 0x30000, v118
	global_load_dwordx4 v[2:5], v[118:119], off nt
	s_nop 0
	global_load_dwordx4 v[10:13], v[10:11], off nt
	v_addc_co_u32_e32 v67, vcc, 0, v119, vcc
	v_add_co_u32_e32 v70, vcc, 0x48000, v118
	s_nop 1
	v_addc_co_u32_e32 v71, vcc, 0, v119, vcc
	v_add_co_u32_e32 v74, vcc, 0x60000, v118
	global_load_dwordx4 v[66:69], v[66:67], off nt
	s_nop 0
	global_load_dwordx4 v[70:73], v[70:71], off nt
	v_addc_co_u32_e32 v75, vcc, 0, v119, vcc
	v_add_co_u32_e32 v78, vcc, 0x78000, v118
	s_nop 1
	v_addc_co_u32_e32 v79, vcc, 0, v119, vcc
	v_add_co_u32_e32 v82, vcc, 0x90000, v118
	global_load_dwordx4 v[74:77], v[74:75], off nt
	s_nop 0
	global_load_dwordx4 v[78:81], v[78:79], off nt
	v_addc_co_u32_e32 v83, vcc, 0, v119, vcc
	v_add_co_u32_e32 v86, vcc, 0xa8000, v118
	s_nop 1
	v_addc_co_u32_e32 v87, vcc, 0, v119, vcc
	v_add_co_u32_e32 v90, vcc, 0xc0000, v118
	global_load_dwordx4 v[82:85], v[82:83], off nt
	s_nop 0
	global_load_dwordx4 v[86:89], v[86:87], off nt
	v_addc_co_u32_e32 v91, vcc, 0, v119, vcc
	v_add_co_u32_e32 v94, vcc, 0xd8000, v118
	s_nop 1
	v_addc_co_u32_e32 v95, vcc, 0, v119, vcc
	v_add_co_u32_e32 v98, vcc, 0xf0000, v118
	global_load_dwordx4 v[90:93], v[90:91], off nt
	s_nop 0
	global_load_dwordx4 v[94:97], v[94:95], off nt
	v_addc_co_u32_e32 v99, vcc, 0, v119, vcc
	v_add_co_u32_e32 v102, vcc, 0x108000, v118
	s_nop 1
	v_addc_co_u32_e32 v103, vcc, 0, v119, vcc
	v_add_co_u32_e32 v106, vcc, 0x120000, v118
	global_load_dwordx4 v[98:101], v[98:99], off nt
	s_nop 0
	global_load_dwordx4 v[102:105], v[102:103], off nt
	v_addc_co_u32_e32 v107, vcc, 0, v119, vcc
	v_add_co_u32_e32 v110, vcc, 0x138000, v118
	s_nop 1
	v_addc_co_u32_e32 v111, vcc, 0, v119, vcc
	global_load_dwordx4 v[106:109], v[106:107], off nt
	s_nop 0
	global_load_dwordx4 v[110:113], v[110:111], off nt
	v_add_co_u32_e32 v114, vcc, 0x150000, v118
	s_nop 1
	v_addc_co_u32_e32 v115, vcc, 0, v119, vcc
	global_load_dwordx4 v[114:117], v[114:115], off nt
	v_add_co_u32_e32 v118, vcc, 0x168000, v118
	s_nop 1
	v_addc_co_u32_e32 v119, vcc, 0, v119, vcc
	global_load_dwordx4 v[118:121], v[118:119], off nt
	s_waitcnt vmcnt(0)
	ds_write2_b32 v31, v2, v3 offset1:1
	ds_write2_b32 v31, v4, v5 offset0:2 offset1:3
	ds_write2_b32 v32, v10, v11 offset1:1
	ds_write2_b32 v33, v12, v13 offset1:1
	ds_write2_b32 v34, v66, v67 offset1:1
	ds_write2_b32 v35, v68, v69 offset1:1
	ds_write2_b32 v36, v70, v71 offset1:1
	ds_write2_b32 v37, v72, v73 offset1:1
	ds_write2_b32 v38, v74, v75 offset1:1
	ds_write2_b32 v39, v76, v77 offset1:1
	ds_write2_b32 v40, v78, v79 offset1:1
	ds_write2_b32 v41, v80, v81 offset1:1
	ds_write2_b32 v42, v82, v83 offset1:1
	ds_write2_b32 v43, v84, v85 offset1:1
	ds_write2_b32 v44, v86, v87 offset1:1
	ds_write2_b32 v45, v88, v89 offset1:1
	ds_write2_b32 v46, v90, v91 offset1:1
	ds_write2_b32 v47, v92, v93 offset1:1
	ds_write2_b32 v48, v94, v95 offset1:1
	ds_write2_b32 v49, v96, v97 offset1:1
	ds_write2_b32 v50, v98, v99 offset1:1
	ds_write2_b32 v51, v100, v101 offset1:1
	ds_write2_b32 v52, v102, v103 offset1:1
	ds_write2_b32 v53, v104, v105 offset1:1
	ds_write2_b32 v54, v106, v107 offset1:1
	ds_write2_b32 v55, v108, v109 offset1:1
	ds_write2_b32 v56, v110, v111 offset1:1
	ds_write2_b32 v57, v112, v113 offset1:1
	ds_write2_b32 v58, v114, v115 offset1:1
	ds_write2_b32 v59, v116, v117 offset1:1
	ds_write2_b32 v60, v118, v119 offset1:1
	ds_write2_b32 v61, v120, v121 offset1:1

.LBB0_767:
	v_mul_hi_i32 v2, v1, s7
	v_add_u32_e32 v2, v2, v1
	v_lshrrev_b32_e32 v6, 31, v2
	v_ashrrev_i32_e32 v2, 13, v2
	v_add_u32_e32 v2, v2, v6
	v_mad_i32_i24 v18, v2, s8, v1
	v_add_u32_e32 v11, 1, v2
	v_mul_hi_i32 v2, v18, s9
	v_mul_hi_i32_i24_e32 v7, 0xc000, v11
	v_mul_i32_i24_e32 v6, 0xc000, v11
	v_lshrrev_b32_e32 v14, 31, v2
	v_ashrrev_i32_e32 v2, 9, v2
	v_lshl_add_u64 v[16:17], s[46:47], 0, v[6:7]
	v_add_u32_e32 v6, v2, v14
	v_lshlrev_b32_e32 v12, 4, v11
	v_mul_i32_i24_e32 v19, 0xfffff400, v6
	v_and_b32_e32 v76, 16, v12
	v_add_lshl_u32 v18, v18, v19, 2
	v_mul_u32_u24_e32 v2, 5, v76
	v_ashrrev_i32_e32 v19, 31, v18
	v_mov_b32_e32 v13, v3
	v_ashrrev_i32_e32 v7, 31, v6
	v_or_b32_e32 v12, 5, v2
	v_lshlrev_b64 v[80:81], 2, v[18:19]
	v_mov_b32_e32 v15, v3
	v_or_b32_e32 v14, 10, v2
	v_lshl_add_u64 v[20:21], v[2:3], 0, v[6:7]
	v_lshl_add_u64 v[22:23], v[12:13], 0, v[6:7]
	v_or_b32_e32 v2, 15, v2
	v_lshl_add_u64 v[12:13], v[16:17], 0, v[80:81]
	v_lshl_add_u64 v[24:25], v[14:15], 0, v[6:7]
	v_lshl_add_u64 v[26:27], v[2:3], 0, v[6:7]
	v_mad_u32_u24 v2, v76, 5, 20
	global_load_dwordx4 v[12:15], v[12:13], off nt
	v_lshl_add_u64 v[18:19], v[2:3], 0, v[6:7]
	v_mad_u32_u24 v2, v76, 5, 25
	v_lshl_add_u64 v[72:73], s[2:3], 0, v[80:81]
	v_lshl_add_u64 v[16:17], v[2:3], 0, v[6:7]
	v_mad_u32_u24 v2, v76, 5, 30
	v_mad_u64_u32 v[28:29], s[12:13], v20, s10, v[72:73]
	v_mad_u64_u32 v[30:31], s[12:13], v22, s10, v[72:73]
	v_mad_u64_u32 v[32:33], s[12:13], v24, s10, v[72:73]
	v_mad_u64_u32 v[34:35], s[12:13], v26, s10, v[72:73]
	v_mad_u64_u32 v[36:37], s[12:13], v18, s10, v[72:73]
	v_mad_u64_u32 v[38:39], s[12:13], v16, s10, v[72:73]
	v_lshl_add_u64 v[40:41], v[2:3], 0, v[6:7]
	v_mad_u32_u24 v2, v76, 5, 35
	v_mad_i32_i24 v29, v21, s10, v29
	v_mad_i32_i24 v31, v23, s10, v31
	v_mad_i32_i24 v33, v25, s10, v33
	v_mad_i32_i24 v35, v27, s10, v35
	v_mad_i32_i24 v37, v19, s10, v37
	v_mad_i32_i24 v39, v17, s10, v39
	v_lshl_add_u64 v[44:45], v[2:3], 0, v[6:7]
	v_mad_u32_u24 v2, v76, 5, 40
	v_mad_u64_u32 v[42:43], s[12:13], v40, s10, v[72:73]
	global_load_dwordx4 v[16:19], v[28:29], off nt
	global_load_dwordx4 v[20:23], v[30:31], off nt
	global_load_dwordx4 v[24:27], v[32:33], off nt
	s_nop 0
	global_load_dwordx4 v[28:31], v[34:35], off nt
	s_nop 0
	global_load_dwordx4 v[32:35], v[36:37], off nt
	s_nop 0
	global_load_dwordx4 v[36:39], v[38:39], off nt
	v_mad_u64_u32 v[46:47], s[12:13], v44, s10, v[72:73]
	v_lshl_add_u64 v[48:49], v[2:3], 0, v[6:7]
	v_mad_u32_u24 v2, v76, 5, 45
	v_mad_i32_i24 v43, v41, s10, v43
	v_mad_i32_i24 v47, v45, s10, v47
	v_lshl_add_u64 v[52:53], v[2:3], 0, v[6:7]
	v_mad_u32_u24 v2, v76, 5, 50
	v_mad_u64_u32 v[50:51], s[12:13], v48, s10, v[72:73]
	global_load_dwordx4 v[40:43], v[42:43], off nt
	s_nop 0
	global_load_dwordx4 v[44:47], v[46:47], off nt
	v_mad_u64_u32 v[54:55], s[12:13], v52, s10, v[72:73]
	v_lshl_add_u64 v[56:57], v[2:3], 0, v[6:7]
	v_mad_u32_u24 v2, v76, 5, 55
	v_mad_i32_i24 v51, v49, s10, v51
	v_mad_i32_i24 v55, v53, s10, v55
	v_lshl_add_u64 v[60:61], v[2:3], 0, v[6:7]
	v_mad_u32_u24 v2, v76, 5, 60
	v_mad_u64_u32 v[58:59], s[12:13], v56, s10, v[72:73]
	global_load_dwordx4 v[48:51], v[50:51], off nt
	s_nop 0
	global_load_dwordx4 v[52:55], v[54:55], off nt
	v_mad_u64_u32 v[62:63], s[12:13], v60, s10, v[72:73]
	v_lshl_add_u64 v[64:65], v[2:3], 0, v[6:7]
	v_mad_u32_u24 v2, v76, 5, v8
	v_mad_i32_i24 v59, v57, s10, v59
	v_mad_i32_i24 v63, v61, s10, v63
	v_lshl_add_u64 v[68:69], v[2:3], 0, v[6:7]
	v_mad_u32_u24 v2, v76, 5, v9
	v_mad_u64_u32 v[66:67], s[12:13], v64, s10, v[72:73]
	global_load_dwordx4 v[56:59], v[58:59], off nt
	s_nop 0
	global_load_dwordx4 v[60:63], v[62:63], off nt
	v_mad_u64_u32 v[70:71], s[12:13], v68, s10, v[72:73]
	v_lshl_add_u64 v[74:75], v[2:3], 0, v[6:7]
	v_mad_u32_u24 v2, v76, 5, v10
	v_mad_i32_i24 v67, v65, s10, v67
	v_mad_i32_i24 v71, v69, s10, v71
	v_mad_u64_u32 v[76:77], s[12:13], v74, s10, v[72:73]
	v_lshl_add_u64 v[78:79], v[2:3], 0, v[6:7]
	global_load_dwordx4 v[64:67], v[66:67], off nt
	s_nop 0
	global_load_dwordx4 v[68:71], v[70:71], off nt
	v_mad_i32_i24 v77, v75, s10, v77
	v_mad_u64_u32 v[82:83], s[12:13], v78, s10, v[72:73]
	global_load_dwordx4 v[72:75], v[76:77], off nt
	v_mad_i32_i24 v83, v79, s10, v83
	global_load_dwordx4 v[76:79], v[82:83], off nt
	v_mul_hi_i32_i24_e32 v83, 5, v11
	v_mul_i32_i24_e32 v82, 5, v11
	v_lshl_add_u64 v[6:7], v[82:83], 0, v[6:7]
	v_mad_u64_u32 v[82:83], s[12:13], v6, s10, v[4:5]
	v_mov_b32_e32 v2, v83
	v_add_u32_e32 v1, s6, v1
	v_mad_u64_u32 v[6:7], s[12:13], v7, s10, v[2:3]
	v_cmp_lt_i32_e32 vcc, s11, v1
	v_mov_b32_e32 v83, v6
	s_or_b64 s[4:5], vcc, s[4:5]
	v_lshl_add_u64 v[6:7], v[82:83], 0, v[80:81]
	s_waitcnt vmcnt(0)
	v_pk_add_f32 v[14:15], v[14:15], v[18:19]
	v_pk_add_f32 v[12:13], v[12:13], v[16:17]
	v_pk_add_f32 v[14:15], v[14:15], v[22:23]
	v_pk_add_f32 v[12:13], v[12:13], v[20:21]
	v_pk_add_f32 v[14:15], v[14:15], v[26:27]
	v_pk_add_f32 v[12:13], v[12:13], v[24:25]
	v_pk_add_f32 v[14:15], v[14:15], v[30:31]
	v_pk_add_f32 v[12:13], v[12:13], v[28:29]
	v_pk_add_f32 v[14:15], v[14:15], v[34:35]
	v_pk_add_f32 v[12:13], v[12:13], v[32:33]
	v_pk_add_f32 v[14:15], v[14:15], v[38:39]
	v_pk_add_f32 v[12:13], v[12:13], v[36:37]
	v_pk_add_f32 v[14:15], v[14:15], v[42:43]
	v_pk_add_f32 v[12:13], v[12:13], v[40:41]
	v_pk_add_f32 v[14:15], v[14:15], v[46:47]
	v_pk_add_f32 v[12:13], v[12:13], v[44:45]
	v_pk_add_f32 v[14:15], v[14:15], v[50:51]
	v_pk_add_f32 v[12:13], v[12:13], v[48:49]
	v_pk_add_f32 v[14:15], v[14:15], v[54:55]
	v_pk_add_f32 v[12:13], v[12:13], v[52:53]
	v_pk_add_f32 v[14:15], v[14:15], v[58:59]
	v_pk_add_f32 v[12:13], v[12:13], v[56:57]
	v_pk_add_f32 v[14:15], v[14:15], v[62:63]
	v_pk_add_f32 v[12:13], v[12:13], v[60:61]
	v_pk_add_f32 v[14:15], v[14:15], v[66:67]
	v_pk_add_f32 v[12:13], v[12:13], v[64:65]
	v_pk_add_f32 v[14:15], v[14:15], v[70:71]
	v_pk_add_f32 v[12:13], v[12:13], v[68:69]
	v_pk_add_f32 v[14:15], v[14:15], v[74:75]
	v_pk_add_f32 v[12:13], v[12:13], v[72:73]
	v_pk_add_f32 v[14:15], v[14:15], v[78:79]
	v_pk_add_f32 v[12:13], v[12:13], v[76:77]
	global_store_dwordx4 v[6:7], v[12:15], off
	s_andn2_b64 exec, exec, s[4:5]
	s_cbranch_execnz .LBB0_767

.LBB0_874:
	s_add_i32 s7, s20, 0xfffffc00
	s_and_b64 s[10:11], s[10:11], exec
	s_cselect_b32 s7, s20, s7
	s_ashr_i32 s10, s7, 31
	s_lshr_b32 s10, s10, 27
	s_add_i32 s10, s7, s10
	s_ashr_i32 s11, s10, 5
	s_lshl_b32 s10, s11, 6
	s_lshl_b32 s11, s11, 11
	s_lshl_b32 s7, s7, 6
	s_sub_i32 s12, s7, s11
	s_cmpk_gt_i32 s12, 0x7ff
	s_cselect_b64 s[14:15], -1, 0
	s_and_b64 vcc, exec, s[14:15]
	s_cbranch_vccnz .LBB0_876
	v_or_b32_e32 v2, s10, v9
	v_ashrrev_i32_e32 v3, 31, v2
	v_lshlrev_b64 v[2:3], 13, v[2:3]
	v_lshl_add_u64 v[2:3], s[0:1], 0, v[2:3]
	s_ashr_i32 s13, s12, 31
	v_lshl_add_u64 v[2:3], s[12:13], 2, v[2:3]
	v_mov_b32_e32 v11, v7
	v_lshl_add_u64 v[120:121], v[2:3], 0, v[10:11]
	v_add_co_u32_e32 v60, vcc, 0x8000, v120
	s_nop 1
	v_addc_co_u32_e32 v61, vcc, 0, v121, vcc
	v_add_co_u32_e32 v64, vcc, 0x10000, v120
	global_load_dwordx4 v[2:5], v[120:121], off nt
	s_nop 0
	global_load_dwordx4 v[60:63], v[60:61], off nt
	v_addc_co_u32_e32 v65, vcc, 0, v121, vcc
	v_add_co_u32_e32 v72, vcc, 0x18000, v120
	s_nop 1
	v_addc_co_u32_e32 v73, vcc, 0, v121, vcc
	v_add_co_u32_e32 v76, vcc, 0x20000, v120
	global_load_dwordx4 v[64:67], v[64:65], off nt
	s_nop 0
	global_load_dwordx4 v[72:75], v[72:73], off nt
	v_addc_co_u32_e32 v77, vcc, 0, v121, vcc
	v_add_co_u32_e32 v80, vcc, 0x28000, v120
	s_nop 1
	v_addc_co_u32_e32 v81, vcc, 0, v121, vcc
	v_add_co_u32_e32 v84, vcc, 0x30000, v120
	global_load_dwordx4 v[76:79], v[76:77], off nt
	s_nop 0
	global_load_dwordx4 v[80:83], v[80:81], off nt
	v_addc_co_u32_e32 v85, vcc, 0, v121, vcc
	v_add_co_u32_e32 v88, vcc, 0x38000, v120
	s_nop 1
	v_addc_co_u32_e32 v89, vcc, 0, v121, vcc
	v_add_co_u32_e32 v92, vcc, 0x40000, v120
	global_load_dwordx4 v[84:87], v[84:85], off nt
	s_nop 0
	global_load_dwordx4 v[88:91], v[88:89], off nt
	v_addc_co_u32_e32 v93, vcc, 0, v121, vcc
	v_add_co_u32_e32 v96, vcc, 0x48000, v120
	s_nop 1
	v_addc_co_u32_e32 v97, vcc, 0, v121, vcc
	v_add_co_u32_e32 v100, vcc, 0x50000, v120
	global_load_dwordx4 v[92:95], v[92:93], off nt
	s_nop 0
	global_load_dwordx4 v[96:99], v[96:97], off nt
	v_addc_co_u32_e32 v101, vcc, 0, v121, vcc
	v_add_co_u32_e32 v104, vcc, 0x58000, v120
	s_nop 1
	v_addc_co_u32_e32 v105, vcc, 0, v121, vcc
	v_add_co_u32_e32 v108, vcc, 0x60000, v120
	global_load_dwordx4 v[100:103], v[100:101], off nt
	s_nop 0
	global_load_dwordx4 v[104:107], v[104:105], off nt
	v_addc_co_u32_e32 v109, vcc, 0, v121, vcc
	v_add_co_u32_e32 v112, vcc, 0x68000, v120
	s_nop 1
	v_addc_co_u32_e32 v113, vcc, 0, v121, vcc
	global_load_dwordx4 v[108:111], v[108:109], off nt
	s_nop 0
	global_load_dwordx4 v[112:115], v[112:113], off nt
	v_add_co_u32_e32 v116, vcc, 0x70000, v120
	s_nop 1
	v_addc_co_u32_e32 v117, vcc, 0, v121, vcc
	global_load_dwordx4 v[116:119], v[116:117], off nt
	v_add_co_u32_e32 v120, vcc, 0x78000, v120
	s_nop 1
	v_addc_co_u32_e32 v121, vcc, 0, v121, vcc
	global_load_dwordx4 v[120:123], v[120:121], off nt
	s_waitcnt vmcnt(0)
	ds_write2_b32 v28, v2, v3 offset1:1
	ds_write2_b32 v28, v4, v5 offset0:2 offset1:3
	ds_write2_b32 v29, v60, v61 offset1:1
	ds_write2_b32 v30, v62, v63 offset1:1
	ds_write2_b32 v31, v64, v65 offset1:1
	ds_write2_b32 v32, v66, v67 offset1:1
	ds_write2_b32 v33, v72, v73 offset1:1
	ds_write2_b32 v34, v74, v75 offset1:1
	ds_write2_b32 v35, v76, v77 offset1:1
	ds_write2_b32 v36, v78, v79 offset1:1
	ds_write2_b32 v37, v80, v81 offset1:1
	ds_write2_b32 v38, v82, v83 offset1:1
	ds_write2_b32 v39, v84, v85 offset1:1
	ds_write2_b32 v40, v86, v87 offset1:1
	ds_write2_b32 v41, v88, v89 offset1:1
	ds_write2_b32 v42, v90, v91 offset1:1
	ds_write2_b32 v43, v92, v93 offset1:1
	ds_write2_b32 v44, v94, v95 offset1:1
	ds_write2_b32 v45, v96, v97 offset1:1
	ds_write2_b32 v46, v98, v99 offset1:1
	ds_write2_b32 v47, v100, v101 offset1:1
	ds_write2_b32 v48, v102, v103 offset1:1
	ds_write2_b32 v49, v104, v105 offset1:1
	ds_write2_b32 v50, v106, v107 offset1:1
	ds_write2_b32 v51, v108, v109 offset1:1
	ds_write2_b32 v52, v110, v111 offset1:1
	ds_write2_b32 v53, v112, v113 offset1:1
	ds_write2_b32 v54, v114, v115 offset1:1
	ds_write2_b32 v55, v116, v117 offset1:1
	ds_write2_b32 v56, v118, v119 offset1:1
	ds_write2_b32 v57, v120, v121 offset1:1
	ds_write2_b32 v58, v122, v123 offset1:1

.LBB0_1241:
	s_lshl_b32 s34, s34, 6
	s_cmp_ge_i32 s0, s2
	s_cselect_b64 s[36:37], -1, 0
	s_and_b64 vcc, exec, s[36:37]
	s_cbranch_vccnz .LBB0_1243
	v_or_b32_e32 v2, s34, v9
	s_ashr_i32 s1, s34, 31
	s_mul_i32 s1, s1, s2
	v_mad_u64_u32 v[2:3], s[70:71], v2, s2, 0
	v_add_u32_e32 v3, s1, v3
	v_lshl_add_u64 v[2:3], v[2:3], 2, s[54:55]
	s_ashr_i32 s1, s0, 31
	v_lshl_add_u64 v[2:3], s[0:1], 2, v[2:3]
	v_mov_b32_e32 v11, v7
	v_lshl_add_u64 v[62:63], v[2:3], 0, v[10:11]
	s_lshl_b64 s[0:1], s[2:3], 4
	v_lshl_add_u64 v[66:67], v[62:63], 0, s[0:1]
	v_lshl_add_u64 v[70:71], v[66:67], 0, s[0:1]
	global_load_dwordx4 v[2:5], v[62:63], off nt
	s_nop 0
	global_load_dwordx4 v[62:65], v[66:67], off nt
	s_nop 0
	global_load_dwordx4 v[66:69], v[70:71], off nt
	v_lshl_add_u64 v[70:71], v[70:71], 0, s[0:1]
	global_load_dwordx4 v[76:79], v[70:71], off nt
	v_lshl_add_u64 v[70:71], v[70:71], 0, s[0:1]
	global_load_dwordx4 v[80:83], v[70:71], off nt
	v_lshl_add_u64 v[70:71], v[70:71], 0, s[0:1]
	global_load_dwordx4 v[84:87], v[70:71], off nt
	v_lshl_add_u64 v[70:71], v[70:71], 0, s[0:1]
	global_load_dwordx4 v[88:91], v[70:71], off nt
	v_lshl_add_u64 v[70:71], v[70:71], 0, s[0:1]
	global_load_dwordx4 v[92:95], v[70:71], off nt
	v_lshl_add_u64 v[70:71], v[70:71], 0, s[0:1]
	global_load_dwordx4 v[96:99], v[70:71], off nt
	v_lshl_add_u64 v[70:71], v[70:71], 0, s[0:1]
	global_load_dwordx4 v[100:103], v[70:71], off nt
	v_lshl_add_u64 v[70:71], v[70:71], 0, s[0:1]
	global_load_dwordx4 v[104:107], v[70:71], off nt
	v_lshl_add_u64 v[70:71], v[70:71], 0, s[0:1]
	global_load_dwordx4 v[108:111], v[70:71], off nt
	v_lshl_add_u64 v[70:71], v[70:71], 0, s[0:1]
	global_load_dwordx4 v[112:115], v[70:71], off nt
	v_lshl_add_u64 v[70:71], v[70:71], 0, s[0:1]
	global_load_dwordx4 v[116:119], v[70:71], off nt
	v_lshl_add_u64 v[70:71], v[70:71], 0, s[0:1]
	global_load_dwordx4 v[120:123], v[70:71], off nt
	v_lshl_add_u64 v[70:71], v[70:71], 0, s[0:1]
	global_load_dwordx4 v[124:127], v[70:71], off nt
	s_waitcnt vmcnt(0)
	ds_write2_b32 v35, v2, v3 offset1:1
	ds_write2_b32 v35, v4, v5 offset0:2 offset1:3
	ds_write2_b32 v36, v62, v63 offset1:1
	ds_write2_b32 v37, v64, v65 offset1:1
	ds_write2_b32 v38, v66, v67 offset1:1
	ds_write2_b32 v39, v68, v69 offset1:1
	ds_write2_b32 v40, v76, v77 offset1:1
	ds_write2_b32 v41, v78, v79 offset1:1
	ds_write2_b32 v42, v80, v81 offset1:1
	ds_write2_b32 v43, v82, v83 offset1:1
	ds_write2_b32 v44, v84, v85 offset1:1
	ds_write2_b32 v45, v86, v87 offset1:1
	ds_write2_b32 v46, v88, v89 offset1:1
	ds_write2_b32 v47, v90, v91 offset1:1
	ds_write2_b32 v48, v92, v93 offset1:1
	ds_write2_b32 v49, v94, v95 offset1:1
	ds_write2_b32 v50, v96, v97 offset1:1
	ds_write2_b32 v51, v98, v99 offset1:1
	ds_write2_b32 v52, v100, v101 offset1:1
	ds_write2_b32 v53, v102, v103 offset1:1
	ds_write2_b32 v54, v104, v105 offset1:1
	ds_write2_b32 v55, v106, v107 offset1:1
	ds_write2_b32 v56, v108, v109 offset1:1
	ds_write2_b32 v57, v110, v111 offset1:1
	ds_write2_b32 v58, v112, v113 offset1:1
	ds_write2_b32 v59, v114, v115 offset1:1
	ds_write2_b32 v60, v116, v117 offset1:1
	ds_write2_b32 v61, v118, v119 offset1:1
	v_add_u32_e32 v2, 0x38e0, v35
	ds_write2_b32 v2, v120, v121 offset1:1
	v_add_u32_e32 v2, 0x38e8, v35
	ds_write2_b32 v2, v122, v123 offset1:1
	v_add_u32_e32 v2, 0x3cf0, v35
	ds_write2_b32 v2, v124, v125 offset1:1
	v_add_u32_e32 v2, 0x3cf8, v35
	ds_write2_b32 v2, v126, v127 offset1:1

.LBB0_1648:
	v_add_co_u32_e32 v28, vcc, s18, v26
	v_mov_b32_e32 v124, s54
	s_nop 0
	v_addc_co_u32_e32 v29, vcc, -1, v27, vcc
	global_load_dwordx4 v[28:31], v[28:29], off nt
	v_add_co_u32_e32 v32, vcc, s19, v26
	s_add_i32 s53, s53, 16
	s_nop 0
	v_addc_co_u32_e32 v33, vcc, -1, v27, vcc
	v_add_co_u32_e32 v36, vcc, s20, v26
	global_load_dwordx4 v[32:35], v[32:33], off nt
	s_nop 0
	v_addc_co_u32_e32 v37, vcc, -1, v27, vcc
	v_add_co_u32_e32 v40, vcc, s21, v26
	global_load_dwordx4 v[36:39], v[36:37], off nt
	s_nop 0
	v_addc_co_u32_e32 v41, vcc, -1, v27, vcc
	global_load_dwordx4 v[40:43], v[40:41], off nt
	v_add_co_u32_e32 v44, vcc, s22, v26
	s_add_i32 s54, s54, 64
	s_nop 0
	v_addc_co_u32_e32 v45, vcc, -1, v27, vcc
	global_load_dwordx4 v[44:47], v[44:45], off nt
	v_add_co_u32_e32 v48, vcc, s23, v26
	s_cmpk_gt_u32 s53, 0x6f
	s_nop 0
	v_addc_co_u32_e32 v49, vcc, -1, v27, vcc
	v_add_co_u32_e32 v52, vcc, s26, v26
	global_load_dwordx4 v[48:51], v[48:49], off nt
	s_nop 0
	v_addc_co_u32_e32 v53, vcc, -1, v27, vcc
	v_add_co_u32_e32 v56, vcc, s27, v26
	global_load_dwordx4 v[52:55], v[52:53], off nt
	s_nop 0
	v_addc_co_u32_e32 v57, vcc, -1, v27, vcc
	global_load_dwordx4 v[56:59], v[56:57], off nt
	v_add_co_u32_e32 v60, vcc, s28, v26
	s_nop 1
	v_addc_co_u32_e32 v61, vcc, -1, v27, vcc
	v_add_co_u32_e32 v64, vcc, s29, v26
	global_load_dwordx4 v[60:63], v[60:61], off nt
	s_nop 0
	v_addc_co_u32_e32 v65, vcc, -1, v27, vcc
	v_add_co_u32_e32 v68, vcc, s30, v26
	global_load_dwordx4 v[64:67], v[64:65], off nt
	s_nop 0
	v_addc_co_u32_e32 v69, vcc, -1, v27, vcc
	v_add_co_u32_e32 v72, vcc, s31, v26
	global_load_dwordx4 v[68:71], v[68:69], off nt
	s_nop 0
	v_addc_co_u32_e32 v73, vcc, -1, v27, vcc
	global_load_dwordx4 v[72:75], v[72:73], off nt
	v_add_co_u32_e32 v76, vcc, s34, v26
	s_nop 1
	v_addc_co_u32_e32 v77, vcc, -1, v27, vcc
	global_load_dwordx4 v[76:79], v[76:77], off nt
	v_add_co_u32_e32 v80, vcc, s35, v26
	s_nop 1
	v_addc_co_u32_e32 v81, vcc, -1, v27, vcc
	global_load_dwordx4 v[80:83], v[80:81], off nt
	v_add_co_u32_e32 v84, vcc, s36, v26
	s_nop 1
	v_addc_co_u32_e32 v85, vcc, -1, v27, vcc
	global_load_dwordx4 v[84:87], v[84:85], off nt
	s_nop 0
	global_load_dwordx4 v[88:91], v[26:27], off nt
	ds_read_b128 v[92:95], v124
	ds_read_b128 v[96:99], v124 offset:16
	ds_read_b128 v[100:103], v124 offset:32
	ds_read_b128 v[104:107], v124 offset:48
	v_lshl_add_u64 v[26:27], v[26:27], 0, s[0:1]
	s_waitcnt vmcnt(0) lgkmcnt(0)
	v_pk_fma_f32 v[108:109], v[30:31], v[92:93], v[20:21] op_sel_hi:[1,0,1]
	v_pk_fma_f32 v[110:111], v[28:29], v[92:93], v[18:19] op_sel_hi:[1,0,1]
	ds_read_b128 v[18:21], v124 offset:512
	s_waitcnt lgkmcnt(0)
	v_pk_fma_f32 v[112:113], v[30:31], v[18:19], v[16:17] op_sel_hi:[1,0,1]
	v_pk_fma_f32 v[114:115], v[28:29], v[18:19], v[14:15] op_sel_hi:[1,0,1]
	ds_read_b128 v[14:17], v124 offset:1024
	s_waitcnt lgkmcnt(0)
	v_pk_fma_f32 v[116:117], v[30:31], v[14:15], v[12:13] op_sel_hi:[1,0,1]
	v_pk_fma_f32 v[118:119], v[28:29], v[14:15], v[10:11] op_sel_hi:[1,0,1]
	ds_read_b128 v[10:13], v124 offset:1536
	s_waitcnt lgkmcnt(0)
	v_pk_fma_f32 v[120:121], v[30:31], v[10:11], v[8:9] op_sel_hi:[1,0,1]
	v_pk_fma_f32 v[122:123], v[28:29], v[10:11], v[6:7] op_sel_hi:[1,0,1]
	ds_read_b128 v[6:9], v124 offset:2048
	s_waitcnt lgkmcnt(0)
	v_pk_fma_f32 v[4:5], v[30:31], v[6:7], v[4:5] op_sel_hi:[1,0,1]
	v_pk_fma_f32 v[2:3], v[28:29], v[6:7], v[2:3] op_sel_hi:[1,0,1]
	v_pk_fma_f32 v[28:29], v[34:35], v[92:93], v[108:109] op_sel:[0,1,0]
	v_pk_fma_f32 v[30:31], v[32:33], v[92:93], v[110:111] op_sel:[0,1,0]
	v_pk_fma_f32 v[4:5], v[34:35], v[6:7], v[4:5] op_sel:[0,1,0]
	v_pk_fma_f32 v[2:3], v[32:33], v[6:7], v[2:3] op_sel:[0,1,0]
	v_pk_fma_f32 v[92:93], v[34:35], v[18:19], v[112:113] op_sel:[0,1,0]
	v_pk_fma_f32 v[18:19], v[32:33], v[18:19], v[114:115] op_sel:[0,1,0]
	v_pk_fma_f32 v[6:7], v[38:39], v[94:95], v[28:29] op_sel_hi:[1,0,1]
	v_pk_fma_f32 v[28:29], v[36:37], v[94:95], v[30:31] op_sel_hi:[1,0,1]
	v_pk_fma_f32 v[4:5], v[38:39], v[8:9], v[4:5] op_sel_hi:[1,0,1]
	v_pk_fma_f32 v[2:3], v[36:37], v[8:9], v[2:3] op_sel_hi:[1,0,1]
	v_mov_b32_e32 v8, v95
	v_pk_fma_f32 v[108:109], v[34:35], v[14:15], v[116:117] op_sel:[0,1,0]
	v_pk_fma_f32 v[14:15], v[32:33], v[14:15], v[118:119] op_sel:[0,1,0]
	v_pk_fma_f32 v[30:31], v[38:39], v[20:21], v[92:93] op_sel_hi:[1,0,1]
	v_pk_fma_f32 v[18:19], v[36:37], v[20:21], v[18:19] op_sel_hi:[1,0,1]
	v_pk_fma_f32 v[6:7], v[42:43], v[8:9], v[6:7] op_sel_hi:[1,0,1]
	v_pk_fma_f32 v[28:29], v[40:41], v[8:9], v[28:29] op_sel_hi:[1,0,1]
	v_mov_b32_e32 v8, v21
	v_pk_fma_f32 v[110:111], v[34:35], v[10:11], v[120:121] op_sel:[0,1,0]
	v_pk_fma_f32 v[10:11], v[32:33], v[10:11], v[122:123] op_sel:[0,1,0]
	v_pk_fma_f32 v[32:33], v[38:39], v[16:17], v[108:109] op_sel_hi:[1,0,1]
	v_pk_fma_f32 v[14:15], v[36:37], v[16:17], v[14:15] op_sel_hi:[1,0,1]
	v_pk_fma_f32 v[20:21], v[42:43], v[8:9], v[30:31] op_sel_hi:[1,0,1]
	v_pk_fma_f32 v[18:19], v[40:41], v[8:9], v[18:19] op_sel_hi:[1,0,1]
	v_mov_b32_e32 v8, v17
	v_pk_fma_f32 v[34:35], v[38:39], v[12:13], v[110:111] op_sel_hi:[1,0,1]
	v_pk_fma_f32 v[10:11], v[36:37], v[12:13], v[10:11] op_sel_hi:[1,0,1]
	v_pk_fma_f32 v[16:17], v[42:43], v[8:9], v[32:33] op_sel_hi:[1,0,1]
	v_pk_fma_f32 v[14:15], v[40:41], v[8:9], v[14:15] op_sel_hi:[1,0,1]
	v_mov_b32_e32 v8, v13
	v_pk_fma_f32 v[30:31], v[42:43], v[8:9], v[34:35] op_sel_hi:[1,0,1]
	v_pk_fma_f32 v[32:33], v[40:41], v[8:9], v[10:11] op_sel_hi:[1,0,1]
	v_mov_b32_e32 v8, v9
	v_pk_fma_f32 v[34:35], v[42:43], v[8:9], v[4:5] op_sel_hi:[1,0,1]
	v_pk_fma_f32 v[36:37], v[40:41], v[8:9], v[2:3] op_sel_hi:[1,0,1]
	v_pk_fma_f32 v[38:39], v[46:47], v[96:97], v[6:7] op_sel_hi:[1,0,1]
	ds_read_b128 v[2:5], v124 offset:528
	ds_read_b128 v[6:9], v124 offset:1040
	ds_read_b128 v[10:13], v124 offset:1552
	v_pk_fma_f32 v[28:29], v[44:45], v[96:97], v[28:29] op_sel_hi:[1,0,1]
	v_pk_fma_f32 v[38:39], v[50:51], v[96:97], v[38:39] op_sel:[0,1,0]
	s_waitcnt lgkmcnt(2)
	v_pk_fma_f32 v[20:21], v[46:47], v[2:3], v[20:21] op_sel_hi:[1,0,1]
	s_waitcnt lgkmcnt(1)
	v_pk_fma_f32 v[40:41], v[46:47], v[6:7], v[16:17] op_sel_hi:[1,0,1]
	v_pk_fma_f32 v[42:43], v[44:45], v[6:7], v[14:15] op_sel_hi:[1,0,1]
	ds_read_b128 v[14:17], v124 offset:2064
	v_pk_fma_f32 v[18:19], v[44:45], v[2:3], v[18:19] op_sel_hi:[1,0,1]
	s_waitcnt lgkmcnt(1)
	v_pk_fma_f32 v[30:31], v[46:47], v[10:11], v[30:31] op_sel_hi:[1,0,1]
	v_pk_fma_f32 v[32:33], v[44:45], v[10:11], v[32:33] op_sel_hi:[1,0,1]
	v_pk_fma_f32 v[28:29], v[48:49], v[96:97], v[28:29] op_sel:[0,1,0]
	s_waitcnt lgkmcnt(0)
	v_pk_fma_f32 v[34:35], v[46:47], v[14:15], v[34:35] op_sel_hi:[1,0,1]
	v_pk_fma_f32 v[20:21], v[50:51], v[2:3], v[20:21] op_sel:[0,1,0]
	v_pk_fma_f32 v[2:3], v[48:49], v[2:3], v[18:19] op_sel:[0,1,0]
	v_pk_fma_f32 v[30:31], v[50:51], v[10:11], v[30:31] op_sel:[0,1,0]
	v_pk_fma_f32 v[10:11], v[48:49], v[10:11], v[32:33] op_sel:[0,1,0]
	v_pk_fma_f32 v[32:33], v[50:51], v[14:15], v[34:35] op_sel:[0,1,0]
	v_pk_fma_f32 v[34:35], v[54:55], v[98:99], v[38:39] op_sel_hi:[1,0,1]
	v_pk_fma_f32 v[28:29], v[52:53], v[98:99], v[28:29] op_sel_hi:[1,0,1]
	v_pk_fma_f32 v[20:21], v[54:55], v[4:5], v[20:21] op_sel_hi:[1,0,1]
	v_pk_fma_f32 v[2:3], v[52:53], v[4:5], v[2:3] op_sel_hi:[1,0,1]
	v_mov_b32_e32 v4, v99
	v_pk_fma_f32 v[36:37], v[44:45], v[14:15], v[36:37] op_sel_hi:[1,0,1]
	v_pk_fma_f32 v[18:19], v[50:51], v[6:7], v[40:41] op_sel:[0,1,0]
	v_pk_fma_f32 v[6:7], v[48:49], v[6:7], v[42:43] op_sel:[0,1,0]
	v_pk_fma_f32 v[34:35], v[58:59], v[4:5], v[34:35] op_sel_hi:[1,0,1]
	v_pk_fma_f32 v[28:29], v[56:57], v[4:5], v[28:29] op_sel_hi:[1,0,1]
	v_mov_b32_e32 v4, v5
	v_pk_fma_f32 v[14:15], v[48:49], v[14:15], v[36:37] op_sel:[0,1,0]
	v_pk_fma_f32 v[18:19], v[54:55], v[8:9], v[18:19] op_sel_hi:[1,0,1]
	v_pk_fma_f32 v[6:7], v[52:53], v[8:9], v[6:7] op_sel_hi:[1,0,1]
	v_pk_fma_f32 v[36:37], v[56:57], v[4:5], v[2:3] op_sel_hi:[1,0,1]
	v_mov_b32_e32 v2, v9
	v_pk_fma_f32 v[30:31], v[54:55], v[12:13], v[30:31] op_sel_hi:[1,0,1]
	v_pk_fma_f32 v[10:11], v[52:53], v[12:13], v[10:11] op_sel_hi:[1,0,1]
	v_pk_fma_f32 v[18:19], v[58:59], v[2:3], v[18:19] op_sel_hi:[1,0,1]
	v_pk_fma_f32 v[38:39], v[56:57], v[2:3], v[6:7] op_sel_hi:[1,0,1]
	v_mov_b32_e32 v2, v13
	v_pk_fma_f32 v[32:33], v[54:55], v[16:17], v[32:33] op_sel_hi:[1,0,1]
	v_pk_fma_f32 v[14:15], v[52:53], v[16:17], v[14:15] op_sel_hi:[1,0,1]
	v_pk_fma_f32 v[30:31], v[58:59], v[2:3], v[30:31] op_sel_hi:[1,0,1]
	v_pk_fma_f32 v[40:41], v[56:57], v[2:3], v[10:11] op_sel_hi:[1,0,1]
	v_mov_b32_e32 v2, v17
	v_pk_fma_f32 v[20:21], v[58:59], v[4:5], v[20:21] op_sel_hi:[1,0,1]
	v_pk_fma_f32 v[32:33], v[58:59], v[2:3], v[32:33] op_sel_hi:[1,0,1]
	v_pk_fma_f32 v[42:43], v[56:57], v[2:3], v[14:15] op_sel_hi:[1,0,1]
	ds_read_b128 v[2:5], v124 offset:544
	ds_read_b128 v[6:9], v124 offset:1056
	ds_read_b128 v[10:13], v124 offset:1568
	ds_read_b128 v[14:17], v124 offset:2080
	v_pk_fma_f32 v[34:35], v[62:63], v[100:101], v[34:35] op_sel_hi:[1,0,1]
	v_pk_fma_f32 v[28:29], v[60:61], v[100:101], v[28:29] op_sel_hi:[1,0,1]
	s_waitcnt lgkmcnt(3)
	v_pk_fma_f32 v[20:21], v[62:63], v[2:3], v[20:21] op_sel_hi:[1,0,1]
	v_pk_fma_f32 v[36:37], v[60:61], v[2:3], v[36:37] op_sel_hi:[1,0,1]
	v_pk_fma_f32 v[34:35], v[66:67], v[100:101], v[34:35] op_sel:[0,1,0]
	v_pk_fma_f32 v[28:29], v[64:65], v[100:101], v[28:29] op_sel:[0,1,0]
	v_pk_fma_f32 v[20:21], v[66:67], v[2:3], v[20:21] op_sel:[0,1,0]
	v_pk_fma_f32 v[2:3], v[64:65], v[2:3], v[36:37] op_sel:[0,1,0]
	s_waitcnt lgkmcnt(2)
	v_pk_fma_f32 v[18:19], v[62:63], v[6:7], v[18:19] op_sel_hi:[1,0,1]
	v_pk_fma_f32 v[38:39], v[60:61], v[6:7], v[38:39] op_sel_hi:[1,0,1]
	v_pk_fma_f32 v[34:35], v[70:71], v[102:103], v[34:35] op_sel_hi:[1,0,1]
	v_pk_fma_f32 v[28:29], v[68:69], v[102:103], v[28:29] op_sel_hi:[1,0,1]
	v_pk_fma_f32 v[20:21], v[70:71], v[4:5], v[20:21] op_sel_hi:[1,0,1]
	v_pk_fma_f32 v[2:3], v[68:69], v[4:5], v[2:3] op_sel_hi:[1,0,1]
	v_mov_b32_e32 v4, v103
	s_waitcnt lgkmcnt(1)
	v_pk_fma_f32 v[30:31], v[62:63], v[10:11], v[30:31] op_sel_hi:[1,0,1]
	v_pk_fma_f32 v[40:41], v[60:61], v[10:11], v[40:41] op_sel_hi:[1,0,1]
	v_pk_fma_f32 v[18:19], v[66:67], v[6:7], v[18:19] op_sel:[0,1,0]
	v_pk_fma_f32 v[6:7], v[64:65], v[6:7], v[38:39] op_sel:[0,1,0]
	v_pk_fma_f32 v[34:35], v[74:75], v[4:5], v[34:35] op_sel_hi:[1,0,1]
	v_pk_fma_f32 v[28:29], v[72:73], v[4:5], v[28:29] op_sel_hi:[1,0,1]
	v_mov_b32_e32 v4, v5
	s_waitcnt lgkmcnt(0)
	v_pk_fma_f32 v[32:33], v[62:63], v[14:15], v[32:33] op_sel_hi:[1,0,1]
	v_pk_fma_f32 v[42:43], v[60:61], v[14:15], v[42:43] op_sel_hi:[1,0,1]
	v_pk_fma_f32 v[30:31], v[66:67], v[10:11], v[30:31] op_sel:[0,1,0]
	v_pk_fma_f32 v[10:11], v[64:65], v[10:11], v[40:41] op_sel:[0,1,0]
	v_pk_fma_f32 v[18:19], v[70:71], v[8:9], v[18:19] op_sel_hi:[1,0,1]
	v_pk_fma_f32 v[6:7], v[68:69], v[8:9], v[6:7] op_sel_hi:[1,0,1]
	v_pk_fma_f32 v[36:37], v[72:73], v[4:5], v[2:3] op_sel_hi:[1,0,1]
	v_mov_b32_e32 v2, v9
	v_pk_fma_f32 v[32:33], v[66:67], v[14:15], v[32:33] op_sel:[0,1,0]
	v_pk_fma_f32 v[14:15], v[64:65], v[14:15], v[42:43] op_sel:[0,1,0]
	v_pk_fma_f32 v[30:31], v[70:71], v[12:13], v[30:31] op_sel_hi:[1,0,1]
	v_pk_fma_f32 v[10:11], v[68:69], v[12:13], v[10:11] op_sel_hi:[1,0,1]
	v_pk_fma_f32 v[18:19], v[74:75], v[2:3], v[18:19] op_sel_hi:[1,0,1]
	v_pk_fma_f32 v[38:39], v[72:73], v[2:3], v[6:7] op_sel_hi:[1,0,1]
	v_mov_b32_e32 v2, v13
	v_pk_fma_f32 v[32:33], v[70:71], v[16:17], v[32:33] op_sel_hi:[1,0,1]
	v_pk_fma_f32 v[14:15], v[68:69], v[16:17], v[14:15] op_sel_hi:[1,0,1]
	v_pk_fma_f32 v[12:13], v[74:75], v[2:3], v[30:31] op_sel_hi:[1,0,1]
	v_pk_fma_f32 v[10:11], v[72:73], v[2:3], v[10:11] op_sel_hi:[1,0,1]
	v_mov_b32_e32 v2, v17
	v_pk_fma_f32 v[20:21], v[74:75], v[4:5], v[20:21] op_sel_hi:[1,0,1]
	v_pk_fma_f32 v[16:17], v[74:75], v[2:3], v[32:33] op_sel_hi:[1,0,1]
	v_pk_fma_f32 v[14:15], v[72:73], v[2:3], v[14:15] op_sel_hi:[1,0,1]
	ds_read_b128 v[2:5], v124 offset:560
	ds_read_b128 v[6:9], v124 offset:1072
	v_pk_fma_f32 v[40:41], v[78:79], v[104:105], v[34:35] op_sel_hi:[1,0,1]
	v_pk_fma_f32 v[42:43], v[76:77], v[104:105], v[28:29] op_sel_hi:[1,0,1]
	ds_read_b128 v[28:31], v124 offset:1584
	ds_read_b128 v[32:35], v124 offset:2096
	s_waitcnt lgkmcnt(3)
	v_pk_fma_f32 v[20:21], v[78:79], v[2:3], v[20:21] op_sel_hi:[1,0,1]
	v_pk_fma_f32 v[36:37], v[76:77], v[2:3], v[36:37] op_sel_hi:[1,0,1]
	s_waitcnt lgkmcnt(2)
	v_pk_fma_f32 v[18:19], v[78:79], v[6:7], v[18:19] op_sel_hi:[1,0,1]
	s_waitcnt lgkmcnt(1)
	v_pk_fma_f32 v[12:13], v[78:79], v[28:29], v[12:13] op_sel_hi:[1,0,1]
	v_pk_fma_f32 v[10:11], v[76:77], v[28:29], v[10:11] op_sel_hi:[1,0,1]
	s_waitcnt lgkmcnt(0)
	v_pk_fma_f32 v[16:17], v[78:79], v[32:33], v[16:17] op_sel_hi:[1,0,1]
	v_pk_fma_f32 v[14:15], v[76:77], v[32:33], v[14:15] op_sel_hi:[1,0,1]
	v_pk_fma_f32 v[40:41], v[82:83], v[104:105], v[40:41] op_sel:[0,1,0]
	v_pk_fma_f32 v[42:43], v[80:81], v[104:105], v[42:43] op_sel:[0,1,0]
	v_pk_fma_f32 v[20:21], v[82:83], v[2:3], v[20:21] op_sel:[0,1,0]
	v_pk_fma_f32 v[2:3], v[80:81], v[2:3], v[36:37] op_sel:[0,1,0]
	v_pk_fma_f32 v[38:39], v[76:77], v[6:7], v[38:39] op_sel_hi:[1,0,1]
	v_pk_fma_f32 v[18:19], v[82:83], v[6:7], v[18:19] op_sel:[0,1,0]
	v_pk_fma_f32 v[12:13], v[82:83], v[28:29], v[12:13] op_sel:[0,1,0]
	v_pk_fma_f32 v[10:11], v[80:81], v[28:29], v[10:11] op_sel:[0,1,0]
	v_pk_fma_f32 v[16:17], v[82:83], v[32:33], v[16:17] op_sel:[0,1,0]
	v_pk_fma_f32 v[14:15], v[80:81], v[32:33], v[14:15] op_sel:[0,1,0]
	v_pk_fma_f32 v[28:29], v[86:87], v[106:107], v[40:41] op_sel_hi:[1,0,1]
	v_pk_fma_f32 v[32:33], v[84:85], v[106:107], v[42:43] op_sel_hi:[1,0,1]
	v_pk_fma_f32 v[36:37], v[86:87], v[4:5], v[20:21] op_sel_hi:[1,0,1]
	v_pk_fma_f32 v[2:3], v[84:85], v[4:5], v[2:3] op_sel_hi:[1,0,1]
	v_mov_b32_e32 v4, v107
	v_pk_fma_f32 v[6:7], v[80:81], v[6:7], v[38:39] op_sel:[0,1,0]
	v_pk_fma_f32 v[38:39], v[86:87], v[8:9], v[18:19] op_sel_hi:[1,0,1]
	v_pk_fma_f32 v[20:21], v[90:91], v[4:5], v[28:29] op_sel_hi:[1,0,1]
	v_pk_fma_f32 v[18:19], v[88:89], v[4:5], v[32:33] op_sel_hi:[1,0,1]
	v_mov_b32_e32 v4, v5
	v_pk_fma_f32 v[6:7], v[84:85], v[8:9], v[6:7] op_sel_hi:[1,0,1]
	v_pk_fma_f32 v[46:47], v[84:85], v[34:35], v[14:15] op_sel_hi:[1,0,1]
	v_pk_fma_f32 v[14:15], v[88:89], v[4:5], v[2:3] op_sel_hi:[1,0,1]
	v_mov_b32_e32 v2, v9
	v_pk_fma_f32 v[40:41], v[86:87], v[30:31], v[12:13] op_sel_hi:[1,0,1]
	v_pk_fma_f32 v[42:43], v[84:85], v[30:31], v[10:11] op_sel_hi:[1,0,1]
	v_pk_fma_f32 v[12:13], v[90:91], v[2:3], v[38:39] op_sel_hi:[1,0,1]
	v_pk_fma_f32 v[10:11], v[88:89], v[2:3], v[6:7] op_sel_hi:[1,0,1]
	v_mov_b32_e32 v2, v31
	v_pk_fma_f32 v[44:45], v[86:87], v[34:35], v[16:17] op_sel_hi:[1,0,1]
	v_pk_fma_f32 v[8:9], v[90:91], v[2:3], v[40:41] op_sel_hi:[1,0,1]
	v_pk_fma_f32 v[6:7], v[88:89], v[2:3], v[42:43] op_sel_hi:[1,0,1]
	v_mov_b32_e32 v2, v35
	v_pk_fma_f32 v[16:17], v[90:91], v[4:5], v[36:37] op_sel_hi:[1,0,1]
	v_pk_fma_f32 v[4:5], v[90:91], v[2:3], v[44:45] op_sel_hi:[1,0,1]
	v_pk_fma_f32 v[2:3], v[88:89], v[2:3], v[46:47] op_sel_hi:[1,0,1]
	s_cbranch_scc0 .LBB0_1648
	s_lshl_b32 s37, s37, 4
	s_and_b32 s37, s37, 16
	s_add_i32 s37, s52, s37
	s_mul_hi_i32 s54, s37, 0x3c000
	s_mul_i32 s37, s37, 0x3c000
	s_add_u32 s52, s7, s37
	s_addc_u32 s53, s8, s54
	s_add_u32 s52, s52, s2
	s_addc_u32 s53, s53, s3
	global_store_dwordx4 v22, v[18:21], s[52:53]
	s_add_u32 s52, s9, s37
	s_addc_u32 s53, s10, s54
	s_add_u32 s52, s52, s2
	s_addc_u32 s53, s53, s3
	global_store_dwordx4 v22, v[14:17], s[52:53]
	s_add_u32 s52, s11, s37
	s_addc_u32 s53, s12, s54
	s_add_u32 s52, s52, s2
	s_addc_u32 s53, s53, s3
	global_store_dwordx4 v22, v[10:13], s[52:53]
	s_add_u32 s52, s13, s37
	s_addc_u32 s53, s14, s54
	s_add_u32 s52, s52, s2
	s_addc_u32 s53, s53, s3
	s_add_u32 s37, s15, s37
	global_store_dwordx4 v22, v[6:9], s[52:53]
	s_addc_u32 s52, s16, s54
	s_add_u32 s2, s37, s2
	s_addc_u32 s3, s52, s3
	global_store_dwordx4 v22, v[2:5], s[2:3]
	s_waitcnt lgkmcnt(0)
	s_add_i32 s4, s4, s6
	s_cmpk_gt_i32 s4, 0x2ff
	s_cbranch_scc0 .LBB0_1647

.LBB0_1754:
	s_add_i32 s7, s22, 0xfffffc00
	s_and_b64 s[10:11], s[10:11], exec
	s_cselect_b32 s7, s22, s7
	s_ashr_i32 s10, s7, 31
	s_lshr_b32 s10, s10, 27
	s_add_i32 s10, s7, s10
	s_ashr_i32 s11, s10, 5
	s_lshl_b32 s10, s11, 6
	s_lshl_b32 s11, s11, 11
	s_lshl_b32 s7, s7, 6
	s_sub_i32 s12, s7, s11
	s_cmpk_gt_i32 s12, 0x7ff
	s_cselect_b64 s[14:15], -1, 0
	s_and_b64 vcc, exec, s[14:15]
	s_cbranch_vccnz .LBB0_1756
	v_or_b32_e32 v2, s10, v10
	v_ashrrev_i32_e32 v3, 31, v2
	v_lshlrev_b64 v[2:3], 13, v[2:3]
	v_lshl_add_u64 v[2:3], s[0:1], 0, v[2:3]
	s_ashr_i32 s13, s12, 31
	v_lshl_add_u64 v[2:3], s[12:13], 2, v[2:3]
	v_mov_b32_e32 v9, v7
	v_lshl_add_u64 v[118:119], v[2:3], 0, v[8:9]
	v_add_co_u32_e32 v62, vcc, 0x8000, v118
	s_nop 1
	v_addc_co_u32_e32 v63, vcc, 0, v119, vcc
	v_add_co_u32_e32 v66, vcc, 0x10000, v118
	global_load_dwordx4 v[2:5], v[118:119], off nt
	s_nop 0
	global_load_dwordx4 v[62:65], v[62:63], off nt
	v_addc_co_u32_e32 v67, vcc, 0, v119, vcc
	v_add_co_u32_e32 v70, vcc, 0x18000, v118
	s_nop 1
	v_addc_co_u32_e32 v71, vcc, 0, v119, vcc
	v_add_co_u32_e32 v74, vcc, 0x20000, v118
	global_load_dwordx4 v[66:69], v[66:67], off nt
	s_nop 0
	global_load_dwordx4 v[70:73], v[70:71], off nt
	v_addc_co_u32_e32 v75, vcc, 0, v119, vcc
	v_add_co_u32_e32 v78, vcc, 0x28000, v118
	s_nop 1
	v_addc_co_u32_e32 v79, vcc, 0, v119, vcc
	v_add_co_u32_e32 v82, vcc, 0x30000, v118
	global_load_dwordx4 v[74:77], v[74:75], off nt
	s_nop 0
	global_load_dwordx4 v[78:81], v[78:79], off nt
	v_addc_co_u32_e32 v83, vcc, 0, v119, vcc
	v_add_co_u32_e32 v86, vcc, 0x38000, v118
	s_nop 1
	v_addc_co_u32_e32 v87, vcc, 0, v119, vcc
	v_add_co_u32_e32 v90, vcc, 0x40000, v118
	global_load_dwordx4 v[82:85], v[82:83], off nt
	s_nop 0
	global_load_dwordx4 v[86:89], v[86:87], off nt
	v_addc_co_u32_e32 v91, vcc, 0, v119, vcc
	v_add_co_u32_e32 v94, vcc, 0x48000, v118
	s_nop 1
	v_addc_co_u32_e32 v95, vcc, 0, v119, vcc
	v_add_co_u32_e32 v98, vcc, 0x50000, v118
	global_load_dwordx4 v[90:93], v[90:91], off nt
	s_nop 0
	global_load_dwordx4 v[94:97], v[94:95], off nt
	v_addc_co_u32_e32 v99, vcc, 0, v119, vcc
	v_add_co_u32_e32 v102, vcc, 0x58000, v118
	s_nop 1
	v_addc_co_u32_e32 v103, vcc, 0, v119, vcc
	v_add_co_u32_e32 v106, vcc, 0x60000, v118
	global_load_dwordx4 v[98:101], v[98:99], off nt
	s_nop 0
	global_load_dwordx4 v[102:105], v[102:103], off nt
	v_addc_co_u32_e32 v107, vcc, 0, v119, vcc
	v_add_co_u32_e32 v110, vcc, 0x68000, v118
	s_nop 1
	v_addc_co_u32_e32 v111, vcc, 0, v119, vcc
	global_load_dwordx4 v[106:109], v[106:107], off nt
	s_nop 0
	global_load_dwordx4 v[110:113], v[110:111], off nt
	v_add_co_u32_e32 v114, vcc, 0x70000, v118
	s_nop 1
	v_addc_co_u32_e32 v115, vcc, 0, v119, vcc
	global_load_dwordx4 v[114:117], v[114:115], off nt
	v_add_co_u32_e32 v118, vcc, 0x78000, v118
	s_nop 1
	v_addc_co_u32_e32 v119, vcc, 0, v119, vcc
	global_load_dwordx4 v[118:121], v[118:119], off nt
	s_waitcnt vmcnt(0)
	ds_write2_b32 v27, v2, v3 offset1:1
	ds_write2_b32 v27, v4, v5 offset0:2 offset1:3
	ds_write2_b32 v28, v62, v63 offset1:1
	ds_write2_b32 v29, v64, v65 offset1:1
	ds_write2_b32 v30, v66, v67 offset1:1
	ds_write2_b32 v31, v68, v69 offset1:1
	ds_write2_b32 v32, v70, v71 offset1:1
	ds_write2_b32 v33, v72, v73 offset1:1
	ds_write2_b32 v34, v74, v75 offset1:1
	ds_write2_b32 v35, v76, v77 offset1:1
	ds_write2_b32 v36, v78, v79 offset1:1
	ds_write2_b32 v37, v80, v81 offset1:1
	ds_write2_b32 v38, v82, v83 offset1:1
	ds_write2_b32 v39, v84, v85 offset1:1
	ds_write2_b32 v40, v86, v87 offset1:1
	ds_write2_b32 v41, v88, v89 offset1:1
	ds_write2_b32 v42, v90, v91 offset1:1
	ds_write2_b32 v43, v92, v93 offset1:1
	ds_write2_b32 v44, v94, v95 offset1:1
	ds_write2_b32 v45, v96, v97 offset1:1
	ds_write2_b32 v46, v98, v99 offset1:1
	ds_write2_b32 v47, v100, v101 offset1:1
	ds_write2_b32 v48, v102, v103 offset1:1
	ds_write2_b32 v49, v104, v105 offset1:1
	ds_write2_b32 v50, v106, v107 offset1:1
	ds_write2_b32 v51, v108, v109 offset1:1
	ds_write2_b32 v52, v110, v111 offset1:1
	ds_write2_b32 v53, v112, v113 offset1:1
	ds_write2_b32 v54, v114, v115 offset1:1
	ds_write2_b32 v55, v116, v117 offset1:1
	ds_write2_b32 v56, v118, v119 offset1:1
	ds_write2_b32 v57, v120, v121 offset1:1

.LBB0_1774:
	v_mul_hi_i32 v2, v1, s7
	v_add_u32_e32 v2, v2, v1
	v_lshrrev_b32_e32 v6, 31, v2
	v_ashrrev_i32_e32 v2, 13, v2
	v_add_u32_e32 v2, v2, v6
	v_mad_i32_i24 v18, v2, s8, v1
	v_add_u32_e32 v11, 2, v2
	v_mul_hi_i32 v12, v18, s9
	v_mul_hi_i32_i24_e32 v7, 0xc000, v11
	v_mul_i32_i24_e32 v6, 0xc000, v11
	v_lshrrev_b32_e32 v14, 31, v12
	v_ashrrev_i32_e32 v12, 9, v12
	v_lshl_add_u64 v[16:17], s[46:47], 0, v[6:7]
	v_add_u32_e32 v6, v12, v14
	v_lshlrev_b32_e32 v2, 4, v2
	v_mul_i32_i24_e32 v19, 0xfffff400, v6
	v_and_b32_e32 v76, 16, v2
	v_add_lshl_u32 v18, v18, v19, 2
	v_mul_u32_u24_e32 v2, 5, v76
	v_ashrrev_i32_e32 v19, 31, v18
	v_mov_b32_e32 v13, v3
	v_or_b32_e32 v12, 5, v2
	v_ashrrev_i32_e32 v7, 31, v6
	v_lshlrev_b64 v[80:81], 2, v[18:19]
	v_mov_b32_e32 v15, v3
	v_or_b32_e32 v14, 10, v2
	v_lshl_add_u64 v[20:21], v[2:3], 0, v[6:7]
	v_lshl_add_u64 v[22:23], v[12:13], 0, v[6:7]
	v_or_b32_e32 v2, 15, v2
	v_lshl_add_u64 v[12:13], v[16:17], 0, v[80:81]
	v_lshl_add_u64 v[24:25], v[14:15], 0, v[6:7]
	v_lshl_add_u64 v[26:27], v[2:3], 0, v[6:7]
	v_mad_u32_u24 v2, v76, 5, 20
	global_load_dwordx4 v[12:15], v[12:13], off nt
	v_lshl_add_u64 v[18:19], v[2:3], 0, v[6:7]
	v_mad_u32_u24 v2, v76, 5, 25
	v_lshl_add_u64 v[72:73], s[2:3], 0, v[80:81]
	v_lshl_add_u64 v[16:17], v[2:3], 0, v[6:7]
	v_mad_u32_u24 v2, v76, 5, 30
	v_mad_u64_u32 v[28:29], s[12:13], v20, s10, v[72:73]
	v_mad_u64_u32 v[30:31], s[12:13], v22, s10, v[72:73]
	v_mad_u64_u32 v[32:33], s[12:13], v24, s10, v[72:73]
	v_mad_u64_u32 v[34:35], s[12:13], v26, s10, v[72:73]
	v_mad_u64_u32 v[36:37], s[12:13], v18, s10, v[72:73]
	v_mad_u64_u32 v[38:39], s[12:13], v16, s10, v[72:73]
	v_lshl_add_u64 v[40:41], v[2:3], 0, v[6:7]
	v_mad_u32_u24 v2, v76, 5, 35
	v_mad_i32_i24 v29, v21, s10, v29
	v_mad_i32_i24 v31, v23, s10, v31
	v_mad_i32_i24 v33, v25, s10, v33
	v_mad_i32_i24 v35, v27, s10, v35
	v_mad_i32_i24 v37, v19, s10, v37
	v_mad_i32_i24 v39, v17, s10, v39
	v_lshl_add_u64 v[44:45], v[2:3], 0, v[6:7]
	v_mad_u32_u24 v2, v76, 5, 40
	v_mad_u64_u32 v[42:43], s[12:13], v40, s10, v[72:73]
	global_load_dwordx4 v[16:19], v[28:29], off nt
	global_load_dwordx4 v[20:23], v[30:31], off nt
	global_load_dwordx4 v[24:27], v[32:33], off nt
	s_nop 0
	global_load_dwordx4 v[28:31], v[34:35], off nt
	s_nop 0
	global_load_dwordx4 v[32:35], v[36:37], off nt
	s_nop 0
	global_load_dwordx4 v[36:39], v[38:39], off nt
	v_mad_u64_u32 v[46:47], s[12:13], v44, s10, v[72:73]
	v_lshl_add_u64 v[48:49], v[2:3], 0, v[6:7]
	v_mad_u32_u24 v2, v76, 5, 45
	v_mad_i32_i24 v43, v41, s10, v43
	v_mad_i32_i24 v47, v45, s10, v47
	v_lshl_add_u64 v[52:53], v[2:3], 0, v[6:7]
	v_mad_u32_u24 v2, v76, 5, 50
	v_mad_u64_u32 v[50:51], s[12:13], v48, s10, v[72:73]
	global_load_dwordx4 v[40:43], v[42:43], off nt
	s_nop 0
	global_load_dwordx4 v[44:47], v[46:47], off nt
	v_mad_u64_u32 v[54:55], s[12:13], v52, s10, v[72:73]
	v_lshl_add_u64 v[56:57], v[2:3], 0, v[6:7]
	v_mad_u32_u24 v2, v76, 5, 55
	v_mad_i32_i24 v51, v49, s10, v51
	v_mad_i32_i24 v55, v53, s10, v55
	v_lshl_add_u64 v[60:61], v[2:3], 0, v[6:7]
	v_mad_u32_u24 v2, v76, 5, 60
	v_mad_u64_u32 v[58:59], s[12:13], v56, s10, v[72:73]
	global_load_dwordx4 v[48:51], v[50:51], off nt
	s_nop 0
	global_load_dwordx4 v[52:55], v[54:55], off nt
	v_mad_u64_u32 v[62:63], s[12:13], v60, s10, v[72:73]
	v_lshl_add_u64 v[64:65], v[2:3], 0, v[6:7]
	v_mad_u32_u24 v2, v76, 5, v8
	v_mad_i32_i24 v59, v57, s10, v59
	v_mad_i32_i24 v63, v61, s10, v63
	v_lshl_add_u64 v[68:69], v[2:3], 0, v[6:7]
	v_mad_u32_u24 v2, v76, 5, v9
	v_mad_u64_u32 v[66:67], s[12:13], v64, s10, v[72:73]
	global_load_dwordx4 v[56:59], v[58:59], off nt
	s_nop 0
	global_load_dwordx4 v[60:63], v[62:63], off nt
	v_mad_u64_u32 v[70:71], s[12:13], v68, s10, v[72:73]
	v_lshl_add_u64 v[74:75], v[2:3], 0, v[6:7]
	v_mad_u32_u24 v2, v76, 5, v10
	v_mad_i32_i24 v67, v65, s10, v67
	v_mad_i32_i24 v71, v69, s10, v71
	v_mad_u64_u32 v[76:77], s[12:13], v74, s10, v[72:73]
	v_lshl_add_u64 v[78:79], v[2:3], 0, v[6:7]
	global_load_dwordx4 v[64:67], v[66:67], off nt
	s_nop 0
	global_load_dwordx4 v[68:71], v[70:71], off nt
	v_mad_i32_i24 v77, v75, s10, v77
	v_mad_u64_u32 v[82:83], s[12:13], v78, s10, v[72:73]
	global_load_dwordx4 v[72:75], v[76:77], off nt
	v_mad_i32_i24 v83, v79, s10, v83
	global_load_dwordx4 v[76:79], v[82:83], off nt
	v_mul_hi_i32_i24_e32 v83, 5, v11
	v_mul_i32_i24_e32 v82, 5, v11
	v_lshl_add_u64 v[6:7], v[82:83], 0, v[6:7]
	v_mad_u64_u32 v[82:83], s[12:13], v6, s10, v[4:5]
	v_mov_b32_e32 v2, v83
	v_add_u32_e32 v1, s6, v1
	v_mad_u64_u32 v[6:7], s[12:13], v7, s10, v[2:3]
	v_cmp_lt_i32_e32 vcc, s11, v1
	v_mov_b32_e32 v83, v6
	s_or_b64 s[4:5], vcc, s[4:5]
	v_lshl_add_u64 v[6:7], v[82:83], 0, v[80:81]
	s_waitcnt vmcnt(0)
	v_pk_add_f32 v[14:15], v[14:15], v[18:19]
	v_pk_add_f32 v[12:13], v[12:13], v[16:17]
	v_pk_add_f32 v[14:15], v[14:15], v[22:23]
	v_pk_add_f32 v[12:13], v[12:13], v[20:21]
	v_pk_add_f32 v[14:15], v[14:15], v[26:27]
	v_pk_add_f32 v[12:13], v[12:13], v[24:25]
	v_pk_add_f32 v[14:15], v[14:15], v[30:31]
	v_pk_add_f32 v[12:13], v[12:13], v[28:29]
	v_pk_add_f32 v[14:15], v[14:15], v[34:35]
	v_pk_add_f32 v[12:13], v[12:13], v[32:33]
	v_pk_add_f32 v[14:15], v[14:15], v[38:39]
	v_pk_add_f32 v[12:13], v[12:13], v[36:37]
	v_pk_add_f32 v[14:15], v[14:15], v[42:43]
	v_pk_add_f32 v[12:13], v[12:13], v[40:41]
	v_pk_add_f32 v[14:15], v[14:15], v[46:47]
	v_pk_add_f32 v[12:13], v[12:13], v[44:45]
	v_pk_add_f32 v[14:15], v[14:15], v[50:51]
	v_pk_add_f32 v[12:13], v[12:13], v[48:49]
	v_pk_add_f32 v[14:15], v[14:15], v[54:55]
	v_pk_add_f32 v[12:13], v[12:13], v[52:53]
	v_pk_add_f32 v[14:15], v[14:15], v[58:59]
	v_pk_add_f32 v[12:13], v[12:13], v[56:57]
	v_pk_add_f32 v[14:15], v[14:15], v[62:63]
	v_pk_add_f32 v[12:13], v[12:13], v[60:61]
	v_pk_add_f32 v[14:15], v[14:15], v[66:67]
	v_pk_add_f32 v[12:13], v[12:13], v[64:65]
	v_pk_add_f32 v[14:15], v[14:15], v[70:71]
	v_pk_add_f32 v[12:13], v[12:13], v[68:69]
	v_pk_add_f32 v[14:15], v[14:15], v[74:75]
	v_pk_add_f32 v[12:13], v[12:13], v[72:73]
	v_pk_add_f32 v[14:15], v[14:15], v[78:79]
	v_pk_add_f32 v[12:13], v[12:13], v[76:77]
	global_store_dwordx4 v[6:7], v[12:15], off
	s_andn2_b64 exec, exec, s[4:5]
	s_cbranch_execnz .LBB0_1774

.LBB0_1998:
	s_lshl_b32 s28, s28, 6
	s_cmp_ge_i32 s0, s2
	s_cselect_b64 s[34:35], -1, 0
	s_and_b64 vcc, exec, s[34:35]
	s_cbranch_vccnz .LBB0_2000
	v_or_b32_e32 v2, s28, v9
	s_ashr_i32 s1, s28, 31
	s_mul_i32 s1, s1, s2
	v_mad_u64_u32 v[2:3], s[54:55], v2, s2, 0
	v_add_u32_e32 v3, s1, v3
	v_lshl_add_u64 v[2:3], v[2:3], 2, s[36:37]
	s_ashr_i32 s1, s0, 31
	v_lshl_add_u64 v[2:3], s[0:1], 2, v[2:3]
	v_mov_b32_e32 v11, v7
	v_lshl_add_u64 v[62:63], v[2:3], 0, v[10:11]
	global_load_dwordx4 v[2:5], v[62:63], off nt
	s_lshl_b64 s[0:1], s[2:3], 4
	v_lshl_add_u64 v[66:67], v[62:63], 0, s[0:1]
	global_load_dwordx4 v[62:65], v[66:67], off nt
	v_lshl_add_u64 v[70:71], v[66:67], 0, s[0:1]
	global_load_dwordx4 v[66:69], v[70:71], off nt
	v_lshl_add_u64 v[70:71], v[70:71], 0, s[0:1]
	global_load_dwordx4 v[76:79], v[70:71], off nt
	v_lshl_add_u64 v[70:71], v[70:71], 0, s[0:1]
	global_load_dwordx4 v[80:83], v[70:71], off nt
	v_lshl_add_u64 v[70:71], v[70:71], 0, s[0:1]
	global_load_dwordx4 v[84:87], v[70:71], off nt
	v_lshl_add_u64 v[70:71], v[70:71], 0, s[0:1]
	global_load_dwordx4 v[88:91], v[70:71], off nt
	v_lshl_add_u64 v[70:71], v[70:71], 0, s[0:1]
	global_load_dwordx4 v[92:95], v[70:71], off nt
	v_lshl_add_u64 v[70:71], v[70:71], 0, s[0:1]
	global_load_dwordx4 v[96:99], v[70:71], off nt
	v_lshl_add_u64 v[70:71], v[70:71], 0, s[0:1]
	global_load_dwordx4 v[100:103], v[70:71], off nt
	v_lshl_add_u64 v[70:71], v[70:71], 0, s[0:1]
	global_load_dwordx4 v[104:107], v[70:71], off nt
	v_lshl_add_u64 v[70:71], v[70:71], 0, s[0:1]
	global_load_dwordx4 v[108:111], v[70:71], off nt
	v_lshl_add_u64 v[70:71], v[70:71], 0, s[0:1]
	global_load_dwordx4 v[112:115], v[70:71], off nt
	v_lshl_add_u64 v[70:71], v[70:71], 0, s[0:1]
	global_load_dwordx4 v[116:119], v[70:71], off nt
	v_lshl_add_u64 v[70:71], v[70:71], 0, s[0:1]
	global_load_dwordx4 v[120:123], v[70:71], off nt
	v_lshl_add_u64 v[70:71], v[70:71], 0, s[0:1]
	global_load_dwordx4 v[124:127], v[70:71], off nt
	v_add_u32_e32 v11, 0x38e0, v35
	v_add_u32_e32 v70, 0x38e8, v35
	v_add_u32_e32 v71, 0x3cf0, v35
	v_add_u32_e32 v128, 0x3cf8, v35
	s_waitcnt vmcnt(0)
	ds_write2_b32 v35, v2, v3 offset1:1
	ds_write2_b32 v35, v4, v5 offset0:2 offset1:3
	ds_write2_b32 v36, v62, v63 offset1:1
	ds_write2_b32 v37, v64, v65 offset1:1
	ds_write2_b32 v38, v66, v67 offset1:1
	ds_write2_b32 v39, v68, v69 offset1:1
	ds_write2_b32 v40, v76, v77 offset1:1
	ds_write2_b32 v41, v78, v79 offset1:1
	ds_write2_b32 v42, v80, v81 offset1:1
	ds_write2_b32 v43, v82, v83 offset1:1
	ds_write2_b32 v44, v84, v85 offset1:1
	ds_write2_b32 v45, v86, v87 offset1:1
	ds_write2_b32 v46, v88, v89 offset1:1
	ds_write2_b32 v47, v90, v91 offset1:1
	ds_write2_b32 v48, v92, v93 offset1:1
	ds_write2_b32 v49, v94, v95 offset1:1
	ds_write2_b32 v50, v96, v97 offset1:1
	ds_write2_b32 v51, v98, v99 offset1:1
	ds_write2_b32 v52, v100, v101 offset1:1
	ds_write2_b32 v53, v102, v103 offset1:1
	ds_write2_b32 v54, v104, v105 offset1:1
	ds_write2_b32 v55, v106, v107 offset1:1
	ds_write2_b32 v56, v108, v109 offset1:1
	ds_write2_b32 v57, v110, v111 offset1:1
	ds_write2_b32 v58, v112, v113 offset1:1
	ds_write2_b32 v59, v114, v115 offset1:1
	ds_write2_b32 v60, v116, v117 offset1:1
	ds_write2_b32 v61, v118, v119 offset1:1
	ds_write2_b32 v11, v120, v121 offset1:1
	ds_write2_b32 v70, v122, v123 offset1:1
	ds_write2_b32 v71, v124, v125 offset1:1
	ds_write2_b32 v128, v126, v127 offset1:1

.LBB0_2478:
	v_add_co_u32_e32 v32, vcc, s26, v30
	global_load_dwordx4 v[22:25], v[30:31], off nt
	s_nop 0
	v_addc_co_u32_e32 v33, vcc, -1, v31, vcc
	v_add_co_u32_e32 v34, vcc, s27, v30
	v_mov_b32_e32 v170, s2
	s_nop 0
	v_addc_co_u32_e32 v35, vcc, -1, v31, vcc
	v_add_co_u32_e32 v36, vcc, s28, v30
	s_add_i32 s3, s3, 16
	s_nop 0
	v_addc_co_u32_e32 v37, vcc, -1, v31, vcc
	v_add_co_u32_e32 v38, vcc, s29, v30
	s_add_i32 s2, s2, 64
	s_nop 0
	v_addc_co_u32_e32 v39, vcc, -1, v31, vcc
	v_add_co_u32_e32 v40, vcc, s30, v30
	s_cmpk_gt_u32 s3, 0x6f
	s_nop 0
	v_addc_co_u32_e32 v41, vcc, -1, v31, vcc
	v_add_co_u32_e32 v42, vcc, s31, v30
	s_nop 1
	v_addc_co_u32_e32 v43, vcc, -1, v31, vcc
	v_add_co_u32_e32 v44, vcc, s34, v30
	s_nop 1
	v_addc_co_u32_e32 v45, vcc, -1, v31, vcc
	v_add_co_u32_e32 v46, vcc, s35, v30
	s_nop 1
	v_addc_co_u32_e32 v47, vcc, -1, v31, vcc
	v_add_co_u32_e32 v48, vcc, s36, v30
	s_nop 1
	v_addc_co_u32_e32 v49, vcc, -1, v31, vcc
	v_add_co_u32_e32 v50, vcc, s37, v30
	s_nop 1
	v_addc_co_u32_e32 v51, vcc, -1, v31, vcc
	v_add_co_u32_e32 v52, vcc, s44, v30
	s_nop 1
	v_addc_co_u32_e32 v53, vcc, -1, v31, vcc
	v_add_co_u32_e32 v54, vcc, s45, v30
	s_nop 1
	v_addc_co_u32_e32 v55, vcc, -1, v31, vcc
	v_add_co_u32_e32 v56, vcc, s52, v30
	s_nop 1
	v_addc_co_u32_e32 v57, vcc, -1, v31, vcc
	v_add_co_u32_e32 v58, vcc, s53, v30
	s_nop 1
	v_addc_co_u32_e32 v59, vcc, -1, v31, vcc
	v_add_co_u32_e32 v60, vcc, s54, v30
	s_nop 1
	v_addc_co_u32_e32 v61, vcc, -1, v31, vcc
	global_load_dwordx4 v[62:65], v[32:33], off nt
	s_nop 0
	global_load_dwordx4 v[32:35], v[34:35], off nt
	s_nop 0
	global_load_dwordx4 v[66:69], v[36:37], off nt
	s_nop 0
	global_load_dwordx4 v[36:39], v[38:39], off nt
	s_nop 0
	global_load_dwordx4 v[70:73], v[40:41], off nt
	s_nop 0
	global_load_dwordx4 v[40:43], v[42:43], off nt
	s_nop 0
	global_load_dwordx4 v[74:77], v[44:45], off nt
	s_nop 0
	global_load_dwordx4 v[44:47], v[46:47], off nt
	s_nop 0
	global_load_dwordx4 v[78:81], v[48:49], off nt
	s_nop 0
	global_load_dwordx4 v[48:51], v[50:51], off nt
	s_nop 0
	global_load_dwordx4 v[82:85], v[52:53], off nt
	s_nop 0
	global_load_dwordx4 v[52:55], v[54:55], off nt
	s_nop 0
	global_load_dwordx4 v[86:89], v[56:57], off nt
	s_nop 0
	global_load_dwordx4 v[56:59], v[58:59], off nt
	s_nop 0
	global_load_dwordx4 v[90:93], v[60:61], off nt
	ds_read_b128 v[94:97], v170
	ds_read_b128 v[98:101], v170 offset:16
	ds_read_b128 v[102:105], v170 offset:32
	ds_read_b128 v[106:109], v170 offset:48
	ds_read_b128 v[110:113], v170 offset:512
	ds_read_b128 v[114:117], v170 offset:528
	ds_read_b128 v[118:121], v170 offset:1024
	ds_read_b128 v[122:125], v170 offset:1040
	ds_read_b128 v[126:129], v170 offset:1536
	ds_read_b128 v[130:133], v170 offset:1552
	ds_read_b128 v[134:137], v170 offset:2048
	ds_read_b128 v[138:141], v170 offset:2064
	ds_read_b128 v[142:145], v170 offset:544
	ds_read_b128 v[146:149], v170 offset:560
	ds_read_b128 v[150:153], v170 offset:1056
	ds_read_b128 v[154:157], v170 offset:1072
	ds_read_b128 v[158:161], v170 offset:1568
	ds_read_b128 v[162:165], v170 offset:1584
	ds_read_b128 v[166:169], v170 offset:2080
	ds_read_b128 v[170:173], v170 offset:2096
	s_waitcnt lgkmcnt(14)
	v_mov_b32_e32 v60, v97
	v_mov_b32_e32 v174, v113
	s_waitcnt lgkmcnt(13)
	v_mov_b32_e32 v176, v121
	s_waitcnt lgkmcnt(11)
	v_mov_b32_e32 v182, v129
	s_waitcnt lgkmcnt(9)
	v_mov_b32_e32 v184, v137
	v_mov_b32_e32 v186, v101
	v_mov_b32_e32 v188, v117
	v_mov_b32_e32 v190, v125
	v_mov_b32_e32 v192, v133
	s_waitcnt lgkmcnt(8)
	v_mov_b32_e32 v194, v141
	v_mov_b32_e32 v196, v105
	s_waitcnt lgkmcnt(7)
	v_mov_b32_e32 v198, v145
	s_waitcnt lgkmcnt(5)
	v_mov_b32_e32 v200, v153
	s_waitcnt lgkmcnt(3)
	v_mov_b32_e32 v202, v161
	s_waitcnt lgkmcnt(1)
	v_mov_b32_e32 v204, v169
	v_mov_b32_e32 v206, v109
	v_mov_b32_e32 v208, v149
	v_mov_b32_e32 v210, v157
	v_mov_b32_e32 v212, v165
	s_waitcnt lgkmcnt(0)
	v_mov_b32_e32 v214, v173
	v_lshl_add_u64 v[30:31], v[30:31], 0, s[6:7]
	s_waitcnt vmcnt(14)
	v_pk_fma_f32 v[20:21], v[64:65], v[94:95], v[20:21] op_sel_hi:[1,0,1]
	v_pk_fma_f32 v[18:19], v[62:63], v[94:95], v[18:19] op_sel_hi:[1,0,1]
	v_pk_fma_f32 v[16:17], v[64:65], v[110:111], v[16:17] op_sel_hi:[1,0,1]
	v_pk_fma_f32 v[14:15], v[62:63], v[110:111], v[14:15] op_sel_hi:[1,0,1]
	v_pk_fma_f32 v[12:13], v[64:65], v[118:119], v[12:13] op_sel_hi:[1,0,1]
	v_pk_fma_f32 v[10:11], v[62:63], v[118:119], v[10:11] op_sel_hi:[1,0,1]
	v_pk_fma_f32 v[8:9], v[64:65], v[126:127], v[8:9] op_sel_hi:[1,0,1]
	v_pk_fma_f32 v[6:7], v[62:63], v[126:127], v[6:7] op_sel_hi:[1,0,1]
	v_pk_fma_f32 v[4:5], v[64:65], v[134:135], v[4:5] op_sel_hi:[1,0,1]
	v_pk_fma_f32 v[2:3], v[62:63], v[134:135], v[2:3] op_sel_hi:[1,0,1]
	s_waitcnt vmcnt(13)
	v_pk_fma_f32 v[20:21], v[34:35], v[94:95], v[20:21] op_sel:[0,1,0]
	v_pk_fma_f32 v[18:19], v[32:33], v[94:95], v[18:19] op_sel:[0,1,0]
	v_pk_fma_f32 v[16:17], v[34:35], v[110:111], v[16:17] op_sel:[0,1,0]
	v_pk_fma_f32 v[14:15], v[32:33], v[110:111], v[14:15] op_sel:[0,1,0]
	v_pk_fma_f32 v[12:13], v[34:35], v[118:119], v[12:13] op_sel:[0,1,0]
	v_pk_fma_f32 v[10:11], v[32:33], v[118:119], v[10:11] op_sel:[0,1,0]
	v_pk_fma_f32 v[8:9], v[34:35], v[126:127], v[8:9] op_sel:[0,1,0]
	v_pk_fma_f32 v[6:7], v[32:33], v[126:127], v[6:7] op_sel:[0,1,0]
	v_pk_fma_f32 v[4:5], v[34:35], v[134:135], v[4:5] op_sel:[0,1,0]
	v_pk_fma_f32 v[2:3], v[32:33], v[134:135], v[2:3] op_sel:[0,1,0]
	s_waitcnt vmcnt(12)
	v_pk_fma_f32 v[20:21], v[68:69], v[96:97], v[20:21] op_sel_hi:[1,0,1]
	v_pk_fma_f32 v[18:19], v[66:67], v[96:97], v[18:19] op_sel_hi:[1,0,1]
	v_pk_fma_f32 v[16:17], v[68:69], v[112:113], v[16:17] op_sel_hi:[1,0,1]
	v_pk_fma_f32 v[14:15], v[66:67], v[112:113], v[14:15] op_sel_hi:[1,0,1]
	v_pk_fma_f32 v[12:13], v[68:69], v[120:121], v[12:13] op_sel_hi:[1,0,1]
	v_pk_fma_f32 v[10:11], v[66:67], v[120:121], v[10:11] op_sel_hi:[1,0,1]
	v_pk_fma_f32 v[8:9], v[68:69], v[128:129], v[8:9] op_sel_hi:[1,0,1]
	v_pk_fma_f32 v[6:7], v[66:67], v[128:129], v[6:7] op_sel_hi:[1,0,1]
	v_pk_fma_f32 v[4:5], v[68:69], v[136:137], v[4:5] op_sel_hi:[1,0,1]
	v_pk_fma_f32 v[2:3], v[66:67], v[136:137], v[2:3] op_sel_hi:[1,0,1]
	s_waitcnt vmcnt(11)
	v_pk_fma_f32 v[20:21], v[38:39], v[60:61], v[20:21] op_sel_hi:[1,0,1]
	v_pk_fma_f32 v[18:19], v[36:37], v[60:61], v[18:19] op_sel_hi:[1,0,1]
	v_pk_fma_f32 v[16:17], v[38:39], v[174:175], v[16:17] op_sel_hi:[1,0,1]
	v_pk_fma_f32 v[14:15], v[36:37], v[174:175], v[14:15] op_sel_hi:[1,0,1]
	v_pk_fma_f32 v[12:13], v[38:39], v[176:177], v[12:13] op_sel_hi:[1,0,1]
	v_pk_fma_f32 v[10:11], v[36:37], v[176:177], v[10:11] op_sel_hi:[1,0,1]
	v_pk_fma_f32 v[8:9], v[38:39], v[182:183], v[8:9] op_sel_hi:[1,0,1]
	v_pk_fma_f32 v[6:7], v[36:37], v[182:183], v[6:7] op_sel_hi:[1,0,1]
	v_pk_fma_f32 v[4:5], v[38:39], v[184:185], v[4:5] op_sel_hi:[1,0,1]
	v_pk_fma_f32 v[2:3], v[36:37], v[184:185], v[2:3] op_sel_hi:[1,0,1]
	s_waitcnt vmcnt(10)
	v_pk_fma_f32 v[20:21], v[72:73], v[98:99], v[20:21] op_sel_hi:[1,0,1]
	v_pk_fma_f32 v[18:19], v[70:71], v[98:99], v[18:19] op_sel_hi:[1,0,1]
	v_pk_fma_f32 v[16:17], v[72:73], v[114:115], v[16:17] op_sel_hi:[1,0,1]
	v_pk_fma_f32 v[14:15], v[70:71], v[114:115], v[14:15] op_sel_hi:[1,0,1]
	v_pk_fma_f32 v[12:13], v[72:73], v[122:123], v[12:13] op_sel_hi:[1,0,1]
	v_pk_fma_f32 v[10:11], v[70:71], v[122:123], v[10:11] op_sel_hi:[1,0,1]
	v_pk_fma_f32 v[8:9], v[72:73], v[130:131], v[8:9] op_sel_hi:[1,0,1]
	v_pk_fma_f32 v[6:7], v[70:71], v[130:131], v[6:7] op_sel_hi:[1,0,1]
	v_pk_fma_f32 v[4:5], v[72:73], v[138:139], v[4:5] op_sel_hi:[1,0,1]
	v_pk_fma_f32 v[2:3], v[70:71], v[138:139], v[2:3] op_sel_hi:[1,0,1]
	s_waitcnt vmcnt(9)
	v_pk_fma_f32 v[20:21], v[42:43], v[98:99], v[20:21] op_sel:[0,1,0]
	v_pk_fma_f32 v[18:19], v[40:41], v[98:99], v[18:19] op_sel:[0,1,0]
	v_pk_fma_f32 v[16:17], v[42:43], v[114:115], v[16:17] op_sel:[0,1,0]
	v_pk_fma_f32 v[14:15], v[40:41], v[114:115], v[14:15] op_sel:[0,1,0]
	v_pk_fma_f32 v[12:13], v[42:43], v[122:123], v[12:13] op_sel:[0,1,0]
	v_pk_fma_f32 v[10:11], v[40:41], v[122:123], v[10:11] op_sel:[0,1,0]
	v_pk_fma_f32 v[8:9], v[42:43], v[130:131], v[8:9] op_sel:[0,1,0]
	v_pk_fma_f32 v[6:7], v[40:41], v[130:131], v[6:7] op_sel:[0,1,0]
	v_pk_fma_f32 v[4:5], v[42:43], v[138:139], v[4:5] op_sel:[0,1,0]
	v_pk_fma_f32 v[2:3], v[40:41], v[138:139], v[2:3] op_sel:[0,1,0]
	s_waitcnt vmcnt(8)
	v_pk_fma_f32 v[20:21], v[76:77], v[100:101], v[20:21] op_sel_hi:[1,0,1]
	v_pk_fma_f32 v[18:19], v[74:75], v[100:101], v[18:19] op_sel_hi:[1,0,1]
	v_pk_fma_f32 v[16:17], v[76:77], v[116:117], v[16:17] op_sel_hi:[1,0,1]
	v_pk_fma_f32 v[14:15], v[74:75], v[116:117], v[14:15] op_sel_hi:[1,0,1]
	v_pk_fma_f32 v[12:13], v[76:77], v[124:125], v[12:13] op_sel_hi:[1,0,1]
	v_pk_fma_f32 v[10:11], v[74:75], v[124:125], v[10:11] op_sel_hi:[1,0,1]
	v_pk_fma_f32 v[8:9], v[76:77], v[132:133], v[8:9] op_sel_hi:[1,0,1]
	v_pk_fma_f32 v[6:7], v[74:75], v[132:133], v[6:7] op_sel_hi:[1,0,1]
	v_pk_fma_f32 v[4:5], v[76:77], v[140:141], v[4:5] op_sel_hi:[1,0,1]
	v_pk_fma_f32 v[2:3], v[74:75], v[140:141], v[2:3] op_sel_hi:[1,0,1]
	s_waitcnt vmcnt(7)
	v_pk_fma_f32 v[20:21], v[46:47], v[186:187], v[20:21] op_sel_hi:[1,0,1]
	v_pk_fma_f32 v[18:19], v[44:45], v[186:187], v[18:19] op_sel_hi:[1,0,1]
	v_pk_fma_f32 v[16:17], v[46:47], v[188:189], v[16:17] op_sel_hi:[1,0,1]
	v_pk_fma_f32 v[14:15], v[44:45], v[188:189], v[14:15] op_sel_hi:[1,0,1]
	v_pk_fma_f32 v[12:13], v[46:47], v[190:191], v[12:13] op_sel_hi:[1,0,1]
	v_pk_fma_f32 v[10:11], v[44:45], v[190:191], v[10:11] op_sel_hi:[1,0,1]
	v_pk_fma_f32 v[8:9], v[46:47], v[192:193], v[8:9] op_sel_hi:[1,0,1]
	v_pk_fma_f32 v[6:7], v[44:45], v[192:193], v[6:7] op_sel_hi:[1,0,1]
	v_pk_fma_f32 v[4:5], v[46:47], v[194:195], v[4:5] op_sel_hi:[1,0,1]
	v_pk_fma_f32 v[2:3], v[44:45], v[194:195], v[2:3] op_sel_hi:[1,0,1]
	s_waitcnt vmcnt(6)
	v_pk_fma_f32 v[20:21], v[80:81], v[102:103], v[20:21] op_sel_hi:[1,0,1]
	v_pk_fma_f32 v[18:19], v[78:79], v[102:103], v[18:19] op_sel_hi:[1,0,1]
	v_pk_fma_f32 v[16:17], v[80:81], v[142:143], v[16:17] op_sel_hi:[1,0,1]
	v_pk_fma_f32 v[14:15], v[78:79], v[142:143], v[14:15] op_sel_hi:[1,0,1]
	v_pk_fma_f32 v[12:13], v[80:81], v[150:151], v[12:13] op_sel_hi:[1,0,1]
	v_pk_fma_f32 v[10:11], v[78:79], v[150:151], v[10:11] op_sel_hi:[1,0,1]
	v_pk_fma_f32 v[8:9], v[80:81], v[158:159], v[8:9] op_sel_hi:[1,0,1]
	v_pk_fma_f32 v[6:7], v[78:79], v[158:159], v[6:7] op_sel_hi:[1,0,1]
	v_pk_fma_f32 v[4:5], v[80:81], v[166:167], v[4:5] op_sel_hi:[1,0,1]
	v_pk_fma_f32 v[2:3], v[78:79], v[166:167], v[2:3] op_sel_hi:[1,0,1]
	s_waitcnt vmcnt(5)
	v_pk_fma_f32 v[20:21], v[50:51], v[102:103], v[20:21] op_sel:[0,1,0]
	v_pk_fma_f32 v[18:19], v[48:49], v[102:103], v[18:19] op_sel:[0,1,0]
	v_pk_fma_f32 v[16:17], v[50:51], v[142:143], v[16:17] op_sel:[0,1,0]
	v_pk_fma_f32 v[14:15], v[48:49], v[142:143], v[14:15] op_sel:[0,1,0]
	v_pk_fma_f32 v[12:13], v[50:51], v[150:151], v[12:13] op_sel:[0,1,0]
	v_pk_fma_f32 v[10:11], v[48:49], v[150:151], v[10:11] op_sel:[0,1,0]
	v_pk_fma_f32 v[8:9], v[50:51], v[158:159], v[8:9] op_sel:[0,1,0]
	v_pk_fma_f32 v[6:7], v[48:49], v[158:159], v[6:7] op_sel:[0,1,0]
	v_pk_fma_f32 v[4:5], v[50:51], v[166:167], v[4:5] op_sel:[0,1,0]
	v_pk_fma_f32 v[2:3], v[48:49], v[166:167], v[2:3] op_sel:[0,1,0]
	s_waitcnt vmcnt(4)
	v_pk_fma_f32 v[20:21], v[84:85], v[104:105], v[20:21] op_sel_hi:[1,0,1]
	v_pk_fma_f32 v[18:19], v[82:83], v[104:105], v[18:19] op_sel_hi:[1,0,1]
	v_pk_fma_f32 v[16:17], v[84:85], v[144:145], v[16:17] op_sel_hi:[1,0,1]
	v_pk_fma_f32 v[14:15], v[82:83], v[144:145], v[14:15] op_sel_hi:[1,0,1]
	v_pk_fma_f32 v[12:13], v[84:85], v[152:153], v[12:13] op_sel_hi:[1,0,1]
	v_pk_fma_f32 v[10:11], v[82:83], v[152:153], v[10:11] op_sel_hi:[1,0,1]
	v_pk_fma_f32 v[8:9], v[84:85], v[160:161], v[8:9] op_sel_hi:[1,0,1]
	v_pk_fma_f32 v[6:7], v[82:83], v[160:161], v[6:7] op_sel_hi:[1,0,1]
	v_pk_fma_f32 v[4:5], v[84:85], v[168:169], v[4:5] op_sel_hi:[1,0,1]
	v_pk_fma_f32 v[2:3], v[82:83], v[168:169], v[2:3] op_sel_hi:[1,0,1]
	s_waitcnt vmcnt(3)
	v_pk_fma_f32 v[20:21], v[54:55], v[196:197], v[20:21] op_sel_hi:[1,0,1]
	v_pk_fma_f32 v[18:19], v[52:53], v[196:197], v[18:19] op_sel_hi:[1,0,1]
	v_pk_fma_f32 v[16:17], v[54:55], v[198:199], v[16:17] op_sel_hi:[1,0,1]
	v_pk_fma_f32 v[14:15], v[52:53], v[198:199], v[14:15] op_sel_hi:[1,0,1]
	v_pk_fma_f32 v[12:13], v[54:55], v[200:201], v[12:13] op_sel_hi:[1,0,1]
	v_pk_fma_f32 v[10:11], v[52:53], v[200:201], v[10:11] op_sel_hi:[1,0,1]
	v_pk_fma_f32 v[8:9], v[54:55], v[202:203], v[8:9] op_sel_hi:[1,0,1]
	v_pk_fma_f32 v[6:7], v[52:53], v[202:203], v[6:7] op_sel_hi:[1,0,1]
	v_pk_fma_f32 v[4:5], v[54:55], v[204:205], v[4:5] op_sel_hi:[1,0,1]
	v_pk_fma_f32 v[2:3], v[52:53], v[204:205], v[2:3] op_sel_hi:[1,0,1]
	s_waitcnt vmcnt(2)
	v_pk_fma_f32 v[20:21], v[88:89], v[106:107], v[20:21] op_sel_hi:[1,0,1]
	v_pk_fma_f32 v[18:19], v[86:87], v[106:107], v[18:19] op_sel_hi:[1,0,1]
	v_pk_fma_f32 v[16:17], v[88:89], v[146:147], v[16:17] op_sel_hi:[1,0,1]
	v_pk_fma_f32 v[14:15], v[86:87], v[146:147], v[14:15] op_sel_hi:[1,0,1]
	v_pk_fma_f32 v[12:13], v[88:89], v[154:155], v[12:13] op_sel_hi:[1,0,1]
	v_pk_fma_f32 v[10:11], v[86:87], v[154:155], v[10:11] op_sel_hi:[1,0,1]
	v_pk_fma_f32 v[8:9], v[88:89], v[162:163], v[8:9] op_sel_hi:[1,0,1]
	v_pk_fma_f32 v[6:7], v[86:87], v[162:163], v[6:7] op_sel_hi:[1,0,1]
	v_pk_fma_f32 v[4:5], v[88:89], v[170:171], v[4:5] op_sel_hi:[1,0,1]
	v_pk_fma_f32 v[2:3], v[86:87], v[170:171], v[2:3] op_sel_hi:[1,0,1]
	s_waitcnt vmcnt(1)
	v_pk_fma_f32 v[20:21], v[58:59], v[106:107], v[20:21] op_sel:[0,1,0]
	v_pk_fma_f32 v[18:19], v[56:57], v[106:107], v[18:19] op_sel:[0,1,0]
	v_pk_fma_f32 v[16:17], v[58:59], v[146:147], v[16:17] op_sel:[0,1,0]
	v_pk_fma_f32 v[14:15], v[56:57], v[146:147], v[14:15] op_sel:[0,1,0]
	v_pk_fma_f32 v[12:13], v[58:59], v[154:155], v[12:13] op_sel:[0,1,0]
	v_pk_fma_f32 v[10:11], v[56:57], v[154:155], v[10:11] op_sel:[0,1,0]
	v_pk_fma_f32 v[8:9], v[58:59], v[162:163], v[8:9] op_sel:[0,1,0]
	v_pk_fma_f32 v[6:7], v[56:57], v[162:163], v[6:7] op_sel:[0,1,0]
	v_pk_fma_f32 v[4:5], v[58:59], v[170:171], v[4:5] op_sel:[0,1,0]
	v_pk_fma_f32 v[2:3], v[56:57], v[170:171], v[2:3] op_sel:[0,1,0]
	s_waitcnt vmcnt(0)
	v_pk_fma_f32 v[20:21], v[92:93], v[108:109], v[20:21] op_sel_hi:[1,0,1]
	v_pk_fma_f32 v[18:19], v[90:91], v[108:109], v[18:19] op_sel_hi:[1,0,1]
	v_pk_fma_f32 v[16:17], v[92:93], v[148:149], v[16:17] op_sel_hi:[1,0,1]
	v_pk_fma_f32 v[14:15], v[90:91], v[148:149], v[14:15] op_sel_hi:[1,0,1]
	v_pk_fma_f32 v[12:13], v[92:93], v[156:157], v[12:13] op_sel_hi:[1,0,1]
	v_pk_fma_f32 v[10:11], v[90:91], v[156:157], v[10:11] op_sel_hi:[1,0,1]
	v_pk_fma_f32 v[8:9], v[92:93], v[164:165], v[8:9] op_sel_hi:[1,0,1]
	v_pk_fma_f32 v[6:7], v[90:91], v[164:165], v[6:7] op_sel_hi:[1,0,1]
	v_pk_fma_f32 v[4:5], v[92:93], v[172:173], v[4:5] op_sel_hi:[1,0,1]
	v_pk_fma_f32 v[2:3], v[90:91], v[172:173], v[2:3] op_sel_hi:[1,0,1]
	v_pk_fma_f32 v[20:21], v[24:25], v[206:207], v[20:21] op_sel_hi:[1,0,1]
	v_pk_fma_f32 v[18:19], v[22:23], v[206:207], v[18:19] op_sel_hi:[1,0,1]
	v_pk_fma_f32 v[16:17], v[24:25], v[208:209], v[16:17] op_sel_hi:[1,0,1]
	v_pk_fma_f32 v[14:15], v[22:23], v[208:209], v[14:15] op_sel_hi:[1,0,1]
	v_pk_fma_f32 v[12:13], v[24:25], v[210:211], v[12:13] op_sel_hi:[1,0,1]
	v_pk_fma_f32 v[10:11], v[22:23], v[210:211], v[10:11] op_sel_hi:[1,0,1]
	v_pk_fma_f32 v[8:9], v[24:25], v[212:213], v[8:9] op_sel_hi:[1,0,1]
	v_pk_fma_f32 v[6:7], v[22:23], v[212:213], v[6:7] op_sel_hi:[1,0,1]
	v_pk_fma_f32 v[4:5], v[24:25], v[214:215], v[4:5] op_sel_hi:[1,0,1]
	v_pk_fma_f32 v[2:3], v[22:23], v[214:215], v[2:3] op_sel_hi:[1,0,1]
	s_cbranch_scc0 .LBB0_2478
	s_lshl_b32 s2, s55, 4
	s_add_i32 s2, s2, -16
	s_and_b32 s2, s2, 16
	s_add_i32 s2, s56, s2
	s_mul_i32 s5, s2, 0x3c000
	s_mul_hi_i32 s4, s2, 0x3c000
	s_add_u32 s2, s11, s5
	s_addc_u32 s3, s12, s4
	s_add_u32 s2, s2, s0
	s_addc_u32 s3, s3, s1
	global_store_dwordx4 v26, v[18:21], s[2:3]
	s_add_u32 s2, s13, s5
	s_addc_u32 s3, s14, s4
	s_add_u32 s2, s2, s0
	s_addc_u32 s3, s3, s1
	global_store_dwordx4 v26, v[14:17], s[2:3]
	s_add_u32 s2, s15, s5
	s_addc_u32 s3, s16, s4
	s_add_u32 s2, s2, s0
	s_addc_u32 s3, s3, s1
	global_store_dwordx4 v26, v[10:13], s[2:3]
	s_add_u32 s2, s17, s5
	s_addc_u32 s3, s18, s4
	s_add_u32 s2, s2, s0
	s_addc_u32 s3, s3, s1
	global_store_dwordx4 v26, v[6:9], s[2:3]
	s_add_u32 s2, s19, s5
	s_addc_u32 s3, s20, s4
	s_add_u32 s0, s2, s0
	s_addc_u32 s1, s3, s1
	global_store_dwordx4 v26, v[2:5], s[0:1]
	s_waitcnt lgkmcnt(0)
	s_add_i32 s8, s8, s10
	s_cmpk_gt_i32 s8, 0x2ff
	s_cbranch_scc0 .LBB0_2477

.LBB0_2580:
	s_mul_hi_i32 s0, s16, 0x2aaaaaab
	s_lshr_b32 s1, s0, 31
	s_ashr_i32 s0, s0, 4
	s_add_i32 s0, s0, s1
	s_mul_i32 s1, s0, 0xffffffa0
	s_lshl_b32 s4, s0, 6
	s_mulk_i32 s0, 0xe800
	s_add_i32 s5, s16, s1
	s_add_i32 s0, s18, s0
	v_readlane_b32 s68, v250, 22
	s_cmpk_gt_i32 s5, 0x5f
	v_readlane_b32 s80, v250, 34
	v_readlane_b32 s81, v250, 35
	s_cselect_b64 s[6:7], -1, 0
	s_mov_b64 s[8:9], s[80:81]
	s_and_b64 vcc, exec, s[6:7]
	v_readlane_b32 s69, v250, 23
	v_readlane_b32 s70, v250, 24
	v_readlane_b32 s71, v250, 25
	v_readlane_b32 s72, v250, 26
	v_readlane_b32 s73, v250, 27
	v_readlane_b32 s74, v250, 28
	v_readlane_b32 s75, v250, 29
	v_readlane_b32 s76, v250, 30
	v_readlane_b32 s77, v250, 31
	v_readlane_b32 s78, v250, 32
	v_readlane_b32 s79, v250, 33
	v_readlane_b32 s82, v250, 36
	v_readlane_b32 s83, v250, 37
	s_cbranch_vccnz .LBB0_2582
	v_or_b32_e32 v4, s4, v14
	v_mov_b64_e32 v[2:3], s[8:9]
	v_mad_i64_i32 v[2:3], s[8:9], v4, s20, v[2:3]
	s_ashr_i32 s1, s0, 31
	v_lshl_add_u64 v[2:3], s[0:1], 2, v[2:3]
	v_mov_b32_e32 v9, v7
	v_lshl_add_u64 v[118:119], v[2:3], 0, v[8:9]
	v_add_co_u32_e32 v10, vcc, 0x18000, v118
	s_nop 1
	v_addc_co_u32_e32 v11, vcc, 0, v119, vcc
	v_add_co_u32_e32 v66, vcc, 0x30000, v118
	global_load_dwordx4 v[2:5], v[118:119], off nt
	s_nop 0
	global_load_dwordx4 v[10:13], v[10:11], off nt
	v_addc_co_u32_e32 v67, vcc, 0, v119, vcc
	v_add_co_u32_e32 v70, vcc, 0x48000, v118
	s_nop 1
	v_addc_co_u32_e32 v71, vcc, 0, v119, vcc
	v_add_co_u32_e32 v74, vcc, 0x60000, v118
	global_load_dwordx4 v[66:69], v[66:67], off nt
	s_nop 0
	global_load_dwordx4 v[70:73], v[70:71], off nt
	v_addc_co_u32_e32 v75, vcc, 0, v119, vcc
	v_add_co_u32_e32 v78, vcc, 0x78000, v118
	s_nop 1
	v_addc_co_u32_e32 v79, vcc, 0, v119, vcc
	v_add_co_u32_e32 v82, vcc, 0x90000, v118
	global_load_dwordx4 v[74:77], v[74:75], off nt
	s_nop 0
	global_load_dwordx4 v[78:81], v[78:79], off nt
	v_addc_co_u32_e32 v83, vcc, 0, v119, vcc
	v_add_co_u32_e32 v86, vcc, 0xa8000, v118
	s_nop 1
	v_addc_co_u32_e32 v87, vcc, 0, v119, vcc
	v_add_co_u32_e32 v90, vcc, 0xc0000, v118
	global_load_dwordx4 v[82:85], v[82:83], off nt
	s_nop 0
	global_load_dwordx4 v[86:89], v[86:87], off nt
	v_addc_co_u32_e32 v91, vcc, 0, v119, vcc
	v_add_co_u32_e32 v94, vcc, 0xd8000, v118
	s_nop 1
	v_addc_co_u32_e32 v95, vcc, 0, v119, vcc
	v_add_co_u32_e32 v98, vcc, 0xf0000, v118
	global_load_dwordx4 v[90:93], v[90:91], off nt
	s_nop 0
	global_load_dwordx4 v[94:97], v[94:95], off nt
	v_addc_co_u32_e32 v99, vcc, 0, v119, vcc
	v_add_co_u32_e32 v102, vcc, 0x108000, v118
	s_nop 1
	v_addc_co_u32_e32 v103, vcc, 0, v119, vcc
	v_add_co_u32_e32 v106, vcc, 0x120000, v118
	global_load_dwordx4 v[98:101], v[98:99], off nt
	s_nop 0
	global_load_dwordx4 v[102:105], v[102:103], off nt
	v_addc_co_u32_e32 v107, vcc, 0, v119, vcc
	v_add_co_u32_e32 v110, vcc, 0x138000, v118
	s_nop 1
	v_addc_co_u32_e32 v111, vcc, 0, v119, vcc
	global_load_dwordx4 v[106:109], v[106:107], off nt
	s_nop 0
	global_load_dwordx4 v[110:113], v[110:111], off nt
	v_add_co_u32_e32 v114, vcc, 0x150000, v118
	s_nop 1
	v_addc_co_u32_e32 v115, vcc, 0, v119, vcc
	global_load_dwordx4 v[114:117], v[114:115], off nt
	v_add_co_u32_e32 v118, vcc, 0x168000, v118
	s_nop 1
	v_addc_co_u32_e32 v119, vcc, 0, v119, vcc
	global_load_dwordx4 v[118:121], v[118:119], off nt
	s_waitcnt vmcnt(0)
	ds_write2_b32 v31, v2, v3 offset1:1
	ds_write2_b32 v31, v4, v5 offset0:2 offset1:3
	ds_write2_b32 v32, v10, v11 offset1:1
	ds_write2_b32 v33, v12, v13 offset1:1
	ds_write2_b32 v34, v66, v67 offset1:1
	ds_write2_b32 v35, v68, v69 offset1:1
	ds_write2_b32 v36, v70, v71 offset1:1
	ds_write2_b32 v37, v72, v73 offset1:1
	ds_write2_b32 v38, v74, v75 offset1:1
	ds_write2_b32 v39, v76, v77 offset1:1
	ds_write2_b32 v40, v78, v79 offset1:1
	ds_write2_b32 v41, v80, v81 offset1:1
	ds_write2_b32 v42, v82, v83 offset1:1
	ds_write2_b32 v43, v84, v85 offset1:1
	ds_write2_b32 v44, v86, v87 offset1:1
	ds_write2_b32 v45, v88, v89 offset1:1
	ds_write2_b32 v46, v90, v91 offset1:1
	ds_write2_b32 v47, v92, v93 offset1:1
	ds_write2_b32 v48, v94, v95 offset1:1
	ds_write2_b32 v49, v96, v97 offset1:1
	ds_write2_b32 v50, v98, v99 offset1:1
	ds_write2_b32 v51, v100, v101 offset1:1
	ds_write2_b32 v52, v102, v103 offset1:1
	ds_write2_b32 v53, v104, v105 offset1:1
	ds_write2_b32 v54, v106, v107 offset1:1
	ds_write2_b32 v55, v108, v109 offset1:1
	ds_write2_b32 v56, v110, v111 offset1:1
	ds_write2_b32 v57, v112, v113 offset1:1
	ds_write2_b32 v58, v114, v115 offset1:1
	ds_write2_b32 v59, v116, v117 offset1:1
	ds_write2_b32 v60, v118, v119 offset1:1
	ds_write2_b32 v61, v120, v121 offset1:1

.LBB0_2600:
	v_mul_hi_i32 v2, v1, s7
	v_add_u32_e32 v2, v2, v1
	v_lshrrev_b32_e32 v6, 31, v2
	v_ashrrev_i32_e32 v2, 13, v2
	v_add_u32_e32 v2, v2, v6
	v_mad_i32_i24 v18, v2, s8, v1
	v_add_u32_e32 v11, 3, v2
	v_mul_hi_i32 v2, v18, s9
	s_waitcnt lgkmcnt(0)
	v_mul_hi_i32_i24_e32 v7, 0xc000, v11
	v_mul_i32_i24_e32 v6, 0xc000, v11
	v_lshrrev_b32_e32 v14, 31, v2
	v_ashrrev_i32_e32 v2, 9, v2
	v_lshl_add_u64 v[16:17], s[46:47], 0, v[6:7]
	v_add_u32_e32 v6, v2, v14
	v_lshlrev_b32_e32 v12, 4, v11
	v_mul_i32_i24_e32 v19, 0xfffff400, v6
	v_and_b32_e32 v76, 16, v12
	v_add_lshl_u32 v18, v18, v19, 2
	v_mul_u32_u24_e32 v2, 5, v76
	v_ashrrev_i32_e32 v19, 31, v18
	v_mov_b32_e32 v13, v3
	v_ashrrev_i32_e32 v7, 31, v6
	v_or_b32_e32 v12, 5, v2
	v_lshlrev_b64 v[80:81], 2, v[18:19]
	v_mov_b32_e32 v15, v3
	v_or_b32_e32 v14, 10, v2
	v_lshl_add_u64 v[20:21], v[2:3], 0, v[6:7]
	v_lshl_add_u64 v[22:23], v[12:13], 0, v[6:7]
	v_or_b32_e32 v2, 15, v2
	v_lshl_add_u64 v[12:13], v[16:17], 0, v[80:81]
	v_lshl_add_u64 v[24:25], v[14:15], 0, v[6:7]
	v_lshl_add_u64 v[26:27], v[2:3], 0, v[6:7]
	v_mad_u32_u24 v2, v76, 5, 20
	global_load_dwordx4 v[12:15], v[12:13], off nt
	v_lshl_add_u64 v[18:19], v[2:3], 0, v[6:7]
	v_mad_u32_u24 v2, v76, 5, 25
	v_lshl_add_u64 v[72:73], s[2:3], 0, v[80:81]
	v_lshl_add_u64 v[16:17], v[2:3], 0, v[6:7]
	v_mad_u32_u24 v2, v76, 5, 30
	v_mad_u64_u32 v[28:29], s[12:13], v20, s10, v[72:73]
	v_mad_u64_u32 v[30:31], s[12:13], v22, s10, v[72:73]
	v_mad_u64_u32 v[32:33], s[12:13], v24, s10, v[72:73]
	v_mad_u64_u32 v[34:35], s[12:13], v26, s10, v[72:73]
	v_mad_u64_u32 v[36:37], s[12:13], v18, s10, v[72:73]
	v_mad_u64_u32 v[38:39], s[12:13], v16, s10, v[72:73]
	v_lshl_add_u64 v[40:41], v[2:3], 0, v[6:7]
	v_mad_u32_u24 v2, v76, 5, 35
	v_mad_i32_i24 v29, v21, s10, v29
	v_mad_i32_i24 v31, v23, s10, v31
	v_mad_i32_i24 v33, v25, s10, v33
	v_mad_i32_i24 v35, v27, s10, v35
	v_mad_i32_i24 v37, v19, s10, v37
	v_mad_i32_i24 v39, v17, s10, v39
	v_lshl_add_u64 v[44:45], v[2:3], 0, v[6:7]
	v_mad_u32_u24 v2, v76, 5, 40
	v_mad_u64_u32 v[42:43], s[12:13], v40, s10, v[72:73]
	global_load_dwordx4 v[16:19], v[28:29], off nt
	global_load_dwordx4 v[20:23], v[30:31], off nt
	global_load_dwordx4 v[24:27], v[32:33], off nt
	s_nop 0
	global_load_dwordx4 v[28:31], v[34:35], off nt
	s_nop 0
	global_load_dwordx4 v[32:35], v[36:37], off nt
	s_nop 0
	global_load_dwordx4 v[36:39], v[38:39], off nt
	v_mad_u64_u32 v[46:47], s[12:13], v44, s10, v[72:73]
	v_lshl_add_u64 v[48:49], v[2:3], 0, v[6:7]
	v_mad_u32_u24 v2, v76, 5, 45
	v_mad_i32_i24 v43, v41, s10, v43
	v_mad_i32_i24 v47, v45, s10, v47
	v_lshl_add_u64 v[52:53], v[2:3], 0, v[6:7]
	v_mad_u32_u24 v2, v76, 5, 50
	v_mad_u64_u32 v[50:51], s[12:13], v48, s10, v[72:73]
	global_load_dwordx4 v[40:43], v[42:43], off nt
	s_nop 0
	global_load_dwordx4 v[44:47], v[46:47], off nt
	v_mad_u64_u32 v[54:55], s[12:13], v52, s10, v[72:73]
	v_lshl_add_u64 v[56:57], v[2:3], 0, v[6:7]
	v_mad_u32_u24 v2, v76, 5, 55
	v_mad_i32_i24 v51, v49, s10, v51
	v_mad_i32_i24 v55, v53, s10, v55
	v_lshl_add_u64 v[60:61], v[2:3], 0, v[6:7]
	v_mad_u32_u24 v2, v76, 5, 60
	v_mad_u64_u32 v[58:59], s[12:13], v56, s10, v[72:73]
	global_load_dwordx4 v[48:51], v[50:51], off nt
	s_nop 0
	global_load_dwordx4 v[52:55], v[54:55], off nt
	v_mad_u64_u32 v[62:63], s[12:13], v60, s10, v[72:73]
	v_lshl_add_u64 v[64:65], v[2:3], 0, v[6:7]
	v_mad_u32_u24 v2, v76, 5, v8
	v_mad_i32_i24 v59, v57, s10, v59
	v_mad_i32_i24 v63, v61, s10, v63
	v_lshl_add_u64 v[68:69], v[2:3], 0, v[6:7]
	v_mad_u32_u24 v2, v76, 5, v9
	v_mad_u64_u32 v[66:67], s[12:13], v64, s10, v[72:73]
	global_load_dwordx4 v[56:59], v[58:59], off nt
	s_nop 0
	global_load_dwordx4 v[60:63], v[62:63], off nt
	v_mad_u64_u32 v[70:71], s[12:13], v68, s10, v[72:73]
	v_lshl_add_u64 v[74:75], v[2:3], 0, v[6:7]
	v_mad_u32_u24 v2, v76, 5, v10
	v_mad_i32_i24 v67, v65, s10, v67
	v_mad_i32_i24 v71, v69, s10, v71
	v_mad_u64_u32 v[76:77], s[12:13], v74, s10, v[72:73]
	v_lshl_add_u64 v[78:79], v[2:3], 0, v[6:7]
	global_load_dwordx4 v[64:67], v[66:67], off nt
	s_nop 0
	global_load_dwordx4 v[68:71], v[70:71], off nt
	v_mad_i32_i24 v77, v75, s10, v77
	v_mad_u64_u32 v[82:83], s[12:13], v78, s10, v[72:73]
	global_load_dwordx4 v[72:75], v[76:77], off nt
	v_mad_i32_i24 v83, v79, s10, v83
	global_load_dwordx4 v[76:79], v[82:83], off nt
	v_mul_hi_i32_i24_e32 v83, 5, v11
	v_mul_i32_i24_e32 v82, 5, v11
	v_lshl_add_u64 v[6:7], v[82:83], 0, v[6:7]
	v_mad_u64_u32 v[82:83], s[12:13], v6, s10, v[4:5]
	v_mov_b32_e32 v2, v83
	v_add_u32_e32 v1, s6, v1
	v_mad_u64_u32 v[6:7], s[12:13], v7, s10, v[2:3]
	v_cmp_lt_i32_e32 vcc, s11, v1
	v_mov_b32_e32 v83, v6
	s_or_b64 s[4:5], vcc, s[4:5]
	v_lshl_add_u64 v[6:7], v[82:83], 0, v[80:81]
	s_waitcnt vmcnt(0)
	v_pk_add_f32 v[14:15], v[14:15], v[18:19]
	v_pk_add_f32 v[12:13], v[12:13], v[16:17]
	v_pk_add_f32 v[14:15], v[14:15], v[22:23]
	v_pk_add_f32 v[12:13], v[12:13], v[20:21]
	v_pk_add_f32 v[14:15], v[14:15], v[26:27]
	v_pk_add_f32 v[12:13], v[12:13], v[24:25]
	v_pk_add_f32 v[14:15], v[14:15], v[30:31]
	v_pk_add_f32 v[12:13], v[12:13], v[28:29]
	v_pk_add_f32 v[14:15], v[14:15], v[34:35]
	v_pk_add_f32 v[12:13], v[12:13], v[32:33]
	v_pk_add_f32 v[14:15], v[14:15], v[38:39]
	v_pk_add_f32 v[12:13], v[12:13], v[36:37]
	v_pk_add_f32 v[14:15], v[14:15], v[42:43]
	v_pk_add_f32 v[12:13], v[12:13], v[40:41]
	v_pk_add_f32 v[14:15], v[14:15], v[46:47]
	v_pk_add_f32 v[12:13], v[12:13], v[44:45]
	v_pk_add_f32 v[14:15], v[14:15], v[50:51]
	v_pk_add_f32 v[12:13], v[12:13], v[48:49]
	v_pk_add_f32 v[14:15], v[14:15], v[54:55]
	v_pk_add_f32 v[12:13], v[12:13], v[52:53]
	v_pk_add_f32 v[14:15], v[14:15], v[58:59]
	v_pk_add_f32 v[12:13], v[12:13], v[56:57]
	v_pk_add_f32 v[14:15], v[14:15], v[62:63]
	v_pk_add_f32 v[12:13], v[12:13], v[60:61]
	v_pk_add_f32 v[14:15], v[14:15], v[66:67]
	v_pk_add_f32 v[12:13], v[12:13], v[64:65]
	v_pk_add_f32 v[14:15], v[14:15], v[70:71]
	v_pk_add_f32 v[12:13], v[12:13], v[68:69]
	v_pk_add_f32 v[14:15], v[14:15], v[74:75]
	v_pk_add_f32 v[12:13], v[12:13], v[72:73]
	v_pk_add_f32 v[14:15], v[14:15], v[78:79]
	v_pk_add_f32 v[12:13], v[12:13], v[76:77]
	global_store_dwordx4 v[6:7], v[12:15], off
	s_andn2_b64 exec, exec, s[4:5]
	s_cbranch_execnz .LBB0_2600

.LBB0_2781:
	s_lshl_b32 s10, s12, 6
	s_cmp_ge_i32 s14, s2
	s_cselect_b64 s[12:13], -1, 0
	s_and_b64 vcc, exec, s[12:13]
	s_cbranch_vccnz .LBB0_2783
	v_or_b32_e32 v2, s10, v12
	v_mad_i64_i32 v[2:3], s[22:23], v2, s2, 0
	v_lshl_add_u64 v[2:3], v[2:3], 2, s[0:1]
	s_ashr_i32 s15, s14, 31
	v_lshl_add_u64 v[2:3], s[14:15], 2, v[2:3]
	v_mov_b32_e32 v9, v7
	v_lshl_add_u64 v[10:11], v[2:3], 0, v[8:9]
	global_load_dwordx4 v[2:5], v[10:11], off nt
	s_lshl_b32 s2, s2, 4
	v_lshl_add_u64 v[10:11], v[10:11], 0, s[2:3]
	global_load_dwordx4 v[64:67], v[10:11], off nt
	v_lshl_add_u64 v[10:11], v[10:11], 0, s[2:3]
	global_load_dwordx4 v[68:71], v[10:11], off nt
	v_lshl_add_u64 v[10:11], v[10:11], 0, s[2:3]
	global_load_dwordx4 v[72:75], v[10:11], off nt
	v_lshl_add_u64 v[10:11], v[10:11], 0, s[2:3]
	global_load_dwordx4 v[76:79], v[10:11], off nt
	v_lshl_add_u64 v[10:11], v[10:11], 0, s[2:3]
	global_load_dwordx4 v[80:83], v[10:11], off nt
	v_lshl_add_u64 v[10:11], v[10:11], 0, s[2:3]
	global_load_dwordx4 v[84:87], v[10:11], off nt
	v_lshl_add_u64 v[10:11], v[10:11], 0, s[2:3]
	global_load_dwordx4 v[88:91], v[10:11], off nt
	v_lshl_add_u64 v[10:11], v[10:11], 0, s[2:3]
	global_load_dwordx4 v[92:95], v[10:11], off nt
	v_lshl_add_u64 v[10:11], v[10:11], 0, s[2:3]
	global_load_dwordx4 v[96:99], v[10:11], off nt
	v_lshl_add_u64 v[10:11], v[10:11], 0, s[2:3]
	global_load_dwordx4 v[100:103], v[10:11], off nt
	v_lshl_add_u64 v[10:11], v[10:11], 0, s[2:3]
	global_load_dwordx4 v[104:107], v[10:11], off nt
	v_lshl_add_u64 v[10:11], v[10:11], 0, s[2:3]
	global_load_dwordx4 v[108:111], v[10:11], off nt
	v_lshl_add_u64 v[10:11], v[10:11], 0, s[2:3]
	global_load_dwordx4 v[112:115], v[10:11], off nt
	v_lshl_add_u64 v[10:11], v[10:11], 0, s[2:3]
	global_load_dwordx4 v[116:119], v[10:11], off nt
	v_lshl_add_u64 v[10:11], v[10:11], 0, s[2:3]
	global_load_dwordx4 v[120:123], v[10:11], off nt
	s_waitcnt vmcnt(0)
	ds_write2_b32 v29, v2, v3 offset1:1
	ds_write2_b32 v29, v4, v5 offset0:2 offset1:3
	ds_write2_b32 v30, v64, v65 offset1:1
	ds_write2_b32 v31, v66, v67 offset1:1
	ds_write2_b32 v32, v68, v69 offset1:1
	ds_write2_b32 v33, v70, v71 offset1:1
	ds_write2_b32 v34, v72, v73 offset1:1
	ds_write2_b32 v35, v74, v75 offset1:1
	ds_write2_b32 v36, v76, v77 offset1:1
	ds_write2_b32 v37, v78, v79 offset1:1
	ds_write2_b32 v38, v80, v81 offset1:1
	ds_write2_b32 v39, v82, v83 offset1:1
	ds_write2_b32 v40, v84, v85 offset1:1
	ds_write2_b32 v41, v86, v87 offset1:1
	ds_write2_b32 v42, v88, v89 offset1:1
	ds_write2_b32 v43, v90, v91 offset1:1
	ds_write2_b32 v44, v92, v93 offset1:1
	ds_write2_b32 v45, v94, v95 offset1:1
	ds_write2_b32 v46, v96, v97 offset1:1
	ds_write2_b32 v47, v98, v99 offset1:1
	ds_write2_b32 v48, v100, v101 offset1:1
	ds_write2_b32 v49, v102, v103 offset1:1
	ds_write2_b32 v50, v104, v105 offset1:1
	ds_write2_b32 v51, v106, v107 offset1:1
	ds_write2_b32 v52, v108, v109 offset1:1
	ds_write2_b32 v53, v110, v111 offset1:1
	ds_write2_b32 v54, v112, v113 offset1:1
	ds_write2_b32 v55, v114, v115 offset1:1
	ds_write2_b32 v56, v116, v117 offset1:1
	ds_write2_b32 v57, v118, v119 offset1:1
	ds_write2_b32 v58, v120, v121 offset1:1
	ds_write2_b32 v59, v122, v123 offset1:1
